# MLA attention: waves 4-7 sleep 512 cycles after each per-tile barrier so SIMD partners run QK MFMAs and softmax VALU out of phase
# speedup vs baseline: 1.0071x; 1.0071x over previous
_Z10fwd_kernel4Args:
	s_load_dword s3, s[0:1], 0x118
	s_mov_b32 s96, s2
	v_readfirstlane_b32 s2, v0
	s_nop 3
	s_lshr_b32 s98, s2, 8
	s_add_u32 s4, s0, 0x118
	s_addc_u32 s5, s1, 0
	v_writelane_b32 v250, s2, 0
	s_waitcnt lgkmcnt(0)
	s_and_b32 s2, s3, 7
	v_writelane_b32 v250, s4, 1
	s_cmp_lg_u32 s2, 0
	s_mov_b32 s33, s96
	v_writelane_b32 v250, s5, 2
	s_cbranch_scc1 .LBB0_2
	s_ashr_i32 s4, s96, 31
	s_lshr_b32 s4, s4, 29
	s_add_i32 s4, s96, s4
	s_and_b32 s5, s4, -8
	s_ashr_i32 s2, s3, 3
	s_sub_i32 s5, s96, s5
	s_mul_i32 s2, s2, s5
	s_ashr_i32 s4, s4, 3
	s_add_i32 s33, s2, s4

.LBB0_200:
	ds_read_b128 v[166:169], v156
	ds_read_b128 v[170:173], v156 offset:1024
	ds_read_b128 v[174:177], v156 offset:2048
	ds_read_b128 v[178:181], v156 offset:3072
	ds_read_b128 v[182:185], v157
	ds_read_b128 v[186:189], v157 offset:1024
	ds_read_b128 v[190:193], v157 offset:2048
	ds_read_b128 v[194:197], v157 offset:3072
	s_add_u32 s54, s60, 0xfff00080
	s_addc_u32 s55, s61, -1
	s_cmp_eq_u32 s70, 60
	s_cselect_b32 s63, s2, s55
	s_cselect_b32 s62, s7, s54
	s_cselect_b32 s55, s25, s69
	s_cselect_b32 s54, s31, s59
	v_lshl_add_u64 v[160:161], s[60:61], 0, v[138:139]
	s_add_i32 m0, s26, 0xc000
	ds_read_b128 v[202:205], v158
	ds_read_b128 v[206:209], v158 offset:1024
	ds_read_b128 v[210:213], v158 offset:2048
	ds_read_b128 v[214:217], v158 offset:3072
	ds_read_b128 v[218:221], v158 offset:4096
	ds_read_b128 v[222:225], v158 offset:5120
	ds_read_b128 v[226:229], v158 offset:6144
	ds_read_b128 v[230:233], v158 offset:7168
	global_load_lds_dwordx4 v[160:161], off
	v_lshl_add_u64 v[160:161], s[60:61], 0, v[140:141]
	s_add_i32 m0, s26, 0xe000
	s_nop 0
	global_load_lds_dwordx4 v[160:161], off
	s_waitcnt vmcnt(8)
	s_waitcnt lgkmcnt(0)
	s_barrier
	s_setprio 1
	s_waitcnt lgkmcnt(0)
	v_mfma_f32_16x16x32_bf16 v[126:129], v[166:169], v[202:205], v[126:129]
	v_mfma_f32_16x16x32_bf16 v[122:125], v[174:177], v[202:205], v[122:125]
	v_mfma_f32_16x16x32_bf16 v[110:113], v[166:169], v[210:213], v[110:113]
	v_mfma_f32_16x16x32_bf16 v[106:109], v[174:177], v[210:213], v[106:109]
	v_mfma_f32_16x16x32_bf16 v[94:97], v[166:169], v[218:221], v[94:97]
	v_mfma_f32_16x16x32_bf16 v[90:93], v[174:177], v[218:221], v[90:93]
	v_mfma_f32_16x16x32_bf16 v[78:81], v[166:169], v[226:229], v[78:81]
	v_mfma_f32_16x16x32_bf16 v[74:77], v[174:177], v[226:229], v[74:77]
	v_mfma_f32_16x16x32_bf16 v[126:129], v[170:173], v[206:209], v[126:129]
	v_mfma_f32_16x16x32_bf16 v[122:125], v[178:181], v[206:209], v[122:125]
	v_mfma_f32_16x16x32_bf16 v[110:113], v[170:173], v[214:217], v[110:113]
	v_mfma_f32_16x16x32_bf16 v[106:109], v[178:181], v[214:217], v[106:109]
	v_mfma_f32_16x16x32_bf16 v[94:97], v[170:173], v[222:225], v[94:97]
	v_mfma_f32_16x16x32_bf16 v[90:93], v[178:181], v[222:225], v[90:93]
	v_mfma_f32_16x16x32_bf16 v[78:81], v[170:173], v[230:233], v[78:81]
	v_mfma_f32_16x16x32_bf16 v[74:77], v[178:181], v[230:233], v[74:77]
	s_setprio 0
	s_setprio 1
	v_mfma_f32_16x16x32_bf16 v[118:121], v[182:185], v[202:205], v[118:121]
	v_mfma_f32_16x16x32_bf16 v[114:117], v[190:193], v[202:205], v[114:117]
	v_mfma_f32_16x16x32_bf16 v[102:105], v[182:185], v[210:213], v[102:105]
	v_mfma_f32_16x16x32_bf16 v[98:101], v[190:193], v[210:213], v[98:101]
	v_mfma_f32_16x16x32_bf16 v[86:89], v[182:185], v[218:221], v[86:89]
	v_mfma_f32_16x16x32_bf16 v[82:85], v[190:193], v[218:221], v[82:85]
	v_mfma_f32_16x16x32_bf16 v[70:73], v[182:185], v[226:229], v[70:73]
	v_mfma_f32_16x16x32_bf16 v[66:69], v[190:193], v[226:229], v[66:69]
	v_mfma_f32_16x16x32_bf16 v[118:121], v[186:189], v[206:209], v[118:121]
	v_mfma_f32_16x16x32_bf16 v[114:117], v[194:197], v[206:209], v[114:117]
	v_mfma_f32_16x16x32_bf16 v[102:105], v[186:189], v[214:217], v[102:105]
	v_mfma_f32_16x16x32_bf16 v[98:101], v[194:197], v[214:217], v[98:101]
	v_mfma_f32_16x16x32_bf16 v[86:89], v[186:189], v[222:225], v[86:89]
	v_mfma_f32_16x16x32_bf16 v[82:85], v[194:197], v[222:225], v[82:85]
	v_mfma_f32_16x16x32_bf16 v[70:73], v[186:189], v[230:233], v[70:73]
	v_mfma_f32_16x16x32_bf16 v[66:69], v[194:197], v[230:233], v[66:69]
	s_setprio 0
	s_barrier
	s_add_i32 s71, s57, s21
	v_lshl_add_u64 v[160:161], s[54:55], 0, v[134:135]
	s_mov_b32 m0, s71
	ds_read_b128 v[202:205], v158 offset:16384
	ds_read_b128 v[206:209], v158 offset:17408
	ds_read_b128 v[210:213], v158 offset:18432
	ds_read_b128 v[214:217], v158 offset:19456
	ds_read_b128 v[218:221], v158 offset:20480
	ds_read_b128 v[222:225], v158 offset:21504
	ds_read_b128 v[226:229], v158 offset:22528
	ds_read_b128 v[230:233], v158 offset:23552
	global_load_lds_dwordx4 v[160:161], off
	s_add_i32 m0, s71, 0x2000
	s_add_u32 s72, s54, 0x100000
	v_lshl_add_u64 v[198:199], s[54:55], 0, v[136:137]
	s_addc_u32 s73, s55, 0
	s_add_i32 s71, s64, s21
	global_load_lds_dwordx4 v[198:199], off
	v_lshl_add_u64 v[234:235], s[72:73], 0, v[134:135]
	s_mov_b32 m0, s71
	v_lshl_add_u64 v[236:237], s[62:63], 0, v[132:133]
	global_load_lds_dwordx4 v[234:235], off
	v_lshl_add_u64 v[234:235], s[72:73], 0, v[136:137]
	s_add_i32 m0, s71, 0x2000
	s_nop 0
	global_load_lds_dwordx4 v[234:235], off
	v_lshl_add_u64 v[234:235], s[62:63], 0, v[130:131]
	s_mov_b32 m0, s26
	s_nop 0
	global_load_lds_dwordx4 v[234:235], off
	s_mov_b32 m0, s27
	s_nop 0
	global_load_lds_dwordx4 v[236:237], off
	s_waitcnt vmcnt(8)
	s_waitcnt lgkmcnt(0)
	s_barrier
	s_setprio 1
	s_waitcnt lgkmcnt(0)
	v_mfma_f32_16x16x32_bf16 v[62:65], v[166:169], v[202:205], v[62:65]
	v_mfma_f32_16x16x32_bf16 v[58:61], v[174:177], v[202:205], v[58:61]
	v_mfma_f32_16x16x32_bf16 v[46:49], v[166:169], v[210:213], v[46:49]
	v_mfma_f32_16x16x32_bf16 v[42:45], v[174:177], v[210:213], v[42:45]
	v_mfma_f32_16x16x32_bf16 v[30:33], v[166:169], v[218:221], v[30:33]
	v_mfma_f32_16x16x32_bf16 v[26:29], v[174:177], v[218:221], v[26:29]
	v_mfma_f32_16x16x32_bf16 v[14:17], v[166:169], v[226:229], v[14:17]
	v_mfma_f32_16x16x32_bf16 v[10:13], v[174:177], v[226:229], v[10:13]
	v_mfma_f32_16x16x32_bf16 v[62:65], v[170:173], v[206:209], v[62:65]
	v_mfma_f32_16x16x32_bf16 v[58:61], v[178:181], v[206:209], v[58:61]
	v_mfma_f32_16x16x32_bf16 v[46:49], v[170:173], v[214:217], v[46:49]
	v_mfma_f32_16x16x32_bf16 v[42:45], v[178:181], v[214:217], v[42:45]
	v_mfma_f32_16x16x32_bf16 v[30:33], v[170:173], v[222:225], v[30:33]
	v_mfma_f32_16x16x32_bf16 v[26:29], v[178:181], v[222:225], v[26:29]
	v_mfma_f32_16x16x32_bf16 v[14:17], v[170:173], v[230:233], v[14:17]
	v_mfma_f32_16x16x32_bf16 v[10:13], v[178:181], v[230:233], v[10:13]
	s_setprio 0
	s_setprio 1
	v_mfma_f32_16x16x32_bf16 v[54:57], v[182:185], v[202:205], v[54:57]
	v_mfma_f32_16x16x32_bf16 v[50:53], v[190:193], v[202:205], v[50:53]
	v_mfma_f32_16x16x32_bf16 v[38:41], v[182:185], v[210:213], v[38:41]
	v_mfma_f32_16x16x32_bf16 v[34:37], v[190:193], v[210:213], v[34:37]
	v_mfma_f32_16x16x32_bf16 v[22:25], v[182:185], v[218:221], v[22:25]
	v_mfma_f32_16x16x32_bf16 v[18:21], v[190:193], v[218:221], v[18:21]
	v_mfma_f32_16x16x32_bf16 v[6:9], v[182:185], v[226:229], v[6:9]
	v_mfma_f32_16x16x32_bf16 v[2:5], v[190:193], v[226:229], v[2:5]
	v_mfma_f32_16x16x32_bf16 v[54:57], v[186:189], v[206:209], v[54:57]
	v_mfma_f32_16x16x32_bf16 v[50:53], v[194:197], v[206:209], v[50:53]
	v_mfma_f32_16x16x32_bf16 v[38:41], v[186:189], v[214:217], v[38:41]
	v_mfma_f32_16x16x32_bf16 v[34:37], v[194:197], v[214:217], v[34:37]
	v_mfma_f32_16x16x32_bf16 v[22:25], v[186:189], v[222:225], v[22:25]
	v_mfma_f32_16x16x32_bf16 v[18:21], v[194:197], v[222:225], v[18:21]
	v_mfma_f32_16x16x32_bf16 v[6:9], v[186:189], v[230:233], v[6:9]
	v_mfma_f32_16x16x32_bf16 v[2:5], v[194:197], v[230:233], v[2:5]
	s_setprio 0
	s_barrier
	s_add_i32 s71, 0, 0x18000
	v_add_u32_e32 v163, s71, v154
	s_add_i32 s72, 0, 0x1c000
	ds_read_b128 v[166:169], v163
	ds_read_b128 v[170:173], v163 offset:1024
	ds_read_b128 v[174:177], v163 offset:2048
	ds_read_b128 v[178:181], v163 offset:3072
	v_add_u32_e32 v163, s72, v154
	ds_read_b128 v[182:185], v163
	ds_read_b128 v[186:189], v163 offset:1024
	ds_read_b128 v[190:193], v163 offset:2048
	ds_read_b128 v[194:197], v163 offset:3072
	s_add_u32 s62, s62, 0x100000
	s_addc_u32 s63, s63, 0
	s_mov_b32 m0, s36
	v_lshl_add_u64 v[238:239], s[62:63], 0, v[130:131]
	ds_read_b128 v[202:205], v158 offset:32768
	ds_read_b128 v[206:209], v158 offset:33792
	ds_read_b128 v[210:213], v158 offset:34816
	ds_read_b128 v[214:217], v158 offset:35840
	ds_read_b128 v[218:221], v158 offset:36864
	ds_read_b128 v[222:225], v158 offset:37888
	ds_read_b128 v[226:229], v158 offset:38912
	ds_read_b128 v[230:233], v158 offset:39936
	global_load_lds_dwordx4 v[238:239], off
	v_lshl_add_u64 v[238:239], s[62:63], 0, v[132:133]
	s_mov_b32 m0, s37
	s_nop 0
	global_load_lds_dwordx4 v[238:239], off
	s_waitcnt vmcnt(8)
	s_waitcnt lgkmcnt(0)
	s_barrier
	s_setprio 1
	s_waitcnt lgkmcnt(0)
	v_mfma_f32_16x16x32_bf16 v[126:129], v[166:169], v[202:205], v[126:129]
	v_mfma_f32_16x16x32_bf16 v[122:125], v[174:177], v[202:205], v[122:125]
	v_mfma_f32_16x16x32_bf16 v[110:113], v[166:169], v[210:213], v[110:113]
	v_mfma_f32_16x16x32_bf16 v[106:109], v[174:177], v[210:213], v[106:109]
	v_mfma_f32_16x16x32_bf16 v[94:97], v[166:169], v[218:221], v[94:97]
	v_mfma_f32_16x16x32_bf16 v[90:93], v[174:177], v[218:221], v[90:93]
	v_mfma_f32_16x16x32_bf16 v[78:81], v[166:169], v[226:229], v[78:81]
	v_mfma_f32_16x16x32_bf16 v[74:77], v[174:177], v[226:229], v[74:77]
	v_mfma_f32_16x16x32_bf16 v[126:129], v[170:173], v[206:209], v[126:129]
	v_mfma_f32_16x16x32_bf16 v[122:125], v[178:181], v[206:209], v[122:125]
	v_mfma_f32_16x16x32_bf16 v[110:113], v[170:173], v[214:217], v[110:113]
	v_mfma_f32_16x16x32_bf16 v[106:109], v[178:181], v[214:217], v[106:109]
	v_mfma_f32_16x16x32_bf16 v[94:97], v[170:173], v[222:225], v[94:97]
	v_mfma_f32_16x16x32_bf16 v[90:93], v[178:181], v[222:225], v[90:93]
	v_mfma_f32_16x16x32_bf16 v[78:81], v[170:173], v[230:233], v[78:81]
	v_mfma_f32_16x16x32_bf16 v[74:77], v[178:181], v[230:233], v[74:77]
	s_setprio 0
	s_setprio 1
	v_mfma_f32_16x16x32_bf16 v[118:121], v[182:185], v[202:205], v[118:121]
	v_mfma_f32_16x16x32_bf16 v[114:117], v[190:193], v[202:205], v[114:117]
	v_mfma_f32_16x16x32_bf16 v[102:105], v[182:185], v[210:213], v[102:105]
	v_mfma_f32_16x16x32_bf16 v[98:101], v[190:193], v[210:213], v[98:101]
	v_mfma_f32_16x16x32_bf16 v[86:89], v[182:185], v[218:221], v[86:89]
	v_mfma_f32_16x16x32_bf16 v[82:85], v[190:193], v[218:221], v[82:85]
	v_mfma_f32_16x16x32_bf16 v[70:73], v[182:185], v[226:229], v[70:73]
	v_mfma_f32_16x16x32_bf16 v[66:69], v[190:193], v[226:229], v[66:69]
	v_mfma_f32_16x16x32_bf16 v[118:121], v[186:189], v[206:209], v[118:121]
	v_mfma_f32_16x16x32_bf16 v[114:117], v[194:197], v[206:209], v[114:117]
	v_mfma_f32_16x16x32_bf16 v[102:105], v[186:189], v[214:217], v[102:105]
	v_mfma_f32_16x16x32_bf16 v[98:101], v[194:197], v[214:217], v[98:101]
	v_mfma_f32_16x16x32_bf16 v[86:89], v[186:189], v[222:225], v[86:89]
	v_mfma_f32_16x16x32_bf16 v[82:85], v[194:197], v[222:225], v[82:85]
	v_mfma_f32_16x16x32_bf16 v[70:73], v[186:189], v[230:233], v[70:73]
	v_mfma_f32_16x16x32_bf16 v[66:69], v[194:197], v[230:233], v[66:69]
	s_setprio 0
	s_barrier
	s_add_i32 s62, s71, s21
	v_lshl_add_u64 v[160:161], v[160:161], 0, s[14:15]
	s_mov_b32 m0, s62
	ds_read_b128 v[202:205], v158 offset:49152
	ds_read_b128 v[206:209], v158 offset:50176
	ds_read_b128 v[210:213], v158 offset:51200
	ds_read_b128 v[214:217], v158 offset:52224
	ds_read_b128 v[218:221], v158 offset:53248
	ds_read_b128 v[222:225], v158 offset:54272
	ds_read_b128 v[226:229], v158 offset:55296
	ds_read_b128 v[230:233], v158 offset:56320
	global_load_lds_dwordx4 v[160:161], off
	s_add_i32 m0, s62, 0x2000
	s_add_u32 s54, s54, 0x100080
	v_lshl_add_u64 v[160:161], v[198:199], 0, s[14:15]
	s_addc_u32 s55, s55, 0
	s_add_i32 s62, s72, s21
	global_load_lds_dwordx4 v[160:161], off
	v_lshl_add_u64 v[160:161], s[54:55], 0, v[134:135]
	s_mov_b32 m0, s62
	s_nop 0
	global_load_lds_dwordx4 v[160:161], off
	v_lshl_add_u64 v[160:161], s[54:55], 0, v[136:137]
	s_add_i32 m0, s62, 0x2000
	s_nop 0
	global_load_lds_dwordx4 v[160:161], off
	v_lshl_add_u64 v[160:161], v[234:235], 0, s[14:15]
	s_mov_b32 m0, s52
	s_nop 0
	global_load_lds_dwordx4 v[160:161], off
	v_lshl_add_u64 v[160:161], v[236:237], 0, s[14:15]
	s_mov_b32 m0, s53
	s_nop 0
	global_load_lds_dwordx4 v[160:161], off
	s_waitcnt vmcnt(8)
	s_waitcnt lgkmcnt(0)
	s_barrier
	s_setprio 1
	s_waitcnt lgkmcnt(0)
	v_mfma_f32_16x16x32_bf16 v[62:65], v[166:169], v[202:205], v[62:65]
	v_mfma_f32_16x16x32_bf16 v[58:61], v[174:177], v[202:205], v[58:61]
	v_mfma_f32_16x16x32_bf16 v[46:49], v[166:169], v[210:213], v[46:49]
	v_mfma_f32_16x16x32_bf16 v[42:45], v[174:177], v[210:213], v[42:45]
	v_mfma_f32_16x16x32_bf16 v[30:33], v[166:169], v[218:221], v[30:33]
	v_mfma_f32_16x16x32_bf16 v[26:29], v[174:177], v[218:221], v[26:29]
	v_mfma_f32_16x16x32_bf16 v[14:17], v[166:169], v[226:229], v[14:17]
	v_mfma_f32_16x16x32_bf16 v[10:13], v[174:177], v[226:229], v[10:13]
	v_mfma_f32_16x16x32_bf16 v[62:65], v[170:173], v[206:209], v[62:65]
	v_mfma_f32_16x16x32_bf16 v[58:61], v[178:181], v[206:209], v[58:61]
	v_mfma_f32_16x16x32_bf16 v[46:49], v[170:173], v[214:217], v[46:49]
	v_mfma_f32_16x16x32_bf16 v[42:45], v[178:181], v[214:217], v[42:45]
	v_mfma_f32_16x16x32_bf16 v[30:33], v[170:173], v[222:225], v[30:33]
	v_mfma_f32_16x16x32_bf16 v[26:29], v[178:181], v[222:225], v[26:29]
	v_mfma_f32_16x16x32_bf16 v[14:17], v[170:173], v[230:233], v[14:17]
	v_mfma_f32_16x16x32_bf16 v[10:13], v[178:181], v[230:233], v[10:13]
	s_setprio 0
	s_setprio 1
	v_mfma_f32_16x16x32_bf16 v[54:57], v[182:185], v[202:205], v[54:57]
	v_mfma_f32_16x16x32_bf16 v[50:53], v[190:193], v[202:205], v[50:53]
	v_mfma_f32_16x16x32_bf16 v[38:41], v[182:185], v[210:213], v[38:41]
	v_mfma_f32_16x16x32_bf16 v[34:37], v[190:193], v[210:213], v[34:37]
	v_mfma_f32_16x16x32_bf16 v[22:25], v[182:185], v[218:221], v[22:25]
	v_mfma_f32_16x16x32_bf16 v[18:21], v[190:193], v[218:221], v[18:21]
	v_mfma_f32_16x16x32_bf16 v[6:9], v[182:185], v[226:229], v[6:9]
	v_mfma_f32_16x16x32_bf16 v[2:5], v[190:193], v[226:229], v[2:5]
	v_mfma_f32_16x16x32_bf16 v[54:57], v[186:189], v[206:209], v[54:57]
	v_mfma_f32_16x16x32_bf16 v[50:53], v[194:197], v[206:209], v[50:53]
	v_mfma_f32_16x16x32_bf16 v[38:41], v[186:189], v[214:217], v[38:41]
	v_mfma_f32_16x16x32_bf16 v[34:37], v[194:197], v[214:217], v[34:37]
	v_mfma_f32_16x16x32_bf16 v[22:25], v[186:189], v[222:225], v[22:25]
	v_mfma_f32_16x16x32_bf16 v[18:21], v[194:197], v[222:225], v[18:21]
	v_mfma_f32_16x16x32_bf16 v[6:9], v[186:189], v[230:233], v[6:9]
	v_mfma_f32_16x16x32_bf16 v[2:5], v[194:197], v[230:233], v[2:5]
	s_setprio 0
	s_barrier
	s_add_i32 s70, s70, 2
	s_add_u32 s60, s60, 0x100
	s_addc_u32 s61, s61, 0
	s_add_u32 s59, s59, 0x100
	s_addc_u32 s69, s69, 0
	s_cmp_gt_u32 s70, 61
	s_cbranch_scc0 .LBB0_200
	s_and_b64 vcc, exec, s[22:23]
	s_cbranch_vccz .LBB0_203
	s_barrier

.LBB0_248:
	ds_read_b128 v[144:147], v140
	ds_read_b128 v[148:151], v140 offset:1024
	ds_read_b128 v[152:155], v140 offset:2048
	ds_read_b128 v[156:159], v140 offset:3072
	ds_read_b128 v[166:169], v141
	ds_read_b128 v[170:173], v141 offset:1024
	ds_read_b128 v[174:177], v141 offset:2048
	ds_read_b128 v[178:181], v141 offset:3072
	s_add_u32 s54, s64, 0xfff00080
	s_addc_u32 s55, s65, -1
	s_cmp_eq_u32 s71, 60
	s_cselect_b32 s67, s15, s55
	s_cselect_b32 s66, s47, s54
	s_cselect_b32 s55, s51, s70
	s_cselect_b32 s54, s68, s69
	v_lshl_add_u64 v[160:161], s[64:65], 0, v[134:135]
	s_add_i32 m0, s23, 0xc000
	ds_read_b128 v[182:185], v142
	ds_read_b128 v[186:189], v142 offset:1024
	ds_read_b128 v[190:193], v142 offset:2048
	ds_read_b128 v[194:197], v142 offset:3072
	ds_read_b128 v[202:205], v142 offset:4096
	ds_read_b128 v[206:209], v142 offset:5120
	ds_read_b128 v[210:213], v142 offset:6144
	ds_read_b128 v[214:217], v142 offset:7168
	global_load_lds_dwordx4 v[160:161], off
	v_lshl_add_u64 v[160:161], s[64:65], 0, v[136:137]
	s_add_i32 m0, s23, 0xe000
	s_nop 0
	global_load_lds_dwordx4 v[160:161], off
	s_waitcnt vmcnt(8)
	s_waitcnt lgkmcnt(0)
	s_barrier
	s_setprio 1
	s_waitcnt lgkmcnt(0)
	v_mfma_f32_16x16x32_bf16 v[126:129], v[144:147], v[182:185], v[126:129]
	v_mfma_f32_16x16x32_bf16 v[122:125], v[152:155], v[182:185], v[122:125]
	v_mfma_f32_16x16x32_bf16 v[118:121], v[144:147], v[190:193], v[118:121]
	v_mfma_f32_16x16x32_bf16 v[114:117], v[152:155], v[190:193], v[114:117]
	v_mfma_f32_16x16x32_bf16 v[110:113], v[144:147], v[202:205], v[110:113]
	v_mfma_f32_16x16x32_bf16 v[102:105], v[152:155], v[202:205], v[102:105]
	v_mfma_f32_16x16x32_bf16 v[94:97], v[144:147], v[210:213], v[94:97]
	v_mfma_f32_16x16x32_bf16 v[86:89], v[152:155], v[210:213], v[86:89]
	v_mfma_f32_16x16x32_bf16 v[126:129], v[148:151], v[186:189], v[126:129]
	v_mfma_f32_16x16x32_bf16 v[122:125], v[156:159], v[186:189], v[122:125]
	v_mfma_f32_16x16x32_bf16 v[118:121], v[148:151], v[194:197], v[118:121]
	v_mfma_f32_16x16x32_bf16 v[114:117], v[156:159], v[194:197], v[114:117]
	v_mfma_f32_16x16x32_bf16 v[110:113], v[148:151], v[206:209], v[110:113]
	v_mfma_f32_16x16x32_bf16 v[102:105], v[156:159], v[206:209], v[102:105]
	v_mfma_f32_16x16x32_bf16 v[94:97], v[148:151], v[214:217], v[94:97]
	v_mfma_f32_16x16x32_bf16 v[86:89], v[156:159], v[214:217], v[86:89]
	s_setprio 0
	s_setprio 1
	v_mfma_f32_16x16x32_bf16 v[106:109], v[166:169], v[182:185], v[106:109]
	v_mfma_f32_16x16x32_bf16 v[98:101], v[174:177], v[182:185], v[98:101]
	v_mfma_f32_16x16x32_bf16 v[90:93], v[166:169], v[190:193], v[90:93]
	v_mfma_f32_16x16x32_bf16 v[82:85], v[174:177], v[190:193], v[82:85]
	v_mfma_f32_16x16x32_bf16 v[78:81], v[166:169], v[202:205], v[78:81]
	v_mfma_f32_16x16x32_bf16 v[74:77], v[174:177], v[202:205], v[74:77]
	v_mfma_f32_16x16x32_bf16 v[70:73], v[166:169], v[210:213], v[70:73]
	v_mfma_f32_16x16x32_bf16 v[66:69], v[174:177], v[210:213], v[66:69]
	v_mfma_f32_16x16x32_bf16 v[106:109], v[170:173], v[186:189], v[106:109]
	v_mfma_f32_16x16x32_bf16 v[98:101], v[178:181], v[186:189], v[98:101]
	v_mfma_f32_16x16x32_bf16 v[90:93], v[170:173], v[194:197], v[90:93]
	v_mfma_f32_16x16x32_bf16 v[82:85], v[178:181], v[194:197], v[82:85]
	v_mfma_f32_16x16x32_bf16 v[78:81], v[170:173], v[206:209], v[78:81]
	v_mfma_f32_16x16x32_bf16 v[74:77], v[178:181], v[206:209], v[74:77]
	v_mfma_f32_16x16x32_bf16 v[70:73], v[170:173], v[214:217], v[70:73]
	v_mfma_f32_16x16x32_bf16 v[66:69], v[178:181], v[214:217], v[66:69]
	s_setprio 0
	s_barrier
	s_add_i32 s72, s56, s4
	v_lshl_add_u64 v[160:161], s[54:55], 0, v[130:131]
	s_mov_b32 m0, s72
	ds_read_b128 v[182:185], v142 offset:16384
	ds_read_b128 v[186:189], v142 offset:17408
	ds_read_b128 v[190:193], v142 offset:18432
	ds_read_b128 v[194:197], v142 offset:19456
	ds_read_b128 v[202:205], v142 offset:20480
	ds_read_b128 v[206:209], v142 offset:21504
	ds_read_b128 v[210:213], v142 offset:22528
	ds_read_b128 v[214:217], v142 offset:23552
	global_load_lds_dwordx4 v[160:161], off
	s_add_i32 m0, s72, 0x2000
	s_add_u32 s72, s54, 0x100000
	v_lshl_add_u64 v[198:199], s[54:55], 0, v[132:133]
	s_addc_u32 s73, s55, 0
	s_add_i32 s74, s57, s4
	global_load_lds_dwordx4 v[198:199], off
	v_lshl_add_u64 v[218:219], s[72:73], 0, v[130:131]
	s_mov_b32 m0, s74
	v_lshl_add_u64 v[220:221], s[66:67], 0, v[132:133]
	global_load_lds_dwordx4 v[218:219], off
	v_lshl_add_u64 v[218:219], s[72:73], 0, v[132:133]
	s_add_i32 m0, s74, 0x2000
	s_nop 0
	global_load_lds_dwordx4 v[218:219], off
	v_lshl_add_u64 v[218:219], s[66:67], 0, v[130:131]
	s_mov_b32 m0, s23
	s_nop 0
	global_load_lds_dwordx4 v[218:219], off
	s_mov_b32 m0, s27
	s_nop 0
	global_load_lds_dwordx4 v[220:221], off
	s_waitcnt vmcnt(8)
	s_waitcnt lgkmcnt(0)
	s_barrier
	s_setprio 1
	s_waitcnt lgkmcnt(0)
	v_mfma_f32_16x16x32_bf16 v[62:65], v[144:147], v[182:185], v[62:65]
	v_mfma_f32_16x16x32_bf16 v[58:61], v[152:155], v[182:185], v[58:61]
	v_mfma_f32_16x16x32_bf16 v[54:57], v[144:147], v[190:193], v[54:57]
	v_mfma_f32_16x16x32_bf16 v[50:53], v[152:155], v[190:193], v[50:53]
	v_mfma_f32_16x16x32_bf16 v[46:49], v[144:147], v[202:205], v[46:49]
	v_mfma_f32_16x16x32_bf16 v[38:41], v[152:155], v[202:205], v[38:41]
	v_mfma_f32_16x16x32_bf16 v[30:33], v[144:147], v[210:213], v[30:33]
	v_mfma_f32_16x16x32_bf16 v[22:25], v[152:155], v[210:213], v[22:25]
	v_mfma_f32_16x16x32_bf16 v[62:65], v[148:151], v[186:189], v[62:65]
	v_mfma_f32_16x16x32_bf16 v[58:61], v[156:159], v[186:189], v[58:61]
	v_mfma_f32_16x16x32_bf16 v[54:57], v[148:151], v[194:197], v[54:57]
	v_mfma_f32_16x16x32_bf16 v[50:53], v[156:159], v[194:197], v[50:53]
	v_mfma_f32_16x16x32_bf16 v[46:49], v[148:151], v[206:209], v[46:49]
	v_mfma_f32_16x16x32_bf16 v[38:41], v[156:159], v[206:209], v[38:41]
	v_mfma_f32_16x16x32_bf16 v[30:33], v[148:151], v[214:217], v[30:33]
	v_mfma_f32_16x16x32_bf16 v[22:25], v[156:159], v[214:217], v[22:25]
	s_setprio 0
	s_setprio 1
	v_mfma_f32_16x16x32_bf16 v[42:45], v[166:169], v[182:185], v[42:45]
	v_mfma_f32_16x16x32_bf16 v[34:37], v[174:177], v[182:185], v[34:37]
	v_mfma_f32_16x16x32_bf16 v[26:29], v[166:169], v[190:193], v[26:29]
	v_mfma_f32_16x16x32_bf16 v[18:21], v[174:177], v[190:193], v[18:21]
	v_mfma_f32_16x16x32_bf16 v[14:17], v[166:169], v[202:205], v[14:17]
	v_mfma_f32_16x16x32_bf16 v[10:13], v[174:177], v[202:205], v[10:13]
	v_mfma_f32_16x16x32_bf16 v[6:9], v[166:169], v[210:213], v[6:9]
	v_mfma_f32_16x16x32_bf16 v[2:5], v[174:177], v[210:213], v[2:5]
	v_mfma_f32_16x16x32_bf16 v[42:45], v[170:173], v[186:189], v[42:45]
	v_mfma_f32_16x16x32_bf16 v[34:37], v[178:181], v[186:189], v[34:37]
	v_mfma_f32_16x16x32_bf16 v[26:29], v[170:173], v[194:197], v[26:29]
	v_mfma_f32_16x16x32_bf16 v[18:21], v[178:181], v[194:197], v[18:21]
	v_mfma_f32_16x16x32_bf16 v[14:17], v[170:173], v[206:209], v[14:17]
	v_mfma_f32_16x16x32_bf16 v[10:13], v[178:181], v[206:209], v[10:13]
	v_mfma_f32_16x16x32_bf16 v[6:9], v[170:173], v[214:217], v[6:9]
	v_mfma_f32_16x16x32_bf16 v[2:5], v[178:181], v[214:217], v[2:5]
	s_setprio 0
	s_barrier
	s_add_i32 s72, 0, 0x18000
	s_add_i32 s73, 0, 0x1c000
	v_add_u32_e32 v156, s72, v138
	v_add_u32_e32 v163, s73, v138
	ds_read_b128 v[144:147], v156
	ds_read_b128 v[148:151], v156 offset:1024
	ds_read_b128 v[152:155], v156 offset:2048
	ds_read_b128 v[156:159], v156 offset:3072
	ds_read_b128 v[166:169], v163
	ds_read_b128 v[170:173], v163 offset:1024
	ds_read_b128 v[174:177], v163 offset:2048
	ds_read_b128 v[178:181], v163 offset:3072
	s_add_u32 s66, s66, 0x100000
	s_addc_u32 s67, s67, 0
	s_mov_b32 m0, s36
	v_lshl_add_u64 v[222:223], s[66:67], 0, v[130:131]
	ds_read_b128 v[182:185], v142 offset:32768
	ds_read_b128 v[186:189], v142 offset:33792
	ds_read_b128 v[190:193], v142 offset:34816
	ds_read_b128 v[194:197], v142 offset:35840
	ds_read_b128 v[202:205], v142 offset:36864
	ds_read_b128 v[206:209], v142 offset:37888
	ds_read_b128 v[210:213], v142 offset:38912
	ds_read_b128 v[214:217], v142 offset:39936
	global_load_lds_dwordx4 v[222:223], off
	v_lshl_add_u64 v[222:223], s[66:67], 0, v[132:133]
	s_mov_b32 m0, s37
	s_nop 0
	global_load_lds_dwordx4 v[222:223], off
	s_waitcnt vmcnt(8)
	s_waitcnt lgkmcnt(0)
	s_barrier
	s_setprio 1
	s_waitcnt lgkmcnt(0)
	v_mfma_f32_16x16x32_bf16 v[126:129], v[144:147], v[182:185], v[126:129]
	v_mfma_f32_16x16x32_bf16 v[122:125], v[152:155], v[182:185], v[122:125]
	v_mfma_f32_16x16x32_bf16 v[118:121], v[144:147], v[190:193], v[118:121]
	v_mfma_f32_16x16x32_bf16 v[114:117], v[152:155], v[190:193], v[114:117]
	v_mfma_f32_16x16x32_bf16 v[110:113], v[144:147], v[202:205], v[110:113]
	v_mfma_f32_16x16x32_bf16 v[102:105], v[152:155], v[202:205], v[102:105]
	v_mfma_f32_16x16x32_bf16 v[94:97], v[144:147], v[210:213], v[94:97]
	v_mfma_f32_16x16x32_bf16 v[86:89], v[152:155], v[210:213], v[86:89]
	v_mfma_f32_16x16x32_bf16 v[126:129], v[148:151], v[186:189], v[126:129]
	v_mfma_f32_16x16x32_bf16 v[122:125], v[156:159], v[186:189], v[122:125]
	v_mfma_f32_16x16x32_bf16 v[118:121], v[148:151], v[194:197], v[118:121]
	v_mfma_f32_16x16x32_bf16 v[114:117], v[156:159], v[194:197], v[114:117]
	v_mfma_f32_16x16x32_bf16 v[110:113], v[148:151], v[206:209], v[110:113]
	v_mfma_f32_16x16x32_bf16 v[102:105], v[156:159], v[206:209], v[102:105]
	v_mfma_f32_16x16x32_bf16 v[94:97], v[148:151], v[214:217], v[94:97]
	v_mfma_f32_16x16x32_bf16 v[86:89], v[156:159], v[214:217], v[86:89]
	s_setprio 0
	s_setprio 1
	v_mfma_f32_16x16x32_bf16 v[106:109], v[166:169], v[182:185], v[106:109]
	v_mfma_f32_16x16x32_bf16 v[98:101], v[174:177], v[182:185], v[98:101]
	v_mfma_f32_16x16x32_bf16 v[90:93], v[166:169], v[190:193], v[90:93]
	v_mfma_f32_16x16x32_bf16 v[82:85], v[174:177], v[190:193], v[82:85]
	v_mfma_f32_16x16x32_bf16 v[78:81], v[166:169], v[202:205], v[78:81]
	v_mfma_f32_16x16x32_bf16 v[74:77], v[174:177], v[202:205], v[74:77]
	v_mfma_f32_16x16x32_bf16 v[70:73], v[166:169], v[210:213], v[70:73]
	v_mfma_f32_16x16x32_bf16 v[66:69], v[174:177], v[210:213], v[66:69]
	v_mfma_f32_16x16x32_bf16 v[106:109], v[170:173], v[186:189], v[106:109]
	v_mfma_f32_16x16x32_bf16 v[98:101], v[178:181], v[186:189], v[98:101]
	v_mfma_f32_16x16x32_bf16 v[90:93], v[170:173], v[194:197], v[90:93]
	v_mfma_f32_16x16x32_bf16 v[82:85], v[178:181], v[194:197], v[82:85]
	v_mfma_f32_16x16x32_bf16 v[78:81], v[170:173], v[206:209], v[78:81]
	v_mfma_f32_16x16x32_bf16 v[74:77], v[178:181], v[206:209], v[74:77]
	v_mfma_f32_16x16x32_bf16 v[70:73], v[170:173], v[214:217], v[70:73]
	v_mfma_f32_16x16x32_bf16 v[66:69], v[178:181], v[214:217], v[66:69]
	s_setprio 0
	s_barrier
	s_add_i32 s66, s72, s4
	v_lshl_add_u64 v[160:161], v[160:161], 0, s[24:25]
	s_mov_b32 m0, s66
	ds_read_b128 v[182:185], v142 offset:49152
	ds_read_b128 v[186:189], v142 offset:50176
	ds_read_b128 v[190:193], v142 offset:51200
	ds_read_b128 v[194:197], v142 offset:52224
	ds_read_b128 v[202:205], v142 offset:53248
	ds_read_b128 v[206:209], v142 offset:54272
	ds_read_b128 v[210:213], v142 offset:55296
	ds_read_b128 v[214:217], v142 offset:56320
	global_load_lds_dwordx4 v[160:161], off
	s_add_i32 m0, s66, 0x2000
	s_add_u32 s54, s54, 0x100080
	v_lshl_add_u64 v[160:161], v[198:199], 0, s[24:25]
	s_addc_u32 s55, s55, 0
	s_add_i32 s66, s73, s4
	global_load_lds_dwordx4 v[160:161], off
	v_lshl_add_u64 v[160:161], s[54:55], 0, v[130:131]
	s_mov_b32 m0, s66
	s_nop 0
	global_load_lds_dwordx4 v[160:161], off
	v_lshl_add_u64 v[160:161], s[54:55], 0, v[132:133]
	s_add_i32 m0, s66, 0x2000
	s_nop 0
	global_load_lds_dwordx4 v[160:161], off
	v_lshl_add_u64 v[160:161], v[218:219], 0, s[24:25]
	s_mov_b32 m0, s39
	s_nop 0
	global_load_lds_dwordx4 v[160:161], off
	v_lshl_add_u64 v[160:161], v[220:221], 0, s[24:25]
	s_mov_b32 m0, s52
	s_nop 0
	global_load_lds_dwordx4 v[160:161], off
	s_waitcnt vmcnt(8)
	s_waitcnt lgkmcnt(0)
	s_barrier
	s_setprio 1
	s_waitcnt lgkmcnt(0)
	v_mfma_f32_16x16x32_bf16 v[62:65], v[144:147], v[182:185], v[62:65]
	v_mfma_f32_16x16x32_bf16 v[58:61], v[152:155], v[182:185], v[58:61]
	v_mfma_f32_16x16x32_bf16 v[54:57], v[144:147], v[190:193], v[54:57]
	v_mfma_f32_16x16x32_bf16 v[50:53], v[152:155], v[190:193], v[50:53]
	v_mfma_f32_16x16x32_bf16 v[46:49], v[144:147], v[202:205], v[46:49]
	v_mfma_f32_16x16x32_bf16 v[38:41], v[152:155], v[202:205], v[38:41]
	v_mfma_f32_16x16x32_bf16 v[30:33], v[144:147], v[210:213], v[30:33]
	v_mfma_f32_16x16x32_bf16 v[22:25], v[152:155], v[210:213], v[22:25]
	v_mfma_f32_16x16x32_bf16 v[62:65], v[148:151], v[186:189], v[62:65]
	v_mfma_f32_16x16x32_bf16 v[58:61], v[156:159], v[186:189], v[58:61]
	v_mfma_f32_16x16x32_bf16 v[54:57], v[148:151], v[194:197], v[54:57]
	v_mfma_f32_16x16x32_bf16 v[50:53], v[156:159], v[194:197], v[50:53]
	v_mfma_f32_16x16x32_bf16 v[46:49], v[148:151], v[206:209], v[46:49]
	v_mfma_f32_16x16x32_bf16 v[38:41], v[156:159], v[206:209], v[38:41]
	v_mfma_f32_16x16x32_bf16 v[30:33], v[148:151], v[214:217], v[30:33]
	v_mfma_f32_16x16x32_bf16 v[22:25], v[156:159], v[214:217], v[22:25]
	s_setprio 0
	s_setprio 1
	v_mfma_f32_16x16x32_bf16 v[42:45], v[166:169], v[182:185], v[42:45]
	v_mfma_f32_16x16x32_bf16 v[34:37], v[174:177], v[182:185], v[34:37]
	v_mfma_f32_16x16x32_bf16 v[26:29], v[166:169], v[190:193], v[26:29]
	v_mfma_f32_16x16x32_bf16 v[18:21], v[174:177], v[190:193], v[18:21]
	v_mfma_f32_16x16x32_bf16 v[14:17], v[166:169], v[202:205], v[14:17]
	v_mfma_f32_16x16x32_bf16 v[10:13], v[174:177], v[202:205], v[10:13]
	v_mfma_f32_16x16x32_bf16 v[6:9], v[166:169], v[210:213], v[6:9]
	v_mfma_f32_16x16x32_bf16 v[2:5], v[174:177], v[210:213], v[2:5]
	v_mfma_f32_16x16x32_bf16 v[42:45], v[170:173], v[186:189], v[42:45]
	v_mfma_f32_16x16x32_bf16 v[34:37], v[178:181], v[186:189], v[34:37]
	v_mfma_f32_16x16x32_bf16 v[26:29], v[170:173], v[194:197], v[26:29]
	v_mfma_f32_16x16x32_bf16 v[18:21], v[178:181], v[194:197], v[18:21]
	v_mfma_f32_16x16x32_bf16 v[14:17], v[170:173], v[206:209], v[14:17]
	v_mfma_f32_16x16x32_bf16 v[10:13], v[178:181], v[206:209], v[10:13]
	v_mfma_f32_16x16x32_bf16 v[6:9], v[170:173], v[214:217], v[6:9]
	v_mfma_f32_16x16x32_bf16 v[2:5], v[178:181], v[214:217], v[2:5]
	s_setprio 0
	s_barrier
	s_add_i32 s71, s71, 2
	s_add_u32 s64, s64, 0x100
	s_addc_u32 s65, s65, 0
	s_add_u32 s69, s69, 0x100
	s_addc_u32 s70, s70, 0
	s_cmp_gt_u32 s71, 61
	s_cbranch_scc0 .LBB0_248
	s_and_b64 vcc, exec, s[30:31]
	s_cbranch_vccz .LBB0_251
	s_barrier

.LBB0_377:
	ds_read_b128 v[138:141], v191
	ds_read_b128 v[142:145], v191 offset:1024
	ds_read_b128 v[146:149], v191 offset:2048
	ds_read_b128 v[150:153], v191 offset:3072
	ds_read_b128 v[180:183], v192
	ds_read_b128 v[184:187], v192 offset:1024
	ds_read_b128 v[202:205], v192 offset:2048
	ds_read_b128 v[206:209], v192 offset:3072
	v_lshl_add_u64 v[188:189], v[4:5], 0, s[74:75]
	s_add_i32 s36, s38, 0xc000
	v_lshl_add_u64 v[198:199], v[188:189], 0, s[30:31]
	s_mov_b32 m0, s36
	ds_read_b128 v[210:213], v193
	ds_read_b128 v[214:217], v193 offset:1024
	ds_read_b128 v[218:221], v193 offset:2048
	ds_read_b128 v[222:225], v193 offset:3072
	ds_read_b128 v[226:229], v193 offset:4096
	ds_read_b128 v[230:233], v193 offset:5120
	ds_read_b128 v[234:237], v193 offset:6144
	ds_read_b128 v[238:241], v193 offset:7168
	global_load_lds_dwordx4 v[198:199], off
	v_lshl_add_u64 v[198:199], v[2:3], 0, s[74:75]
	s_add_i32 s37, s38, 0xe000
	v_lshl_add_u64 v[242:243], v[198:199], 0, s[30:31]
	s_mov_b32 m0, s37
	s_nop 0
	global_load_lds_dwordx4 v[242:243], off
	s_waitcnt vmcnt(8)
	s_waitcnt lgkmcnt(0)
	s_barrier
	s_setprio 1
	s_waitcnt lgkmcnt(0)
	v_mfma_f32_16x16x32_bf16 v[134:137], v[138:141], v[210:213], v[134:137]
	v_mfma_f32_16x16x32_bf16 v[130:133], v[146:149], v[210:213], v[130:133]
	v_mfma_f32_16x16x32_bf16 v[118:121], v[138:141], v[218:221], v[118:121]
	v_mfma_f32_16x16x32_bf16 v[114:117], v[146:149], v[218:221], v[114:117]
	v_mfma_f32_16x16x32_bf16 v[102:105], v[138:141], v[226:229], v[102:105]
	v_mfma_f32_16x16x32_bf16 v[98:101], v[146:149], v[226:229], v[98:101]
	v_mfma_f32_16x16x32_bf16 v[86:89], v[138:141], v[234:237], v[86:89]
	v_mfma_f32_16x16x32_bf16 v[82:85], v[146:149], v[234:237], v[82:85]
	v_mfma_f32_16x16x32_bf16 v[134:137], v[142:145], v[214:217], v[134:137]
	v_mfma_f32_16x16x32_bf16 v[130:133], v[150:153], v[214:217], v[130:133]
	v_mfma_f32_16x16x32_bf16 v[118:121], v[142:145], v[222:225], v[118:121]
	v_mfma_f32_16x16x32_bf16 v[114:117], v[150:153], v[222:225], v[114:117]
	v_mfma_f32_16x16x32_bf16 v[102:105], v[142:145], v[230:233], v[102:105]
	v_mfma_f32_16x16x32_bf16 v[98:101], v[150:153], v[230:233], v[98:101]
	v_mfma_f32_16x16x32_bf16 v[86:89], v[142:145], v[238:241], v[86:89]
	v_mfma_f32_16x16x32_bf16 v[82:85], v[150:153], v[238:241], v[82:85]
	s_setprio 0
	s_setprio 1
	v_mfma_f32_16x16x32_bf16 v[126:129], v[180:183], v[210:213], v[126:129]
	v_mfma_f32_16x16x32_bf16 v[122:125], v[202:205], v[210:213], v[122:125]
	v_mfma_f32_16x16x32_bf16 v[110:113], v[180:183], v[218:221], v[110:113]
	v_mfma_f32_16x16x32_bf16 v[106:109], v[202:205], v[218:221], v[106:109]
	v_mfma_f32_16x16x32_bf16 v[94:97], v[180:183], v[226:229], v[94:97]
	v_mfma_f32_16x16x32_bf16 v[90:93], v[202:205], v[226:229], v[90:93]
	v_mfma_f32_16x16x32_bf16 v[78:81], v[180:183], v[234:237], v[78:81]
	v_mfma_f32_16x16x32_bf16 v[74:77], v[202:205], v[234:237], v[74:77]
	v_mfma_f32_16x16x32_bf16 v[126:129], v[184:187], v[214:217], v[126:129]
	v_mfma_f32_16x16x32_bf16 v[122:125], v[206:209], v[214:217], v[122:125]
	v_mfma_f32_16x16x32_bf16 v[110:113], v[184:187], v[222:225], v[110:113]
	v_mfma_f32_16x16x32_bf16 v[106:109], v[206:209], v[222:225], v[106:109]
	v_mfma_f32_16x16x32_bf16 v[94:97], v[184:187], v[230:233], v[94:97]
	v_mfma_f32_16x16x32_bf16 v[90:93], v[206:209], v[230:233], v[90:93]
	v_mfma_f32_16x16x32_bf16 v[78:81], v[184:187], v[238:241], v[78:81]
	v_mfma_f32_16x16x32_bf16 v[74:77], v[206:209], v[238:241], v[74:77]
	s_setprio 0
	s_barrier
	v_lshl_add_u64 v[246:247], v[8:9], 0, s[74:75]
	s_add_i32 s83, s79, s27
	v_lshl_add_u64 v[242:243], v[246:247], 0, s[58:59]
	s_mov_b32 m0, s83
	v_lshl_add_u64 v[248:249], v[6:7], 0, s[74:75]
	s_add_i32 s84, s83, 0x2000
	ds_read_b128 v[210:213], v193 offset:16384
	ds_read_b128 v[214:217], v193 offset:17408
	ds_read_b128 v[218:221], v193 offset:18432
	ds_read_b128 v[222:225], v193 offset:19456
	ds_read_b128 v[226:229], v193 offset:20480
	ds_read_b128 v[230:233], v193 offset:21504
	ds_read_b128 v[234:237], v193 offset:22528
	ds_read_b128 v[238:241], v193 offset:23552
	global_load_lds_dwordx4 v[242:243], off
	v_lshl_add_u64 v[242:243], v[248:249], 0, s[58:59]
	s_mov_b32 m0, s84
	s_add_i32 s85, s80, s27
	global_load_lds_dwordx4 v[242:243], off
	v_lshl_add_u64 v[242:243], v[246:247], 0, s[60:61]
	s_mov_b32 m0, s85
	s_add_i32 s86, s85, 0x2000
	global_load_lds_dwordx4 v[242:243], off
	v_lshl_add_u64 v[242:243], v[248:249], 0, s[60:61]
	s_mov_b32 m0, s86
	s_nop 0
	global_load_lds_dwordx4 v[242:243], off
	v_lshl_add_u64 v[242:243], v[188:189], 0, s[58:59]
	s_mov_b32 m0, s38
	s_nop 0
	global_load_lds_dwordx4 v[242:243], off
	v_lshl_add_u64 v[242:243], v[198:199], 0, s[58:59]
	s_mov_b32 m0, s39
	s_nop 0
	global_load_lds_dwordx4 v[242:243], off
	s_waitcnt vmcnt(8)
	s_waitcnt lgkmcnt(0)
	s_barrier
	s_setprio 1
	s_waitcnt lgkmcnt(0)
	v_mfma_f32_16x16x32_bf16 v[70:73], v[138:141], v[210:213], v[70:73]
	v_mfma_f32_16x16x32_bf16 v[66:69], v[146:149], v[210:213], v[66:69]
	v_mfma_f32_16x16x32_bf16 v[54:57], v[138:141], v[218:221], v[54:57]
	v_mfma_f32_16x16x32_bf16 v[50:53], v[146:149], v[218:221], v[50:53]
	v_mfma_f32_16x16x32_bf16 v[38:41], v[138:141], v[226:229], v[38:41]
	v_mfma_f32_16x16x32_bf16 v[34:37], v[146:149], v[226:229], v[34:37]
	v_mfma_f32_16x16x32_bf16 v[22:25], v[138:141], v[234:237], v[22:25]
	v_mfma_f32_16x16x32_bf16 v[18:21], v[146:149], v[234:237], v[18:21]
	v_mfma_f32_16x16x32_bf16 v[70:73], v[142:145], v[214:217], v[70:73]
	v_mfma_f32_16x16x32_bf16 v[66:69], v[150:153], v[214:217], v[66:69]
	v_mfma_f32_16x16x32_bf16 v[54:57], v[142:145], v[222:225], v[54:57]
	v_mfma_f32_16x16x32_bf16 v[50:53], v[150:153], v[222:225], v[50:53]
	v_mfma_f32_16x16x32_bf16 v[38:41], v[142:145], v[230:233], v[38:41]
	v_mfma_f32_16x16x32_bf16 v[34:37], v[150:153], v[230:233], v[34:37]
	v_mfma_f32_16x16x32_bf16 v[22:25], v[142:145], v[238:241], v[22:25]
	v_mfma_f32_16x16x32_bf16 v[18:21], v[150:153], v[238:241], v[18:21]
	s_setprio 0
	s_setprio 1
	v_mfma_f32_16x16x32_bf16 v[62:65], v[180:183], v[210:213], v[62:65]
	v_mfma_f32_16x16x32_bf16 v[58:61], v[202:205], v[210:213], v[58:61]
	v_mfma_f32_16x16x32_bf16 v[46:49], v[180:183], v[218:221], v[46:49]
	v_mfma_f32_16x16x32_bf16 v[42:45], v[202:205], v[218:221], v[42:45]
	v_mfma_f32_16x16x32_bf16 v[30:33], v[180:183], v[226:229], v[30:33]
	v_mfma_f32_16x16x32_bf16 v[26:29], v[202:205], v[226:229], v[26:29]
	v_mfma_f32_16x16x32_bf16 v[14:17], v[180:183], v[234:237], v[14:17]
	v_mfma_f32_16x16x32_bf16 v[10:13], v[202:205], v[234:237], v[10:13]
	v_mfma_f32_16x16x32_bf16 v[62:65], v[184:187], v[214:217], v[62:65]
	v_mfma_f32_16x16x32_bf16 v[58:61], v[206:209], v[214:217], v[58:61]
	v_mfma_f32_16x16x32_bf16 v[46:49], v[184:187], v[222:225], v[46:49]
	v_mfma_f32_16x16x32_bf16 v[42:45], v[206:209], v[222:225], v[42:45]
	v_mfma_f32_16x16x32_bf16 v[30:33], v[184:187], v[230:233], v[30:33]
	v_mfma_f32_16x16x32_bf16 v[26:29], v[206:209], v[230:233], v[26:29]
	v_mfma_f32_16x16x32_bf16 v[14:17], v[184:187], v[238:241], v[14:17]
	v_mfma_f32_16x16x32_bf16 v[10:13], v[206:209], v[238:241], v[10:13]
	s_setprio 0
	s_barrier
	s_add_i32 s87, 0, 0x18000
	s_add_i32 s89, 0, 0x1c000
	v_add_u32_e32 v146, s87, v190
	v_add_u32_e32 v147, s89, v190
	ds_read_b128 v[138:141], v146
	ds_read_b128 v[142:145], v146 offset:1024
	ds_read_b128 v[148:151], v146 offset:2048
	ds_read_b128 v[180:183], v146 offset:3072
	ds_read_b128 v[184:187], v147
	ds_read_b128 v[202:205], v147 offset:1024
	ds_read_b128 v[206:209], v147 offset:2048
	ds_read_b128 v[210:213], v147 offset:3072
	s_mov_b32 m0, s52
	v_lshl_add_u64 v[152:153], v[188:189], 0, s[60:61]
	ds_read_b128 v[214:217], v193 offset:32768
	ds_read_b128 v[218:221], v193 offset:33792
	ds_read_b128 v[222:225], v193 offset:34816
	ds_read_b128 v[226:229], v193 offset:35840
	ds_read_b128 v[230:233], v193 offset:36864
	ds_read_b128 v[234:237], v193 offset:37888
	ds_read_b128 v[238:241], v193 offset:38912
	ds_read_b128 v[242:245], v193 offset:39936
	global_load_lds_dwordx4 v[152:153], off
	v_lshl_add_u64 v[152:153], v[198:199], 0, s[60:61]
	s_mov_b32 m0, s53
	s_nop 0
	global_load_lds_dwordx4 v[152:153], off
	s_waitcnt vmcnt(8)
	s_waitcnt lgkmcnt(0)
	s_barrier
	s_setprio 1
	s_waitcnt lgkmcnt(0)
	v_mfma_f32_16x16x32_bf16 v[134:137], v[138:141], v[214:217], v[134:137]
	v_mfma_f32_16x16x32_bf16 v[130:133], v[148:151], v[214:217], v[130:133]
	v_mfma_f32_16x16x32_bf16 v[118:121], v[138:141], v[222:225], v[118:121]
	v_mfma_f32_16x16x32_bf16 v[114:117], v[148:151], v[222:225], v[114:117]
	v_mfma_f32_16x16x32_bf16 v[102:105], v[138:141], v[230:233], v[102:105]
	v_mfma_f32_16x16x32_bf16 v[98:101], v[148:151], v[230:233], v[98:101]
	v_mfma_f32_16x16x32_bf16 v[86:89], v[138:141], v[238:241], v[86:89]
	v_mfma_f32_16x16x32_bf16 v[82:85], v[148:151], v[238:241], v[82:85]
	v_mfma_f32_16x16x32_bf16 v[134:137], v[142:145], v[218:221], v[134:137]
	v_mfma_f32_16x16x32_bf16 v[130:133], v[180:183], v[218:221], v[130:133]
	v_mfma_f32_16x16x32_bf16 v[118:121], v[142:145], v[226:229], v[118:121]
	v_mfma_f32_16x16x32_bf16 v[114:117], v[180:183], v[226:229], v[114:117]
	v_mfma_f32_16x16x32_bf16 v[102:105], v[142:145], v[234:237], v[102:105]
	v_mfma_f32_16x16x32_bf16 v[98:101], v[180:183], v[234:237], v[98:101]
	v_mfma_f32_16x16x32_bf16 v[86:89], v[142:145], v[242:245], v[86:89]
	v_mfma_f32_16x16x32_bf16 v[82:85], v[180:183], v[242:245], v[82:85]
	s_setprio 0
	s_setprio 1
	v_mfma_f32_16x16x32_bf16 v[126:129], v[184:187], v[214:217], v[126:129]
	v_mfma_f32_16x16x32_bf16 v[122:125], v[206:209], v[214:217], v[122:125]
	v_mfma_f32_16x16x32_bf16 v[110:113], v[184:187], v[222:225], v[110:113]
	v_mfma_f32_16x16x32_bf16 v[106:109], v[206:209], v[222:225], v[106:109]
	v_mfma_f32_16x16x32_bf16 v[94:97], v[184:187], v[230:233], v[94:97]
	v_mfma_f32_16x16x32_bf16 v[90:93], v[206:209], v[230:233], v[90:93]
	v_mfma_f32_16x16x32_bf16 v[78:81], v[184:187], v[238:241], v[78:81]
	v_mfma_f32_16x16x32_bf16 v[74:77], v[206:209], v[238:241], v[74:77]
	v_mfma_f32_16x16x32_bf16 v[126:129], v[202:205], v[218:221], v[126:129]
	v_mfma_f32_16x16x32_bf16 v[122:125], v[210:213], v[218:221], v[122:125]
	v_mfma_f32_16x16x32_bf16 v[110:113], v[202:205], v[226:229], v[110:113]
	v_mfma_f32_16x16x32_bf16 v[106:109], v[210:213], v[226:229], v[106:109]
	v_mfma_f32_16x16x32_bf16 v[94:97], v[202:205], v[234:237], v[94:97]
	v_mfma_f32_16x16x32_bf16 v[90:93], v[210:213], v[234:237], v[90:93]
	v_mfma_f32_16x16x32_bf16 v[78:81], v[202:205], v[242:245], v[78:81]
	v_mfma_f32_16x16x32_bf16 v[74:77], v[210:213], v[242:245], v[74:77]
	s_setprio 0
	s_barrier
	s_add_i32 s87, s87, s27
	v_lshl_add_u64 v[152:153], v[246:247], 0, s[62:63]
	s_mov_b32 m0, s87
	s_add_i32 s88, s87, 0x2000
	ds_read_b128 v[214:217], v193 offset:49152
	ds_read_b128 v[218:221], v193 offset:50176
	ds_read_b128 v[222:225], v193 offset:51200
	ds_read_b128 v[226:229], v193 offset:52224
	ds_read_b128 v[230:233], v193 offset:53248
	ds_read_b128 v[234:237], v193 offset:54272
	ds_read_b128 v[238:241], v193 offset:55296
	ds_read_b128 v[242:245], v193 offset:56320
	global_load_lds_dwordx4 v[152:153], off
	v_lshl_add_u64 v[152:153], v[248:249], 0, s[62:63]
	s_mov_b32 m0, s88
	s_add_i32 s89, s89, s27
	global_load_lds_dwordx4 v[152:153], off
	v_lshl_add_u64 v[152:153], v[246:247], 0, s[64:65]
	s_mov_b32 m0, s89
	s_add_i32 s90, s89, 0x2000
	global_load_lds_dwordx4 v[152:153], off
	v_lshl_add_u64 v[152:153], v[248:249], 0, s[64:65]
	s_mov_b32 m0, s90
	s_nop 0
	global_load_lds_dwordx4 v[152:153], off
	v_lshl_add_u64 v[152:153], v[188:189], 0, s[62:63]
	s_mov_b32 m0, s57
	s_nop 0
	global_load_lds_dwordx4 v[152:153], off
	v_lshl_add_u64 v[152:153], v[198:199], 0, s[62:63]
	s_mov_b32 m0, s67
	s_nop 0
	global_load_lds_dwordx4 v[152:153], off
	s_waitcnt vmcnt(8)
	s_waitcnt lgkmcnt(0)
	s_barrier
	s_setprio 1
	s_waitcnt lgkmcnt(0)
	v_mfma_f32_16x16x32_bf16 v[70:73], v[138:141], v[214:217], v[70:73]
	v_mfma_f32_16x16x32_bf16 v[66:69], v[148:151], v[214:217], v[66:69]
	v_mfma_f32_16x16x32_bf16 v[54:57], v[138:141], v[222:225], v[54:57]
	v_mfma_f32_16x16x32_bf16 v[50:53], v[148:151], v[222:225], v[50:53]
	v_mfma_f32_16x16x32_bf16 v[38:41], v[138:141], v[230:233], v[38:41]
	v_mfma_f32_16x16x32_bf16 v[34:37], v[148:151], v[230:233], v[34:37]
	v_mfma_f32_16x16x32_bf16 v[22:25], v[138:141], v[238:241], v[22:25]
	v_mfma_f32_16x16x32_bf16 v[18:21], v[148:151], v[238:241], v[18:21]
	v_mfma_f32_16x16x32_bf16 v[70:73], v[142:145], v[218:221], v[70:73]
	v_mfma_f32_16x16x32_bf16 v[66:69], v[180:183], v[218:221], v[66:69]
	v_mfma_f32_16x16x32_bf16 v[54:57], v[142:145], v[226:229], v[54:57]
	v_mfma_f32_16x16x32_bf16 v[50:53], v[180:183], v[226:229], v[50:53]
	v_mfma_f32_16x16x32_bf16 v[38:41], v[142:145], v[234:237], v[38:41]
	v_mfma_f32_16x16x32_bf16 v[34:37], v[180:183], v[234:237], v[34:37]
	v_mfma_f32_16x16x32_bf16 v[22:25], v[142:145], v[242:245], v[22:25]
	v_mfma_f32_16x16x32_bf16 v[18:21], v[180:183], v[242:245], v[18:21]
	s_setprio 0
	s_setprio 1
	v_mfma_f32_16x16x32_bf16 v[62:65], v[184:187], v[214:217], v[62:65]
	v_mfma_f32_16x16x32_bf16 v[58:61], v[206:209], v[214:217], v[58:61]
	v_mfma_f32_16x16x32_bf16 v[46:49], v[184:187], v[222:225], v[46:49]
	v_mfma_f32_16x16x32_bf16 v[42:45], v[206:209], v[222:225], v[42:45]
	v_mfma_f32_16x16x32_bf16 v[30:33], v[184:187], v[230:233], v[30:33]
	v_mfma_f32_16x16x32_bf16 v[26:29], v[206:209], v[230:233], v[26:29]
	v_mfma_f32_16x16x32_bf16 v[14:17], v[184:187], v[238:241], v[14:17]
	v_mfma_f32_16x16x32_bf16 v[10:13], v[206:209], v[238:241], v[10:13]
	v_mfma_f32_16x16x32_bf16 v[62:65], v[202:205], v[218:221], v[62:65]
	v_mfma_f32_16x16x32_bf16 v[58:61], v[210:213], v[218:221], v[58:61]
	v_mfma_f32_16x16x32_bf16 v[46:49], v[202:205], v[226:229], v[46:49]
	v_mfma_f32_16x16x32_bf16 v[42:45], v[210:213], v[226:229], v[42:45]
	v_mfma_f32_16x16x32_bf16 v[30:33], v[202:205], v[234:237], v[30:33]
	v_mfma_f32_16x16x32_bf16 v[26:29], v[210:213], v[234:237], v[26:29]
	v_mfma_f32_16x16x32_bf16 v[14:17], v[202:205], v[242:245], v[14:17]
	v_mfma_f32_16x16x32_bf16 v[10:13], v[210:213], v[242:245], v[10:13]
	s_setprio 0
	s_barrier
	s_add_i32 s54, s54, 2
	s_add_u32 s74, s74, 0x100
	s_addc_u32 s75, s75, 0
	s_cmpk_lt_u32 s54, 0x8a
	s_cbranch_scc1 .LBB0_377
	s_add_u32 s54, s72, 0x2b4680
	s_addc_u32 s55, s73, 0
	s_add_u32 s74, s70, 0x4700
	s_addc_u32 s75, s71, 0
	s_movk_i32 s91, 0x8a
.LBB0_379:
	ds_read_b128 v[2:5], v191
	ds_read_b128 v[6:9], v191 offset:1024
	ds_read_b128 v[180:183], v191 offset:2048
	ds_read_b128 v[184:187], v191 offset:3072
	ds_read_b128 v[202:205], v192
	ds_read_b128 v[206:209], v192 offset:1024
	ds_read_b128 v[210:213], v192 offset:2048
	ds_read_b128 v[214:217], v192 offset:3072
	s_add_u32 s70, s54, 0xffd50080
	s_addc_u32 s71, s55, -1
	s_cmpk_eq_i32 s91, 0x98
	s_cselect_b32 s73, s9, s71
	s_cselect_b32 s72, s8, s70
	s_cselect_b32 s71, s69, s75
	s_cselect_b32 s70, s68, s74
	s_mov_b32 m0, s36
	v_lshl_add_u64 v[148:149], s[54:55], 0, v[170:171]
	ds_read_b128 v[138:141], v193
	ds_read_b128 v[142:145], v193 offset:1024
	ds_read_b128 v[218:221], v193 offset:2048
	ds_read_b128 v[222:225], v193 offset:3072
	ds_read_b128 v[226:229], v193 offset:4096
	ds_read_b128 v[230:233], v193 offset:5120
	ds_read_b128 v[234:237], v193 offset:6144
	ds_read_b128 v[238:241], v193 offset:7168
	global_load_lds_dwordx4 v[148:149], off
	v_lshl_add_u64 v[148:149], s[54:55], 0, v[168:169]
	s_mov_b32 m0, s37
	s_nop 0
	global_load_lds_dwordx4 v[148:149], off
	s_waitcnt vmcnt(8)
	s_waitcnt lgkmcnt(0)
	s_barrier
	s_setprio 1
	s_waitcnt lgkmcnt(0)
	v_mfma_scale_f32_16x16x128_f8f6f4 v[134:137], v[2:9], v[138:145], v[134:137], v194, v194 op_sel_hi:[0,0,0]
	v_mfma_scale_f32_16x16x128_f8f6f4 v[130:133], v[180:187], v[138:145], v[130:133], v194, v194 op_sel_hi:[0,0,0]
	v_mfma_scale_f32_16x16x128_f8f6f4 v[118:121], v[2:9], v[218:225], v[118:121], v194, v194 op_sel_hi:[0,0,0]
	v_mfma_scale_f32_16x16x128_f8f6f4 v[114:117], v[180:187], v[218:225], v[114:117], v194, v194 op_sel_hi:[0,0,0]
	v_mfma_scale_f32_16x16x128_f8f6f4 v[102:105], v[2:9], v[226:233], v[102:105], v194, v194 op_sel_hi:[0,0,0]
	v_mfma_scale_f32_16x16x128_f8f6f4 v[98:101], v[180:187], v[226:233], v[98:101], v194, v194 op_sel_hi:[0,0,0]
	v_mfma_scale_f32_16x16x128_f8f6f4 v[86:89], v[2:9], v[234:241], v[86:89], v194, v194 op_sel_hi:[0,0,0]
	v_mfma_scale_f32_16x16x128_f8f6f4 v[82:85], v[180:187], v[234:241], v[82:85], v194, v194 op_sel_hi:[0,0,0]
	s_setprio 0
	s_setprio 1
	v_mfma_scale_f32_16x16x128_f8f6f4 v[126:129], v[202:209], v[138:145], v[126:129], v194, v194 op_sel_hi:[0,0,0]
	v_mfma_scale_f32_16x16x128_f8f6f4 v[122:125], v[210:217], v[138:145], v[122:125], v194, v194 op_sel_hi:[0,0,0]
	v_mfma_scale_f32_16x16x128_f8f6f4 v[110:113], v[202:209], v[218:225], v[110:113], v194, v194 op_sel_hi:[0,0,0]
	v_mfma_scale_f32_16x16x128_f8f6f4 v[106:109], v[210:217], v[218:225], v[106:109], v194, v194 op_sel_hi:[0,0,0]
	v_mfma_scale_f32_16x16x128_f8f6f4 v[94:97], v[202:209], v[226:233], v[94:97], v194, v194 op_sel_hi:[0,0,0]
	v_mfma_scale_f32_16x16x128_f8f6f4 v[90:93], v[210:217], v[226:233], v[90:93], v194, v194 op_sel_hi:[0,0,0]
	v_mfma_scale_f32_16x16x128_f8f6f4 v[78:81], v[202:209], v[234:241], v[78:81], v194, v194 op_sel_hi:[0,0,0]
	v_mfma_scale_f32_16x16x128_f8f6f4 v[74:77], v[210:217], v[234:241], v[74:77], v194, v194 op_sel_hi:[0,0,0]
	s_setprio 0
	s_barrier
	s_mov_b32 m0, s83
	v_lshl_add_u64 v[138:139], s[70:71], 0, v[156:157]
	s_add_u32 s92, s70, 0x2b0000
	ds_read_b128 v[218:221], v193 offset:16384
	ds_read_b128 v[222:225], v193 offset:17408
	ds_read_b128 v[226:229], v193 offset:18432
	ds_read_b128 v[230:233], v193 offset:19456
	ds_read_b128 v[234:237], v193 offset:20480
	ds_read_b128 v[238:241], v193 offset:21504
	ds_read_b128 v[242:245], v193 offset:22528
	ds_read_b128 v[246:249], v193 offset:23552
	global_load_lds_dwordx4 v[138:139], off
	v_lshl_add_u64 v[140:141], s[70:71], 0, v[160:161]
	s_mov_b32 m0, s84
	s_addc_u32 s93, s71, 0
	global_load_lds_dwordx4 v[140:141], off
	v_lshl_add_u64 v[142:143], s[92:93], 0, v[156:157]
	s_mov_b32 m0, s85
	v_lshl_add_u64 v[144:145], s[72:73], 0, v[158:159]
	global_load_lds_dwordx4 v[142:143], off
	v_lshl_add_u64 v[142:143], s[92:93], 0, v[160:161]
	s_mov_b32 m0, s86
	s_nop 0
	global_load_lds_dwordx4 v[142:143], off
	v_lshl_add_u64 v[142:143], s[72:73], 0, v[154:155]
	s_mov_b32 m0, s38
	s_nop 0
	global_load_lds_dwordx4 v[142:143], off
	s_mov_b32 m0, s39
	s_nop 0
	global_load_lds_dwordx4 v[144:145], off
	s_waitcnt vmcnt(8)
	s_waitcnt lgkmcnt(0)
	s_barrier
	s_setprio 1
	s_waitcnt lgkmcnt(0)
	v_mfma_scale_f32_16x16x128_f8f6f4 v[70:73], v[2:9], v[218:225], v[70:73], v194, v194 op_sel_hi:[0,0,0]
	v_mfma_scale_f32_16x16x128_f8f6f4 v[66:69], v[180:187], v[218:225], v[66:69], v194, v194 op_sel_hi:[0,0,0]
	v_mfma_scale_f32_16x16x128_f8f6f4 v[54:57], v[2:9], v[226:233], v[54:57], v194, v194 op_sel_hi:[0,0,0]
	v_mfma_scale_f32_16x16x128_f8f6f4 v[50:53], v[180:187], v[226:233], v[50:53], v194, v194 op_sel_hi:[0,0,0]
	v_mfma_scale_f32_16x16x128_f8f6f4 v[38:41], v[2:9], v[234:241], v[38:41], v194, v194 op_sel_hi:[0,0,0]
	v_mfma_scale_f32_16x16x128_f8f6f4 v[34:37], v[180:187], v[234:241], v[34:37], v194, v194 op_sel_hi:[0,0,0]
	v_mfma_scale_f32_16x16x128_f8f6f4 v[22:25], v[2:9], v[242:249], v[22:25], v194, v194 op_sel_hi:[0,0,0]
	v_mfma_scale_f32_16x16x128_f8f6f4 v[18:21], v[180:187], v[242:249], v[18:21], v194, v194 op_sel_hi:[0,0,0]
	s_setprio 0
	s_setprio 1
	v_mfma_scale_f32_16x16x128_f8f6f4 v[62:65], v[202:209], v[218:225], v[62:65], v194, v194 op_sel_hi:[0,0,0]
	v_mfma_scale_f32_16x16x128_f8f6f4 v[58:61], v[210:217], v[218:225], v[58:61], v194, v194 op_sel_hi:[0,0,0]
	v_mfma_scale_f32_16x16x128_f8f6f4 v[46:49], v[202:209], v[226:233], v[46:49], v194, v194 op_sel_hi:[0,0,0]
	v_mfma_scale_f32_16x16x128_f8f6f4 v[42:45], v[210:217], v[226:233], v[42:45], v194, v194 op_sel_hi:[0,0,0]
	v_mfma_scale_f32_16x16x128_f8f6f4 v[30:33], v[202:209], v[234:241], v[30:33], v194, v194 op_sel_hi:[0,0,0]
	v_mfma_scale_f32_16x16x128_f8f6f4 v[26:29], v[210:217], v[234:241], v[26:29], v194, v194 op_sel_hi:[0,0,0]
	v_mfma_scale_f32_16x16x128_f8f6f4 v[14:17], v[202:209], v[242:249], v[14:17], v194, v194 op_sel_hi:[0,0,0]
	v_mfma_scale_f32_16x16x128_f8f6f4 v[10:13], v[210:217], v[242:249], v[10:13], v194, v194 op_sel_hi:[0,0,0]
	s_setprio 0
	s_barrier
	ds_read_b128 v[180:183], v146
	ds_read_b128 v[184:187], v146 offset:1024
	ds_read_b128 v[202:205], v146 offset:2048
	ds_read_b128 v[206:209], v146 offset:3072
	ds_read_b128 v[2:5], v147
	ds_read_b128 v[6:9], v147 offset:1024
	ds_read_b128 v[210:213], v147 offset:2048
	ds_read_b128 v[214:217], v147 offset:3072
	s_add_u32 s72, s72, 0x2b0000
	s_addc_u32 s73, s73, 0
	s_mov_b32 m0, s52
	v_lshl_add_u64 v[148:149], s[72:73], 0, v[154:155]
	ds_read_b128 v[218:221], v193 offset:32768
	ds_read_b128 v[222:225], v193 offset:33792
	ds_read_b128 v[226:229], v193 offset:34816
	ds_read_b128 v[230:233], v193 offset:35840
	ds_read_b128 v[234:237], v193 offset:36864
	ds_read_b128 v[238:241], v193 offset:37888
	ds_read_b128 v[242:245], v193 offset:38912
	ds_read_b128 v[246:249], v193 offset:39936
	global_load_lds_dwordx4 v[148:149], off
	v_lshl_add_u64 v[148:149], s[72:73], 0, v[158:159]
	s_mov_b32 m0, s53
	s_nop 0
	global_load_lds_dwordx4 v[148:149], off
	s_waitcnt vmcnt(8)
	s_waitcnt lgkmcnt(0)
	s_barrier
	s_setprio 1
	s_waitcnt lgkmcnt(0)
	v_mfma_scale_f32_16x16x128_f8f6f4 v[134:137], v[180:187], v[218:225], v[134:137], v194, v194 op_sel_hi:[0,0,0]
	v_mfma_scale_f32_16x16x128_f8f6f4 v[130:133], v[202:209], v[218:225], v[130:133], v194, v194 op_sel_hi:[0,0,0]
	v_mfma_scale_f32_16x16x128_f8f6f4 v[118:121], v[180:187], v[226:233], v[118:121], v194, v194 op_sel_hi:[0,0,0]
	v_mfma_scale_f32_16x16x128_f8f6f4 v[114:117], v[202:209], v[226:233], v[114:117], v194, v194 op_sel_hi:[0,0,0]
	v_mfma_scale_f32_16x16x128_f8f6f4 v[102:105], v[180:187], v[234:241], v[102:105], v194, v194 op_sel_hi:[0,0,0]
	v_mfma_scale_f32_16x16x128_f8f6f4 v[98:101], v[202:209], v[234:241], v[98:101], v194, v194 op_sel_hi:[0,0,0]
	v_mfma_scale_f32_16x16x128_f8f6f4 v[86:89], v[180:187], v[242:249], v[86:89], v194, v194 op_sel_hi:[0,0,0]
	v_mfma_scale_f32_16x16x128_f8f6f4 v[82:85], v[202:209], v[242:249], v[82:85], v194, v194 op_sel_hi:[0,0,0]
	s_setprio 0
	s_setprio 1
	v_mfma_scale_f32_16x16x128_f8f6f4 v[126:129], v[2:9], v[218:225], v[126:129], v194, v194 op_sel_hi:[0,0,0]
	v_mfma_scale_f32_16x16x128_f8f6f4 v[122:125], v[210:217], v[218:225], v[122:125], v194, v194 op_sel_hi:[0,0,0]
	v_mfma_scale_f32_16x16x128_f8f6f4 v[110:113], v[2:9], v[226:233], v[110:113], v194, v194 op_sel_hi:[0,0,0]
	v_mfma_scale_f32_16x16x128_f8f6f4 v[106:109], v[210:217], v[226:233], v[106:109], v194, v194 op_sel_hi:[0,0,0]
	v_mfma_scale_f32_16x16x128_f8f6f4 v[94:97], v[2:9], v[234:241], v[94:97], v194, v194 op_sel_hi:[0,0,0]
	v_mfma_scale_f32_16x16x128_f8f6f4 v[90:93], v[210:217], v[234:241], v[90:93], v194, v194 op_sel_hi:[0,0,0]
	v_mfma_scale_f32_16x16x128_f8f6f4 v[78:81], v[2:9], v[242:249], v[78:81], v194, v194 op_sel_hi:[0,0,0]
	v_mfma_scale_f32_16x16x128_f8f6f4 v[74:77], v[210:217], v[242:249], v[74:77], v194, v194 op_sel_hi:[0,0,0]
	s_setprio 0
	s_barrier
	s_mov_b32 m0, s87
	v_lshl_add_u64 v[138:139], v[138:139], 0, s[24:25]
	s_add_u32 s70, s70, 0x2b0080
	ds_read_b128 v[218:221], v193 offset:49152
	ds_read_b128 v[222:225], v193 offset:50176
	ds_read_b128 v[226:229], v193 offset:51200
	ds_read_b128 v[230:233], v193 offset:52224
	ds_read_b128 v[234:237], v193 offset:53248
	ds_read_b128 v[238:241], v193 offset:54272
	ds_read_b128 v[242:245], v193 offset:55296
	ds_read_b128 v[246:249], v193 offset:56320
	global_load_lds_dwordx4 v[138:139], off
	v_lshl_add_u64 v[138:139], v[140:141], 0, s[24:25]
	s_mov_b32 m0, s88
	s_addc_u32 s71, s71, 0
	global_load_lds_dwordx4 v[138:139], off
	v_lshl_add_u64 v[138:139], s[70:71], 0, v[156:157]
	s_mov_b32 m0, s89
	s_nop 0
	global_load_lds_dwordx4 v[138:139], off
	v_lshl_add_u64 v[138:139], s[70:71], 0, v[160:161]
	s_mov_b32 m0, s90
	s_nop 0
	global_load_lds_dwordx4 v[138:139], off
	v_lshl_add_u64 v[138:139], v[142:143], 0, s[24:25]
	s_mov_b32 m0, s57
	s_nop 0
	global_load_lds_dwordx4 v[138:139], off
	v_lshl_add_u64 v[138:139], v[144:145], 0, s[24:25]
	s_mov_b32 m0, s67
	s_nop 0
	global_load_lds_dwordx4 v[138:139], off
	s_waitcnt vmcnt(8)
	s_waitcnt lgkmcnt(0)
	s_barrier
	s_setprio 1
	s_waitcnt lgkmcnt(0)
	v_mfma_scale_f32_16x16x128_f8f6f4 v[70:73], v[180:187], v[218:225], v[70:73], v194, v194 op_sel_hi:[0,0,0]
	v_mfma_scale_f32_16x16x128_f8f6f4 v[66:69], v[202:209], v[218:225], v[66:69], v194, v194 op_sel_hi:[0,0,0]
	v_mfma_scale_f32_16x16x128_f8f6f4 v[54:57], v[180:187], v[226:233], v[54:57], v194, v194 op_sel_hi:[0,0,0]
	v_mfma_scale_f32_16x16x128_f8f6f4 v[50:53], v[202:209], v[226:233], v[50:53], v194, v194 op_sel_hi:[0,0,0]
	v_mfma_scale_f32_16x16x128_f8f6f4 v[38:41], v[180:187], v[234:241], v[38:41], v194, v194 op_sel_hi:[0,0,0]
	v_mfma_scale_f32_16x16x128_f8f6f4 v[34:37], v[202:209], v[234:241], v[34:37], v194, v194 op_sel_hi:[0,0,0]
	v_mfma_scale_f32_16x16x128_f8f6f4 v[22:25], v[180:187], v[242:249], v[22:25], v194, v194 op_sel_hi:[0,0,0]
	v_mfma_scale_f32_16x16x128_f8f6f4 v[18:21], v[202:209], v[242:249], v[18:21], v194, v194 op_sel_hi:[0,0,0]
	s_setprio 0
	s_setprio 1
	v_mfma_scale_f32_16x16x128_f8f6f4 v[62:65], v[2:9], v[218:225], v[62:65], v194, v194 op_sel_hi:[0,0,0]
	v_mfma_scale_f32_16x16x128_f8f6f4 v[58:61], v[210:217], v[218:225], v[58:61], v194, v194 op_sel_hi:[0,0,0]
	v_mfma_scale_f32_16x16x128_f8f6f4 v[46:49], v[2:9], v[226:233], v[46:49], v194, v194 op_sel_hi:[0,0,0]
	v_mfma_scale_f32_16x16x128_f8f6f4 v[42:45], v[210:217], v[226:233], v[42:45], v194, v194 op_sel_hi:[0,0,0]
	v_mfma_scale_f32_16x16x128_f8f6f4 v[30:33], v[2:9], v[234:241], v[30:33], v194, v194 op_sel_hi:[0,0,0]
	v_mfma_scale_f32_16x16x128_f8f6f4 v[26:29], v[210:217], v[234:241], v[26:29], v194, v194 op_sel_hi:[0,0,0]
	v_mfma_scale_f32_16x16x128_f8f6f4 v[14:17], v[2:9], v[242:249], v[14:17], v194, v194 op_sel_hi:[0,0,0]
	v_mfma_scale_f32_16x16x128_f8f6f4 v[10:13], v[210:217], v[242:249], v[10:13], v194, v194 op_sel_hi:[0,0,0]
	s_setprio 0
	s_barrier
	s_add_i32 s91, s91, 2
	s_add_u32 s54, s54, 0x100
	s_addc_u32 s55, s55, 0
	s_add_u32 s74, s74, 0x100
	s_addc_u32 s75, s75, 0
	s_cmpk_gt_u32 s91, 0x99
	s_cbranch_scc0 .LBB0_379
	s_and_b64 vcc, exec, s[50:51]
	s_cbranch_vccz .LBB0_382
	s_barrier

.LBB0_484:
	ds_read_b128 v[18:21], v172
	ds_read_b128 v[22:25], v172 offset:1024
	ds_read_b128 v[26:29], v172 offset:2048
	ds_read_b128 v[30:33], v172 offset:3072
	ds_read_b128 v[180:183], v173
	ds_read_b128 v[184:187], v173 offset:1024
	ds_read_b128 v[188:191], v173 offset:2048
	ds_read_b128 v[192:195], v173 offset:3072
	s_add_u32 s14, s10, 0xfff00080
	s_addc_u32 s15, s11, -1
	s_cmp_eq_u32 s36, 60
	s_cselect_b32 s23, s2, s15
	s_cselect_b32 s22, s9, s14
	s_cselect_b32 s15, s24, s31
	s_cselect_b32 s14, s25, s30
	v_lshl_add_u64 v[230:231], s[10:11], 0, v[154:155]
	s_add_i32 m0, s73, 0xc000
	ds_read_b128 v[196:199], v174
	ds_read_b128 v[202:205], v174 offset:1024
	ds_read_b128 v[206:209], v174 offset:2048
	ds_read_b128 v[210:213], v174 offset:3072
	ds_read_b128 v[214:217], v174 offset:4096
	ds_read_b128 v[218:221], v174 offset:5120
	ds_read_b128 v[222:225], v174 offset:6144
	ds_read_b128 v[226:229], v174 offset:7168
	global_load_lds_dwordx4 v[230:231], off
	v_lshl_add_u64 v[230:231], s[10:11], 0, v[156:157]
	s_add_i32 m0, s73, 0xe000
	s_nop 0
	global_load_lds_dwordx4 v[230:231], off
	s_waitcnt vmcnt(8)
	s_waitcnt lgkmcnt(0)
	s_barrier
	s_setprio 1
	s_waitcnt lgkmcnt(0)
	v_mfma_f32_16x16x32_bf16 v[142:145], v[18:21], v[196:199], v[142:145]
	v_mfma_f32_16x16x32_bf16 v[138:141], v[26:29], v[196:199], v[138:141]
	v_mfma_f32_16x16x32_bf16 v[126:129], v[18:21], v[206:209], v[126:129]
	v_mfma_f32_16x16x32_bf16 v[122:125], v[26:29], v[206:209], v[122:125]
	v_mfma_f32_16x16x32_bf16 v[110:113], v[18:21], v[214:217], v[110:113]
	v_mfma_f32_16x16x32_bf16 v[106:109], v[26:29], v[214:217], v[106:109]
	v_mfma_f32_16x16x32_bf16 v[94:97], v[18:21], v[222:225], v[94:97]
	v_mfma_f32_16x16x32_bf16 v[90:93], v[26:29], v[222:225], v[90:93]
	v_mfma_f32_16x16x32_bf16 v[142:145], v[22:25], v[202:205], v[142:145]
	v_mfma_f32_16x16x32_bf16 v[138:141], v[30:33], v[202:205], v[138:141]
	v_mfma_f32_16x16x32_bf16 v[126:129], v[22:25], v[210:213], v[126:129]
	v_mfma_f32_16x16x32_bf16 v[122:125], v[30:33], v[210:213], v[122:125]
	v_mfma_f32_16x16x32_bf16 v[110:113], v[22:25], v[218:221], v[110:113]
	v_mfma_f32_16x16x32_bf16 v[106:109], v[30:33], v[218:221], v[106:109]
	v_mfma_f32_16x16x32_bf16 v[94:97], v[22:25], v[226:229], v[94:97]
	v_mfma_f32_16x16x32_bf16 v[90:93], v[30:33], v[226:229], v[90:93]
	s_setprio 0
	s_setprio 1
	v_mfma_f32_16x16x32_bf16 v[134:137], v[180:183], v[196:199], v[134:137]
	v_mfma_f32_16x16x32_bf16 v[130:133], v[188:191], v[196:199], v[130:133]
	v_mfma_f32_16x16x32_bf16 v[118:121], v[180:183], v[206:209], v[118:121]
	v_mfma_f32_16x16x32_bf16 v[114:117], v[188:191], v[206:209], v[114:117]
	v_mfma_f32_16x16x32_bf16 v[102:105], v[180:183], v[214:217], v[102:105]
	v_mfma_f32_16x16x32_bf16 v[98:101], v[188:191], v[214:217], v[98:101]
	v_mfma_f32_16x16x32_bf16 v[86:89], v[180:183], v[222:225], v[86:89]
	v_mfma_f32_16x16x32_bf16 v[82:85], v[188:191], v[222:225], v[82:85]
	v_mfma_f32_16x16x32_bf16 v[134:137], v[184:187], v[202:205], v[134:137]
	v_mfma_f32_16x16x32_bf16 v[130:133], v[192:195], v[202:205], v[130:133]
	v_mfma_f32_16x16x32_bf16 v[118:121], v[184:187], v[210:213], v[118:121]
	v_mfma_f32_16x16x32_bf16 v[114:117], v[192:195], v[210:213], v[114:117]
	v_mfma_f32_16x16x32_bf16 v[102:105], v[184:187], v[218:221], v[102:105]
	v_mfma_f32_16x16x32_bf16 v[98:101], v[192:195], v[218:221], v[98:101]
	v_mfma_f32_16x16x32_bf16 v[86:89], v[184:187], v[226:229], v[86:89]
	v_mfma_f32_16x16x32_bf16 v[82:85], v[192:195], v[226:229], v[82:85]
	s_setprio 0
	s_barrier
	s_add_i32 s37, s74, s39
	v_lshl_add_u64 v[230:231], s[14:15], 0, v[148:149]
	s_mov_b32 m0, s37
	ds_read_b128 v[196:199], v174 offset:16384
	ds_read_b128 v[202:205], v174 offset:17408
	ds_read_b128 v[206:209], v174 offset:18432
	ds_read_b128 v[210:213], v174 offset:19456
	ds_read_b128 v[214:217], v174 offset:20480
	ds_read_b128 v[218:221], v174 offset:21504
	ds_read_b128 v[222:225], v174 offset:22528
	ds_read_b128 v[226:229], v174 offset:23552
	global_load_lds_dwordx4 v[230:231], off
	s_add_i32 m0, s37, 0x2000
	s_add_u32 s54, s14, 0x100000
	v_lshl_add_u64 v[232:233], s[14:15], 0, v[152:153]
	s_addc_u32 s55, s15, 0
	s_add_i32 s37, s75, s39
	global_load_lds_dwordx4 v[232:233], off
	v_lshl_add_u64 v[234:235], s[54:55], 0, v[148:149]
	s_mov_b32 m0, s37
	v_lshl_add_u64 v[236:237], s[22:23], 0, v[150:151]
	global_load_lds_dwordx4 v[234:235], off
	v_lshl_add_u64 v[234:235], s[54:55], 0, v[152:153]
	s_add_i32 m0, s37, 0x2000
	s_nop 0
	global_load_lds_dwordx4 v[234:235], off
	v_lshl_add_u64 v[234:235], s[22:23], 0, v[146:147]
	s_mov_b32 m0, s73
	s_nop 0
	global_load_lds_dwordx4 v[234:235], off
	s_mov_b32 m0, s52
	s_nop 0
	global_load_lds_dwordx4 v[236:237], off
	s_waitcnt vmcnt(8)
	s_waitcnt lgkmcnt(0)
	s_barrier
	s_setprio 1
	s_waitcnt lgkmcnt(0)
	v_mfma_f32_16x16x32_bf16 v[78:81], v[18:21], v[196:199], v[78:81]
	v_mfma_f32_16x16x32_bf16 v[74:77], v[26:29], v[196:199], v[74:77]
	v_mfma_f32_16x16x32_bf16 v[62:65], v[18:21], v[206:209], v[62:65]
	v_mfma_f32_16x16x32_bf16 v[58:61], v[26:29], v[206:209], v[58:61]
	v_mfma_f32_16x16x32_bf16 v[46:49], v[18:21], v[214:217], v[46:49]
	v_mfma_f32_16x16x32_bf16 v[42:45], v[26:29], v[214:217], v[42:45]
	v_mfma_f32_16x16x32_bf16 v[14:17], v[18:21], v[222:225], v[14:17]
	v_mfma_f32_16x16x32_bf16 v[10:13], v[26:29], v[222:225], v[10:13]
	v_mfma_f32_16x16x32_bf16 v[78:81], v[22:25], v[202:205], v[78:81]
	v_mfma_f32_16x16x32_bf16 v[74:77], v[30:33], v[202:205], v[74:77]
	v_mfma_f32_16x16x32_bf16 v[62:65], v[22:25], v[210:213], v[62:65]
	v_mfma_f32_16x16x32_bf16 v[58:61], v[30:33], v[210:213], v[58:61]
	v_mfma_f32_16x16x32_bf16 v[46:49], v[22:25], v[218:221], v[46:49]
	v_mfma_f32_16x16x32_bf16 v[42:45], v[30:33], v[218:221], v[42:45]
	v_mfma_f32_16x16x32_bf16 v[14:17], v[22:25], v[226:229], v[14:17]
	v_mfma_f32_16x16x32_bf16 v[10:13], v[30:33], v[226:229], v[10:13]
	s_setprio 0
	s_setprio 1
	v_mfma_f32_16x16x32_bf16 v[38:41], v[180:183], v[214:217], v[38:41]
	v_mfma_f32_16x16x32_bf16 v[34:37], v[188:191], v[214:217], v[34:37]
	v_mfma_f32_16x16x32_bf16 v[6:9], v[180:183], v[222:225], v[6:9]
	v_mfma_f32_16x16x32_bf16 v[2:5], v[188:191], v[222:225], v[2:5]
	v_mfma_f32_16x16x32_bf16 v[18:21], v[180:183], v[196:199], v[70:73]
	v_mfma_f32_16x16x32_bf16 v[22:25], v[188:191], v[196:199], v[66:69]
	v_mfma_f32_16x16x32_bf16 v[26:29], v[180:183], v[206:209], v[54:57]
	v_mfma_f32_16x16x32_bf16 v[30:33], v[188:191], v[206:209], v[50:53]
	v_mfma_f32_16x16x32_bf16 v[38:41], v[184:187], v[218:221], v[38:41]
	v_mfma_f32_16x16x32_bf16 v[34:37], v[192:195], v[218:221], v[34:37]
	v_mfma_f32_16x16x32_bf16 v[6:9], v[184:187], v[226:229], v[6:9]
	v_mfma_f32_16x16x32_bf16 v[2:5], v[192:195], v[226:229], v[2:5]
	v_mfma_f32_16x16x32_bf16 v[18:21], v[184:187], v[202:205], v[18:21]
	v_mfma_f32_16x16x32_bf16 v[22:25], v[192:195], v[202:205], v[22:25]
	v_mfma_f32_16x16x32_bf16 v[26:29], v[184:187], v[210:213], v[26:29]
	v_mfma_f32_16x16x32_bf16 v[30:33], v[192:195], v[210:213], v[30:33]
	s_setprio 0
	s_barrier
	s_add_i32 s37, 0, 0x18000
	s_add_i32 s54, 0, 0x1c000
	v_add_u32_e32 v70, s37, v166
	v_add_u32_e32 v179, s54, v166
	ds_read_b128 v[50:53], v70
	ds_read_b128 v[54:57], v70 offset:1024
	ds_read_b128 v[66:69], v70 offset:2048
	ds_read_b128 v[70:73], v70 offset:3072
	ds_read_b128 v[180:183], v179
	ds_read_b128 v[184:187], v179 offset:1024
	ds_read_b128 v[188:191], v179 offset:2048
	ds_read_b128 v[192:195], v179 offset:3072
	s_add_u32 s22, s22, 0x100000
	s_addc_u32 s23, s23, 0
	s_mov_b32 m0, s53
	v_lshl_add_u64 v[238:239], s[22:23], 0, v[146:147]
	ds_read_b128 v[196:199], v174 offset:32768
	ds_read_b128 v[202:205], v174 offset:33792
	ds_read_b128 v[206:209], v174 offset:34816
	ds_read_b128 v[210:213], v174 offset:35840
	ds_read_b128 v[214:217], v174 offset:36864
	ds_read_b128 v[218:221], v174 offset:37888
	ds_read_b128 v[222:225], v174 offset:38912
	ds_read_b128 v[226:229], v174 offset:39936
	global_load_lds_dwordx4 v[238:239], off
	v_lshl_add_u64 v[238:239], s[22:23], 0, v[150:151]
	s_mov_b32 m0, s20
	s_nop 0
	global_load_lds_dwordx4 v[238:239], off
	s_waitcnt vmcnt(8)
	s_waitcnt lgkmcnt(0)
	s_barrier
	s_setprio 1
	s_waitcnt lgkmcnt(0)
	v_mfma_f32_16x16x32_bf16 v[142:145], v[50:53], v[196:199], v[142:145]
	v_mfma_f32_16x16x32_bf16 v[138:141], v[66:69], v[196:199], v[138:141]
	v_mfma_f32_16x16x32_bf16 v[126:129], v[50:53], v[206:209], v[126:129]
	v_mfma_f32_16x16x32_bf16 v[122:125], v[66:69], v[206:209], v[122:125]
	v_mfma_f32_16x16x32_bf16 v[110:113], v[50:53], v[214:217], v[110:113]
	v_mfma_f32_16x16x32_bf16 v[106:109], v[66:69], v[214:217], v[106:109]
	v_mfma_f32_16x16x32_bf16 v[94:97], v[50:53], v[222:225], v[94:97]
	v_mfma_f32_16x16x32_bf16 v[90:93], v[66:69], v[222:225], v[90:93]
	v_mfma_f32_16x16x32_bf16 v[142:145], v[54:57], v[202:205], v[142:145]
	v_mfma_f32_16x16x32_bf16 v[138:141], v[70:73], v[202:205], v[138:141]
	v_mfma_f32_16x16x32_bf16 v[126:129], v[54:57], v[210:213], v[126:129]
	v_mfma_f32_16x16x32_bf16 v[122:125], v[70:73], v[210:213], v[122:125]
	v_mfma_f32_16x16x32_bf16 v[110:113], v[54:57], v[218:221], v[110:113]
	v_mfma_f32_16x16x32_bf16 v[106:109], v[70:73], v[218:221], v[106:109]
	v_mfma_f32_16x16x32_bf16 v[94:97], v[54:57], v[226:229], v[94:97]
	v_mfma_f32_16x16x32_bf16 v[90:93], v[70:73], v[226:229], v[90:93]
	s_setprio 0
	s_setprio 1
	v_mfma_f32_16x16x32_bf16 v[134:137], v[180:183], v[196:199], v[134:137]
	v_mfma_f32_16x16x32_bf16 v[130:133], v[188:191], v[196:199], v[130:133]
	v_mfma_f32_16x16x32_bf16 v[118:121], v[180:183], v[206:209], v[118:121]
	v_mfma_f32_16x16x32_bf16 v[114:117], v[188:191], v[206:209], v[114:117]
	v_mfma_f32_16x16x32_bf16 v[102:105], v[180:183], v[214:217], v[102:105]
	v_mfma_f32_16x16x32_bf16 v[98:101], v[188:191], v[214:217], v[98:101]
	v_mfma_f32_16x16x32_bf16 v[86:89], v[180:183], v[222:225], v[86:89]
	v_mfma_f32_16x16x32_bf16 v[82:85], v[188:191], v[222:225], v[82:85]
	v_mfma_f32_16x16x32_bf16 v[134:137], v[184:187], v[202:205], v[134:137]
	v_mfma_f32_16x16x32_bf16 v[130:133], v[192:195], v[202:205], v[130:133]
	v_mfma_f32_16x16x32_bf16 v[118:121], v[184:187], v[210:213], v[118:121]
	v_mfma_f32_16x16x32_bf16 v[114:117], v[192:195], v[210:213], v[114:117]
	v_mfma_f32_16x16x32_bf16 v[102:105], v[184:187], v[218:221], v[102:105]
	v_mfma_f32_16x16x32_bf16 v[98:101], v[192:195], v[218:221], v[98:101]
	v_mfma_f32_16x16x32_bf16 v[86:89], v[184:187], v[226:229], v[86:89]
	v_mfma_f32_16x16x32_bf16 v[82:85], v[192:195], v[226:229], v[82:85]
	s_setprio 0
	s_barrier
	s_add_i32 s22, s37, s39
	v_lshl_add_u64 v[230:231], v[230:231], 0, s[82:83]
	s_mov_b32 m0, s22
	ds_read_b128 v[196:199], v174 offset:49152
	ds_read_b128 v[202:205], v174 offset:50176
	ds_read_b128 v[206:209], v174 offset:51200
	ds_read_b128 v[210:213], v174 offset:52224
	ds_read_b128 v[214:217], v174 offset:53248
	ds_read_b128 v[218:221], v174 offset:54272
	ds_read_b128 v[222:225], v174 offset:55296
	ds_read_b128 v[226:229], v174 offset:56320
	global_load_lds_dwordx4 v[230:231], off
	s_add_i32 m0, s22, 0x2000
	s_add_u32 s14, s14, 0x100080
	v_lshl_add_u64 v[230:231], v[232:233], 0, s[82:83]
	s_addc_u32 s15, s15, 0
	s_add_i32 s22, s54, s39
	global_load_lds_dwordx4 v[230:231], off
	v_lshl_add_u64 v[230:231], s[14:15], 0, v[148:149]
	s_mov_b32 m0, s22
	s_nop 0
	global_load_lds_dwordx4 v[230:231], off
	v_lshl_add_u64 v[230:231], s[14:15], 0, v[152:153]
	s_add_i32 m0, s22, 0x2000
	s_nop 0
	global_load_lds_dwordx4 v[230:231], off
	v_lshl_add_u64 v[230:231], v[234:235], 0, s[82:83]
	s_mov_b32 m0, s67
	s_nop 0
	global_load_lds_dwordx4 v[230:231], off
	v_lshl_add_u64 v[230:231], v[236:237], 0, s[82:83]
	s_mov_b32 m0, s26
	s_nop 0
	global_load_lds_dwordx4 v[230:231], off
	s_waitcnt vmcnt(8)
	s_waitcnt lgkmcnt(0)
	s_barrier
	s_setprio 1
	s_waitcnt lgkmcnt(0)
	v_mfma_f32_16x16x32_bf16 v[78:81], v[50:53], v[196:199], v[78:81]
	v_mfma_f32_16x16x32_bf16 v[74:77], v[66:69], v[196:199], v[74:77]
	v_mfma_f32_16x16x32_bf16 v[62:65], v[50:53], v[206:209], v[62:65]
	v_mfma_f32_16x16x32_bf16 v[58:61], v[66:69], v[206:209], v[58:61]
	v_mfma_f32_16x16x32_bf16 v[46:49], v[50:53], v[214:217], v[46:49]
	v_mfma_f32_16x16x32_bf16 v[42:45], v[66:69], v[214:217], v[42:45]
	v_mfma_f32_16x16x32_bf16 v[14:17], v[50:53], v[222:225], v[14:17]
	v_mfma_f32_16x16x32_bf16 v[10:13], v[66:69], v[222:225], v[10:13]
	v_mfma_f32_16x16x32_bf16 v[78:81], v[54:57], v[202:205], v[78:81]
	v_mfma_f32_16x16x32_bf16 v[74:77], v[70:73], v[202:205], v[74:77]
	v_mfma_f32_16x16x32_bf16 v[62:65], v[54:57], v[210:213], v[62:65]
	v_mfma_f32_16x16x32_bf16 v[58:61], v[70:73], v[210:213], v[58:61]
	v_mfma_f32_16x16x32_bf16 v[46:49], v[54:57], v[218:221], v[46:49]
	v_mfma_f32_16x16x32_bf16 v[42:45], v[70:73], v[218:221], v[42:45]
	v_mfma_f32_16x16x32_bf16 v[14:17], v[54:57], v[226:229], v[14:17]
	v_mfma_f32_16x16x32_bf16 v[10:13], v[70:73], v[226:229], v[10:13]
	s_setprio 0
	s_setprio 1
	v_mfma_f32_16x16x32_bf16 v[18:21], v[180:183], v[196:199], v[18:21]
	v_mfma_f32_16x16x32_bf16 v[70:73], v[184:187], v[202:205], v[18:21]
	v_mfma_f32_16x16x32_bf16 v[18:21], v[188:191], v[196:199], v[22:25]
	v_mfma_f32_16x16x32_bf16 v[66:69], v[192:195], v[202:205], v[18:21]
	v_mfma_f32_16x16x32_bf16 v[18:21], v[180:183], v[206:209], v[26:29]
	v_mfma_f32_16x16x32_bf16 v[54:57], v[184:187], v[210:213], v[18:21]
	v_mfma_f32_16x16x32_bf16 v[18:21], v[188:191], v[206:209], v[30:33]
	v_mfma_f32_16x16x32_bf16 v[50:53], v[192:195], v[210:213], v[18:21]
	v_mfma_f32_16x16x32_bf16 v[18:21], v[180:183], v[214:217], v[38:41]
	v_mfma_f32_16x16x32_bf16 v[38:41], v[184:187], v[218:221], v[18:21]
	v_mfma_f32_16x16x32_bf16 v[18:21], v[188:191], v[214:217], v[34:37]
	v_mfma_f32_16x16x32_bf16 v[6:9], v[180:183], v[222:225], v[6:9]
	v_mfma_f32_16x16x32_bf16 v[2:5], v[188:191], v[222:225], v[2:5]
	v_mfma_f32_16x16x32_bf16 v[34:37], v[192:195], v[218:221], v[18:21]
	v_mfma_f32_16x16x32_bf16 v[6:9], v[184:187], v[226:229], v[6:9]
	v_mfma_f32_16x16x32_bf16 v[2:5], v[192:195], v[226:229], v[2:5]
	s_setprio 0
	s_barrier
	s_add_i32 s36, s36, 2
	s_add_u32 s10, s10, 0x100
	s_addc_u32 s11, s11, 0
	s_add_u32 s30, s30, 0x100
	s_addc_u32 s31, s31, 0
	s_cmp_gt_u32 s36, 61
	s_cbranch_scc0 .LBB0_484
	s_and_b64 vcc, exec, s[84:85]
	s_cbranch_vccz .LBB0_487
	s_barrier

.LBB0_830:
	ds_read_b128 v[170:173], v167
	ds_read_b128 v[174:177], v167 offset:1024
	ds_read_b128 v[178:181], v167 offset:2048
	ds_read_b128 v[182:185], v167 offset:3072
	ds_read_b128 v[186:189], v168
	ds_read_b128 v[190:193], v168 offset:1024
	ds_read_b128 v[194:197], v168 offset:2048
	ds_read_b128 v[202:205], v168 offset:3072
	s_add_u32 s54, s30, 0xfffc8080
	s_addc_u32 s55, s31, -1
	s_cmp_eq_u32 s75, 10
	s_cselect_b32 s67, s7, s55
	s_cselect_b32 s66, s6, s54
	s_cselect_b32 s55, s25, s74
	s_cselect_b32 s54, s24, s73
	v_lshl_add_u64 v[146:147], s[30:31], 0, v[138:139]
	s_add_i32 m0, s26, 0xc000
	ds_read_b128 v[206:209], v169
	ds_read_b128 v[210:213], v169 offset:1024
	ds_read_b128 v[214:217], v169 offset:2048
	ds_read_b128 v[218:221], v169 offset:3072
	ds_read_b128 v[222:225], v169 offset:4096
	ds_read_b128 v[226:229], v169 offset:5120
	ds_read_b128 v[230:233], v169 offset:6144
	ds_read_b128 v[234:237], v169 offset:7168
	global_load_lds_dwordx4 v[146:147], off
	v_lshl_add_u64 v[146:147], s[30:31], 0, v[140:141]
	s_add_i32 m0, s26, 0xe000
	s_nop 0
	global_load_lds_dwordx4 v[146:147], off
	s_waitcnt vmcnt(8)
	s_waitcnt lgkmcnt(0)
	s_barrier
	s_setprio 1
	s_waitcnt lgkmcnt(0)
	v_mfma_f32_16x16x32_bf16 v[126:129], v[170:173], v[206:209], v[126:129]
	v_mfma_f32_16x16x32_bf16 v[122:125], v[178:181], v[206:209], v[122:125]
	v_mfma_f32_16x16x32_bf16 v[110:113], v[170:173], v[214:217], v[110:113]
	v_mfma_f32_16x16x32_bf16 v[106:109], v[178:181], v[214:217], v[106:109]
	v_mfma_f32_16x16x32_bf16 v[102:105], v[170:173], v[222:225], v[102:105]
	v_mfma_f32_16x16x32_bf16 v[98:101], v[178:181], v[222:225], v[98:101]
	v_mfma_f32_16x16x32_bf16 v[86:89], v[170:173], v[230:233], v[86:89]
	v_mfma_f32_16x16x32_bf16 v[82:85], v[178:181], v[230:233], v[82:85]
	v_mfma_f32_16x16x32_bf16 v[126:129], v[174:177], v[210:213], v[126:129]
	v_mfma_f32_16x16x32_bf16 v[122:125], v[182:185], v[210:213], v[122:125]
	v_mfma_f32_16x16x32_bf16 v[110:113], v[174:177], v[218:221], v[110:113]
	v_mfma_f32_16x16x32_bf16 v[106:109], v[182:185], v[218:221], v[106:109]
	v_mfma_f32_16x16x32_bf16 v[102:105], v[174:177], v[226:229], v[102:105]
	v_mfma_f32_16x16x32_bf16 v[98:101], v[182:185], v[226:229], v[98:101]
	v_mfma_f32_16x16x32_bf16 v[86:89], v[174:177], v[234:237], v[86:89]
	v_mfma_f32_16x16x32_bf16 v[82:85], v[182:185], v[234:237], v[82:85]
	s_setprio 0
	s_setprio 1
	v_mfma_f32_16x16x32_bf16 v[118:121], v[186:189], v[206:209], v[118:121]
	v_mfma_f32_16x16x32_bf16 v[114:117], v[194:197], v[206:209], v[114:117]
	v_mfma_f32_16x16x32_bf16 v[94:97], v[186:189], v[214:217], v[94:97]
	v_mfma_f32_16x16x32_bf16 v[90:93], v[194:197], v[214:217], v[90:93]
	v_mfma_f32_16x16x32_bf16 v[78:81], v[186:189], v[222:225], v[78:81]
	v_mfma_f32_16x16x32_bf16 v[74:77], v[194:197], v[222:225], v[74:77]
	v_mfma_f32_16x16x32_bf16 v[70:73], v[186:189], v[230:233], v[70:73]
	v_mfma_f32_16x16x32_bf16 v[66:69], v[194:197], v[230:233], v[66:69]
	v_mfma_f32_16x16x32_bf16 v[118:121], v[190:193], v[210:213], v[118:121]
	v_mfma_f32_16x16x32_bf16 v[114:117], v[202:205], v[210:213], v[114:117]
	v_mfma_f32_16x16x32_bf16 v[94:97], v[190:193], v[218:221], v[94:97]
	v_mfma_f32_16x16x32_bf16 v[90:93], v[202:205], v[218:221], v[90:93]
	v_mfma_f32_16x16x32_bf16 v[78:81], v[190:193], v[226:229], v[78:81]
	v_mfma_f32_16x16x32_bf16 v[74:77], v[202:205], v[226:229], v[74:77]
	v_mfma_f32_16x16x32_bf16 v[70:73], v[190:193], v[234:237], v[70:73]
	v_mfma_f32_16x16x32_bf16 v[66:69], v[202:205], v[234:237], v[66:69]
	s_setprio 0
	s_barrier
	s_add_i32 s76, s56, s21
	v_lshl_add_u64 v[146:147], s[54:55], 0, v[134:135]
	s_mov_b32 m0, s76
	ds_read_b128 v[206:209], v169 offset:16384
	ds_read_b128 v[210:213], v169 offset:17408
	ds_read_b128 v[214:217], v169 offset:18432
	ds_read_b128 v[218:221], v169 offset:19456
	ds_read_b128 v[222:225], v169 offset:20480
	ds_read_b128 v[226:229], v169 offset:21504
	ds_read_b128 v[230:233], v169 offset:22528
	ds_read_b128 v[234:237], v169 offset:23552
	global_load_lds_dwordx4 v[146:147], off
	s_add_i32 m0, s76, 0x2000
	s_add_u32 s76, s54, 0x38000
	v_lshl_add_u64 v[198:199], s[54:55], 0, v[130:131]
	s_addc_u32 s77, s55, 0
	s_add_i32 s78, s57, s21
	global_load_lds_dwordx4 v[198:199], off
	v_lshl_add_u64 v[238:239], s[76:77], 0, v[134:135]
	s_mov_b32 m0, s78
	v_lshl_add_u64 v[240:241], s[66:67], 0, v[132:133]
	global_load_lds_dwordx4 v[238:239], off
	v_lshl_add_u64 v[238:239], s[76:77], 0, v[130:131]
	s_add_i32 m0, s78, 0x2000
	s_nop 0
	global_load_lds_dwordx4 v[238:239], off
	v_lshl_add_u64 v[238:239], s[66:67], 0, v[136:137]
	s_mov_b32 m0, s26
	s_nop 0
	global_load_lds_dwordx4 v[238:239], off
	s_mov_b32 m0, s27
	s_nop 0
	global_load_lds_dwordx4 v[240:241], off
	s_waitcnt vmcnt(8)
	s_waitcnt lgkmcnt(0)
	s_barrier
	s_setprio 1
	s_waitcnt lgkmcnt(0)
	v_mfma_f32_16x16x32_bf16 v[62:65], v[170:173], v[206:209], v[62:65]
	v_mfma_f32_16x16x32_bf16 v[58:61], v[178:181], v[206:209], v[58:61]
	v_mfma_f32_16x16x32_bf16 v[54:57], v[170:173], v[214:217], v[54:57]
	v_mfma_f32_16x16x32_bf16 v[50:53], v[178:181], v[214:217], v[50:53]
	v_mfma_f32_16x16x32_bf16 v[38:41], v[170:173], v[222:225], v[38:41]
	v_mfma_f32_16x16x32_bf16 v[34:37], v[178:181], v[222:225], v[34:37]
	v_mfma_f32_16x16x32_bf16 v[22:25], v[170:173], v[230:233], v[22:25]
	v_mfma_f32_16x16x32_bf16 v[18:21], v[178:181], v[230:233], v[18:21]
	v_mfma_f32_16x16x32_bf16 v[62:65], v[174:177], v[210:213], v[62:65]
	v_mfma_f32_16x16x32_bf16 v[58:61], v[182:185], v[210:213], v[58:61]
	v_mfma_f32_16x16x32_bf16 v[54:57], v[174:177], v[218:221], v[54:57]
	v_mfma_f32_16x16x32_bf16 v[50:53], v[182:185], v[218:221], v[50:53]
	v_mfma_f32_16x16x32_bf16 v[38:41], v[174:177], v[226:229], v[38:41]
	v_mfma_f32_16x16x32_bf16 v[34:37], v[182:185], v[226:229], v[34:37]
	v_mfma_f32_16x16x32_bf16 v[22:25], v[174:177], v[234:237], v[22:25]
	v_mfma_f32_16x16x32_bf16 v[18:21], v[182:185], v[234:237], v[18:21]
	s_setprio 0
	s_setprio 1
	v_mfma_f32_16x16x32_bf16 v[46:49], v[186:189], v[206:209], v[46:49]
	v_mfma_f32_16x16x32_bf16 v[42:45], v[194:197], v[206:209], v[42:45]
	v_mfma_f32_16x16x32_bf16 v[30:33], v[186:189], v[214:217], v[30:33]
	v_mfma_f32_16x16x32_bf16 v[26:29], v[194:197], v[214:217], v[26:29]
	v_mfma_f32_16x16x32_bf16 v[14:17], v[186:189], v[222:225], v[14:17]
	v_mfma_f32_16x16x32_bf16 v[10:13], v[194:197], v[222:225], v[10:13]
	v_mfma_f32_16x16x32_bf16 v[6:9], v[186:189], v[230:233], v[6:9]
	v_mfma_f32_16x16x32_bf16 v[2:5], v[194:197], v[230:233], v[2:5]
	v_mfma_f32_16x16x32_bf16 v[46:49], v[190:193], v[210:213], v[46:49]
	v_mfma_f32_16x16x32_bf16 v[42:45], v[202:205], v[210:213], v[42:45]
	v_mfma_f32_16x16x32_bf16 v[30:33], v[190:193], v[218:221], v[30:33]
	v_mfma_f32_16x16x32_bf16 v[26:29], v[202:205], v[218:221], v[26:29]
	v_mfma_f32_16x16x32_bf16 v[14:17], v[190:193], v[226:229], v[14:17]
	v_mfma_f32_16x16x32_bf16 v[10:13], v[202:205], v[226:229], v[10:13]
	v_mfma_f32_16x16x32_bf16 v[6:9], v[190:193], v[234:237], v[6:9]
	v_mfma_f32_16x16x32_bf16 v[2:5], v[202:205], v[234:237], v[2:5]
	s_setprio 0
	s_barrier
	s_add_i32 s76, 0, 0x18000
	s_add_i32 s77, 0, 0x1c000
	v_add_u32_e32 v182, s76, v163
	v_add_u32_e32 v201, s77, v163
	ds_read_b128 v[170:173], v182
	ds_read_b128 v[174:177], v182 offset:1024
	ds_read_b128 v[178:181], v182 offset:2048
	ds_read_b128 v[182:185], v182 offset:3072
	ds_read_b128 v[186:189], v201
	ds_read_b128 v[190:193], v201 offset:1024
	ds_read_b128 v[194:197], v201 offset:2048
	ds_read_b128 v[202:205], v201 offset:3072
	s_add_u32 s66, s66, 0x38000
	s_addc_u32 s67, s67, 0
	s_mov_b32 m0, s36
	v_lshl_add_u64 v[242:243], s[66:67], 0, v[136:137]
	ds_read_b128 v[206:209], v169 offset:32768
	ds_read_b128 v[210:213], v169 offset:33792
	ds_read_b128 v[214:217], v169 offset:34816
	ds_read_b128 v[218:221], v169 offset:35840
	ds_read_b128 v[222:225], v169 offset:36864
	ds_read_b128 v[226:229], v169 offset:37888
	ds_read_b128 v[230:233], v169 offset:38912
	ds_read_b128 v[234:237], v169 offset:39936
	global_load_lds_dwordx4 v[242:243], off
	v_lshl_add_u64 v[242:243], s[66:67], 0, v[132:133]
	s_mov_b32 m0, s37
	s_nop 0
	global_load_lds_dwordx4 v[242:243], off
	s_waitcnt vmcnt(8)
	s_waitcnt lgkmcnt(0)
	s_barrier
	s_setprio 1
	s_waitcnt lgkmcnt(0)
	v_mfma_f32_16x16x32_bf16 v[126:129], v[170:173], v[206:209], v[126:129]
	v_mfma_f32_16x16x32_bf16 v[122:125], v[178:181], v[206:209], v[122:125]
	v_mfma_f32_16x16x32_bf16 v[110:113], v[170:173], v[214:217], v[110:113]
	v_mfma_f32_16x16x32_bf16 v[106:109], v[178:181], v[214:217], v[106:109]
	v_mfma_f32_16x16x32_bf16 v[102:105], v[170:173], v[222:225], v[102:105]
	v_mfma_f32_16x16x32_bf16 v[98:101], v[178:181], v[222:225], v[98:101]
	v_mfma_f32_16x16x32_bf16 v[86:89], v[170:173], v[230:233], v[86:89]
	v_mfma_f32_16x16x32_bf16 v[82:85], v[178:181], v[230:233], v[82:85]
	v_mfma_f32_16x16x32_bf16 v[126:129], v[174:177], v[210:213], v[126:129]
	v_mfma_f32_16x16x32_bf16 v[122:125], v[182:185], v[210:213], v[122:125]
	v_mfma_f32_16x16x32_bf16 v[110:113], v[174:177], v[218:221], v[110:113]
	v_mfma_f32_16x16x32_bf16 v[106:109], v[182:185], v[218:221], v[106:109]
	v_mfma_f32_16x16x32_bf16 v[102:105], v[174:177], v[226:229], v[102:105]
	v_mfma_f32_16x16x32_bf16 v[98:101], v[182:185], v[226:229], v[98:101]
	v_mfma_f32_16x16x32_bf16 v[86:89], v[174:177], v[234:237], v[86:89]
	v_mfma_f32_16x16x32_bf16 v[82:85], v[182:185], v[234:237], v[82:85]
	s_setprio 0
	s_setprio 1
	v_mfma_f32_16x16x32_bf16 v[118:121], v[186:189], v[206:209], v[118:121]
	v_mfma_f32_16x16x32_bf16 v[114:117], v[194:197], v[206:209], v[114:117]
	v_mfma_f32_16x16x32_bf16 v[94:97], v[186:189], v[214:217], v[94:97]
	v_mfma_f32_16x16x32_bf16 v[90:93], v[194:197], v[214:217], v[90:93]
	v_mfma_f32_16x16x32_bf16 v[78:81], v[186:189], v[222:225], v[78:81]
	v_mfma_f32_16x16x32_bf16 v[74:77], v[194:197], v[222:225], v[74:77]
	v_mfma_f32_16x16x32_bf16 v[70:73], v[186:189], v[230:233], v[70:73]
	v_mfma_f32_16x16x32_bf16 v[66:69], v[194:197], v[230:233], v[66:69]
	v_mfma_f32_16x16x32_bf16 v[118:121], v[190:193], v[210:213], v[118:121]
	v_mfma_f32_16x16x32_bf16 v[114:117], v[202:205], v[210:213], v[114:117]
	v_mfma_f32_16x16x32_bf16 v[94:97], v[190:193], v[218:221], v[94:97]
	v_mfma_f32_16x16x32_bf16 v[90:93], v[202:205], v[218:221], v[90:93]
	v_mfma_f32_16x16x32_bf16 v[78:81], v[190:193], v[226:229], v[78:81]
	v_mfma_f32_16x16x32_bf16 v[74:77], v[202:205], v[226:229], v[74:77]
	v_mfma_f32_16x16x32_bf16 v[70:73], v[190:193], v[234:237], v[70:73]
	v_mfma_f32_16x16x32_bf16 v[66:69], v[202:205], v[234:237], v[66:69]
	s_setprio 0
	s_barrier
	s_add_i32 s66, s76, s21
	v_lshl_add_u64 v[146:147], v[146:147], 0, s[14:15]
	s_mov_b32 m0, s66
	ds_read_b128 v[206:209], v169 offset:49152
	ds_read_b128 v[210:213], v169 offset:50176
	ds_read_b128 v[214:217], v169 offset:51200
	ds_read_b128 v[218:221], v169 offset:52224
	ds_read_b128 v[222:225], v169 offset:53248
	ds_read_b128 v[226:229], v169 offset:54272
	ds_read_b128 v[230:233], v169 offset:55296
	ds_read_b128 v[234:237], v169 offset:56320
	global_load_lds_dwordx4 v[146:147], off
	s_add_i32 m0, s66, 0x2000
	s_add_u32 s54, s54, 0x38080
	v_lshl_add_u64 v[146:147], v[198:199], 0, s[14:15]
	s_addc_u32 s55, s55, 0
	s_add_i32 s66, s77, s21
	global_load_lds_dwordx4 v[146:147], off
	v_lshl_add_u64 v[146:147], s[54:55], 0, v[134:135]
	s_mov_b32 m0, s66
	s_nop 0
	global_load_lds_dwordx4 v[146:147], off
	v_lshl_add_u64 v[146:147], s[54:55], 0, v[130:131]
	s_add_i32 m0, s66, 0x2000
	s_nop 0
	global_load_lds_dwordx4 v[146:147], off
	v_lshl_add_u64 v[146:147], v[238:239], 0, s[14:15]
	s_mov_b32 m0, s39
	s_nop 0
	global_load_lds_dwordx4 v[146:147], off
	v_lshl_add_u64 v[146:147], v[240:241], 0, s[14:15]
	s_mov_b32 m0, s52
	s_nop 0
	global_load_lds_dwordx4 v[146:147], off
	s_waitcnt vmcnt(8)
	s_waitcnt lgkmcnt(0)
	s_barrier
	s_setprio 1
	s_waitcnt lgkmcnt(0)
	v_mfma_f32_16x16x32_bf16 v[62:65], v[170:173], v[206:209], v[62:65]
	v_mfma_f32_16x16x32_bf16 v[58:61], v[178:181], v[206:209], v[58:61]
	v_mfma_f32_16x16x32_bf16 v[54:57], v[170:173], v[214:217], v[54:57]
	v_mfma_f32_16x16x32_bf16 v[50:53], v[178:181], v[214:217], v[50:53]
	v_mfma_f32_16x16x32_bf16 v[38:41], v[170:173], v[222:225], v[38:41]
	v_mfma_f32_16x16x32_bf16 v[34:37], v[178:181], v[222:225], v[34:37]
	v_mfma_f32_16x16x32_bf16 v[22:25], v[170:173], v[230:233], v[22:25]
	v_mfma_f32_16x16x32_bf16 v[18:21], v[178:181], v[230:233], v[18:21]
	v_mfma_f32_16x16x32_bf16 v[62:65], v[174:177], v[210:213], v[62:65]
	v_mfma_f32_16x16x32_bf16 v[58:61], v[182:185], v[210:213], v[58:61]
	v_mfma_f32_16x16x32_bf16 v[54:57], v[174:177], v[218:221], v[54:57]
	v_mfma_f32_16x16x32_bf16 v[50:53], v[182:185], v[218:221], v[50:53]
	v_mfma_f32_16x16x32_bf16 v[38:41], v[174:177], v[226:229], v[38:41]
	v_mfma_f32_16x16x32_bf16 v[34:37], v[182:185], v[226:229], v[34:37]
	v_mfma_f32_16x16x32_bf16 v[22:25], v[174:177], v[234:237], v[22:25]
	v_mfma_f32_16x16x32_bf16 v[18:21], v[182:185], v[234:237], v[18:21]
	s_setprio 0
	s_setprio 1
	v_mfma_f32_16x16x32_bf16 v[46:49], v[186:189], v[206:209], v[46:49]
	v_mfma_f32_16x16x32_bf16 v[42:45], v[194:197], v[206:209], v[42:45]
	v_mfma_f32_16x16x32_bf16 v[30:33], v[186:189], v[214:217], v[30:33]
	v_mfma_f32_16x16x32_bf16 v[26:29], v[194:197], v[214:217], v[26:29]
	v_mfma_f32_16x16x32_bf16 v[14:17], v[186:189], v[222:225], v[14:17]
	v_mfma_f32_16x16x32_bf16 v[10:13], v[194:197], v[222:225], v[10:13]
	v_mfma_f32_16x16x32_bf16 v[6:9], v[186:189], v[230:233], v[6:9]
	v_mfma_f32_16x16x32_bf16 v[2:5], v[194:197], v[230:233], v[2:5]
	v_mfma_f32_16x16x32_bf16 v[46:49], v[190:193], v[210:213], v[46:49]
	v_mfma_f32_16x16x32_bf16 v[42:45], v[202:205], v[210:213], v[42:45]
	v_mfma_f32_16x16x32_bf16 v[30:33], v[190:193], v[218:221], v[30:33]
	v_mfma_f32_16x16x32_bf16 v[26:29], v[202:205], v[218:221], v[26:29]
	v_mfma_f32_16x16x32_bf16 v[14:17], v[190:193], v[226:229], v[14:17]
	v_mfma_f32_16x16x32_bf16 v[10:13], v[202:205], v[226:229], v[10:13]
	v_mfma_f32_16x16x32_bf16 v[6:9], v[190:193], v[234:237], v[6:9]
	v_mfma_f32_16x16x32_bf16 v[2:5], v[202:205], v[234:237], v[2:5]
	s_setprio 0
	s_barrier
	s_add_i32 s75, s75, 2
	s_add_u32 s30, s30, 0x100
	s_addc_u32 s31, s31, 0
	s_add_u32 s73, s73, 0x100
	s_addc_u32 s74, s74, 0
	s_cmp_gt_u32 s75, 11
	s_cbranch_scc0 .LBB0_830
	s_and_b64 vcc, exec, s[22:23]
	s_cbranch_vccz .LBB0_833
	s_barrier

.LBB0_878:
	ds_read_b128 v[152:155], v148
	ds_read_b128 v[156:159], v148 offset:1024
	ds_read_b128 v[166:169], v148 offset:2048
	ds_read_b128 v[170:173], v148 offset:3072
	ds_read_b128 v[174:177], v149
	ds_read_b128 v[178:181], v149 offset:1024
	ds_read_b128 v[182:185], v149 offset:2048
	ds_read_b128 v[186:189], v149 offset:3072
	s_add_u32 s54, s68, 0xfffe0080
	s_addc_u32 s55, s69, -1
	s_cmp_eq_u32 s81, 4
	s_cselect_b32 s71, s25, s55
	s_cselect_b32 s70, s77, s54
	s_cselect_b32 s55, s23, s80
	s_cselect_b32 s54, s78, s79
	v_lshl_add_u64 v[160:161], s[68:69], 0, v[138:139]
	s_add_i32 m0, s36, 0xc000
	ds_read_b128 v[190:193], v150
	ds_read_b128 v[194:197], v150 offset:1024
	ds_read_b128 v[202:205], v150 offset:2048
	ds_read_b128 v[206:209], v150 offset:3072
	ds_read_b128 v[210:213], v150 offset:4096
	ds_read_b128 v[214:217], v150 offset:5120
	ds_read_b128 v[218:221], v150 offset:6144
	ds_read_b128 v[222:225], v150 offset:7168
	global_load_lds_dwordx4 v[160:161], off
	v_lshl_add_u64 v[160:161], s[68:69], 0, v[140:141]
	s_add_i32 m0, s36, 0xe000
	s_nop 0
	global_load_lds_dwordx4 v[160:161], off
	s_waitcnt vmcnt(8)
	s_waitcnt lgkmcnt(0)
	s_barrier
	s_setprio 1
	s_waitcnt lgkmcnt(0)
	v_mfma_f32_16x16x32_bf16 v[126:129], v[152:155], v[190:193], v[126:129]
	v_mfma_f32_16x16x32_bf16 v[122:125], v[166:169], v[190:193], v[122:125]
	v_mfma_f32_16x16x32_bf16 v[110:113], v[152:155], v[202:205], v[110:113]
	v_mfma_f32_16x16x32_bf16 v[106:109], v[166:169], v[202:205], v[106:109]
	v_mfma_f32_16x16x32_bf16 v[94:97], v[152:155], v[210:213], v[94:97]
	v_mfma_f32_16x16x32_bf16 v[90:93], v[166:169], v[210:213], v[90:93]
	v_mfma_f32_16x16x32_bf16 v[78:81], v[152:155], v[218:221], v[78:81]
	v_mfma_f32_16x16x32_bf16 v[74:77], v[166:169], v[218:221], v[74:77]
	v_mfma_f32_16x16x32_bf16 v[126:129], v[156:159], v[194:197], v[126:129]
	v_mfma_f32_16x16x32_bf16 v[122:125], v[170:173], v[194:197], v[122:125]
	v_mfma_f32_16x16x32_bf16 v[110:113], v[156:159], v[206:209], v[110:113]
	v_mfma_f32_16x16x32_bf16 v[106:109], v[170:173], v[206:209], v[106:109]
	v_mfma_f32_16x16x32_bf16 v[94:97], v[156:159], v[214:217], v[94:97]
	v_mfma_f32_16x16x32_bf16 v[90:93], v[170:173], v[214:217], v[90:93]
	v_mfma_f32_16x16x32_bf16 v[78:81], v[156:159], v[222:225], v[78:81]
	v_mfma_f32_16x16x32_bf16 v[74:77], v[170:173], v[222:225], v[74:77]
	s_setprio 0
	s_setprio 1
	v_mfma_f32_16x16x32_bf16 v[118:121], v[174:177], v[190:193], v[118:121]
	v_mfma_f32_16x16x32_bf16 v[114:117], v[182:185], v[190:193], v[114:117]
	v_mfma_f32_16x16x32_bf16 v[102:105], v[174:177], v[202:205], v[102:105]
	v_mfma_f32_16x16x32_bf16 v[98:101], v[182:185], v[202:205], v[98:101]
	v_mfma_f32_16x16x32_bf16 v[86:89], v[174:177], v[210:213], v[86:89]
	v_mfma_f32_16x16x32_bf16 v[82:85], v[182:185], v[210:213], v[82:85]
	v_mfma_f32_16x16x32_bf16 v[70:73], v[174:177], v[218:221], v[70:73]
	v_mfma_f32_16x16x32_bf16 v[66:69], v[182:185], v[218:221], v[66:69]
	v_mfma_f32_16x16x32_bf16 v[118:121], v[178:181], v[194:197], v[118:121]
	v_mfma_f32_16x16x32_bf16 v[114:117], v[186:189], v[194:197], v[114:117]
	v_mfma_f32_16x16x32_bf16 v[102:105], v[178:181], v[206:209], v[102:105]
	v_mfma_f32_16x16x32_bf16 v[98:101], v[186:189], v[206:209], v[98:101]
	v_mfma_f32_16x16x32_bf16 v[86:89], v[178:181], v[214:217], v[86:89]
	v_mfma_f32_16x16x32_bf16 v[82:85], v[186:189], v[214:217], v[82:85]
	v_mfma_f32_16x16x32_bf16 v[70:73], v[178:181], v[222:225], v[70:73]
	v_mfma_f32_16x16x32_bf16 v[66:69], v[186:189], v[222:225], v[66:69]
	s_setprio 0
	s_barrier
	s_add_i32 s82, s73, s2
	v_lshl_add_u64 v[160:161], s[54:55], 0, v[132:133]
	s_mov_b32 m0, s82
	ds_read_b128 v[190:193], v150 offset:16384
	ds_read_b128 v[194:197], v150 offset:17408
	ds_read_b128 v[202:205], v150 offset:18432
	ds_read_b128 v[206:209], v150 offset:19456
	ds_read_b128 v[210:213], v150 offset:20480
	ds_read_b128 v[214:217], v150 offset:21504
	ds_read_b128 v[218:221], v150 offset:22528
	ds_read_b128 v[222:225], v150 offset:23552
	global_load_lds_dwordx4 v[160:161], off
	s_add_i32 m0, s82, 0x2000
	s_add_u32 s82, s54, 0x20000
	v_lshl_add_u64 v[198:199], s[54:55], 0, v[136:137]
	s_addc_u32 s83, s55, 0
	s_add_i32 s84, s74, s2
	global_load_lds_dwordx4 v[198:199], off
	v_lshl_add_u64 v[226:227], s[82:83], 0, v[132:133]
	s_mov_b32 m0, s84
	v_lshl_add_u64 v[228:229], s[70:71], 0, v[134:135]
	global_load_lds_dwordx4 v[226:227], off
	v_lshl_add_u64 v[226:227], s[82:83], 0, v[136:137]
	s_add_i32 m0, s84, 0x2000
	s_nop 0
	global_load_lds_dwordx4 v[226:227], off
	v_lshl_add_u64 v[226:227], s[70:71], 0, v[130:131]
	s_mov_b32 m0, s36
	s_nop 0
	global_load_lds_dwordx4 v[226:227], off
	s_mov_b32 m0, s37
	s_nop 0
	global_load_lds_dwordx4 v[228:229], off
	s_waitcnt vmcnt(8)
	s_waitcnt lgkmcnt(0)
	s_barrier
	s_setprio 1
	s_waitcnt lgkmcnt(0)
	v_mfma_f32_16x16x32_bf16 v[62:65], v[152:155], v[190:193], v[62:65]
	v_mfma_f32_16x16x32_bf16 v[58:61], v[166:169], v[190:193], v[58:61]
	v_mfma_f32_16x16x32_bf16 v[46:49], v[152:155], v[202:205], v[46:49]
	v_mfma_f32_16x16x32_bf16 v[42:45], v[166:169], v[202:205], v[42:45]
	v_mfma_f32_16x16x32_bf16 v[30:33], v[152:155], v[210:213], v[30:33]
	v_mfma_f32_16x16x32_bf16 v[26:29], v[166:169], v[210:213], v[26:29]
	v_mfma_f32_16x16x32_bf16 v[14:17], v[152:155], v[218:221], v[14:17]
	v_mfma_f32_16x16x32_bf16 v[10:13], v[166:169], v[218:221], v[10:13]
	v_mfma_f32_16x16x32_bf16 v[62:65], v[156:159], v[194:197], v[62:65]
	v_mfma_f32_16x16x32_bf16 v[58:61], v[170:173], v[194:197], v[58:61]
	v_mfma_f32_16x16x32_bf16 v[46:49], v[156:159], v[206:209], v[46:49]
	v_mfma_f32_16x16x32_bf16 v[42:45], v[170:173], v[206:209], v[42:45]
	v_mfma_f32_16x16x32_bf16 v[30:33], v[156:159], v[214:217], v[30:33]
	v_mfma_f32_16x16x32_bf16 v[26:29], v[170:173], v[214:217], v[26:29]
	v_mfma_f32_16x16x32_bf16 v[14:17], v[156:159], v[222:225], v[14:17]
	v_mfma_f32_16x16x32_bf16 v[10:13], v[170:173], v[222:225], v[10:13]
	s_setprio 0
	s_setprio 1
	v_mfma_f32_16x16x32_bf16 v[54:57], v[174:177], v[190:193], v[54:57]
	v_mfma_f32_16x16x32_bf16 v[50:53], v[182:185], v[190:193], v[50:53]
	v_mfma_f32_16x16x32_bf16 v[38:41], v[174:177], v[202:205], v[38:41]
	v_mfma_f32_16x16x32_bf16 v[34:37], v[182:185], v[202:205], v[34:37]
	v_mfma_f32_16x16x32_bf16 v[22:25], v[174:177], v[210:213], v[22:25]
	v_mfma_f32_16x16x32_bf16 v[18:21], v[182:185], v[210:213], v[18:21]
	v_mfma_f32_16x16x32_bf16 v[6:9], v[174:177], v[218:221], v[6:9]
	v_mfma_f32_16x16x32_bf16 v[2:5], v[182:185], v[218:221], v[2:5]
	v_mfma_f32_16x16x32_bf16 v[54:57], v[178:181], v[194:197], v[54:57]
	v_mfma_f32_16x16x32_bf16 v[50:53], v[186:189], v[194:197], v[50:53]
	v_mfma_f32_16x16x32_bf16 v[38:41], v[178:181], v[206:209], v[38:41]
	v_mfma_f32_16x16x32_bf16 v[34:37], v[186:189], v[206:209], v[34:37]
	v_mfma_f32_16x16x32_bf16 v[22:25], v[178:181], v[214:217], v[22:25]
	v_mfma_f32_16x16x32_bf16 v[18:21], v[186:189], v[214:217], v[18:21]
	v_mfma_f32_16x16x32_bf16 v[6:9], v[178:181], v[222:225], v[6:9]
	v_mfma_f32_16x16x32_bf16 v[2:5], v[186:189], v[222:225], v[2:5]
	s_setprio 0
	s_barrier
	s_add_i32 s82, 0, 0x18000
	v_add_u32_e32 v163, s82, v147
	s_add_i32 s83, 0, 0x1c000
	ds_read_b128 v[152:155], v163
	ds_read_b128 v[156:159], v163 offset:1024
	ds_read_b128 v[166:169], v163 offset:2048
	ds_read_b128 v[170:173], v163 offset:3072
	v_add_u32_e32 v163, s83, v147
	ds_read_b128 v[174:177], v163
	ds_read_b128 v[178:181], v163 offset:1024
	ds_read_b128 v[182:185], v163 offset:2048
	ds_read_b128 v[186:189], v163 offset:3072
	s_add_u32 s70, s70, 0x20000
	s_addc_u32 s71, s71, 0
	s_mov_b32 m0, s38
	v_lshl_add_u64 v[230:231], s[70:71], 0, v[130:131]
	ds_read_b128 v[190:193], v150 offset:32768
	ds_read_b128 v[194:197], v150 offset:33792
	ds_read_b128 v[202:205], v150 offset:34816
	ds_read_b128 v[206:209], v150 offset:35840
	ds_read_b128 v[210:213], v150 offset:36864
	ds_read_b128 v[214:217], v150 offset:37888
	ds_read_b128 v[218:221], v150 offset:38912
	ds_read_b128 v[222:225], v150 offset:39936
	global_load_lds_dwordx4 v[230:231], off
	v_lshl_add_u64 v[230:231], s[70:71], 0, v[134:135]
	s_mov_b32 m0, s39
	s_nop 0
	global_load_lds_dwordx4 v[230:231], off
	s_waitcnt vmcnt(8)
	s_waitcnt lgkmcnt(0)
	s_barrier
	s_setprio 1
	s_waitcnt lgkmcnt(0)
	v_mfma_f32_16x16x32_bf16 v[126:129], v[152:155], v[190:193], v[126:129]
	v_mfma_f32_16x16x32_bf16 v[122:125], v[166:169], v[190:193], v[122:125]
	v_mfma_f32_16x16x32_bf16 v[110:113], v[152:155], v[202:205], v[110:113]
	v_mfma_f32_16x16x32_bf16 v[106:109], v[166:169], v[202:205], v[106:109]
	v_mfma_f32_16x16x32_bf16 v[94:97], v[152:155], v[210:213], v[94:97]
	v_mfma_f32_16x16x32_bf16 v[90:93], v[166:169], v[210:213], v[90:93]
	v_mfma_f32_16x16x32_bf16 v[78:81], v[152:155], v[218:221], v[78:81]
	v_mfma_f32_16x16x32_bf16 v[74:77], v[166:169], v[218:221], v[74:77]
	v_mfma_f32_16x16x32_bf16 v[126:129], v[156:159], v[194:197], v[126:129]
	v_mfma_f32_16x16x32_bf16 v[122:125], v[170:173], v[194:197], v[122:125]
	v_mfma_f32_16x16x32_bf16 v[110:113], v[156:159], v[206:209], v[110:113]
	v_mfma_f32_16x16x32_bf16 v[106:109], v[170:173], v[206:209], v[106:109]
	v_mfma_f32_16x16x32_bf16 v[94:97], v[156:159], v[214:217], v[94:97]
	v_mfma_f32_16x16x32_bf16 v[90:93], v[170:173], v[214:217], v[90:93]
	v_mfma_f32_16x16x32_bf16 v[78:81], v[156:159], v[222:225], v[78:81]
	v_mfma_f32_16x16x32_bf16 v[74:77], v[170:173], v[222:225], v[74:77]
	s_setprio 0
	s_setprio 1
	v_mfma_f32_16x16x32_bf16 v[118:121], v[174:177], v[190:193], v[118:121]
	v_mfma_f32_16x16x32_bf16 v[114:117], v[182:185], v[190:193], v[114:117]
	v_mfma_f32_16x16x32_bf16 v[102:105], v[174:177], v[202:205], v[102:105]
	v_mfma_f32_16x16x32_bf16 v[98:101], v[182:185], v[202:205], v[98:101]
	v_mfma_f32_16x16x32_bf16 v[86:89], v[174:177], v[210:213], v[86:89]
	v_mfma_f32_16x16x32_bf16 v[82:85], v[182:185], v[210:213], v[82:85]
	v_mfma_f32_16x16x32_bf16 v[70:73], v[174:177], v[218:221], v[70:73]
	v_mfma_f32_16x16x32_bf16 v[66:69], v[182:185], v[218:221], v[66:69]
	v_mfma_f32_16x16x32_bf16 v[118:121], v[178:181], v[194:197], v[118:121]
	v_mfma_f32_16x16x32_bf16 v[114:117], v[186:189], v[194:197], v[114:117]
	v_mfma_f32_16x16x32_bf16 v[102:105], v[178:181], v[206:209], v[102:105]
	v_mfma_f32_16x16x32_bf16 v[98:101], v[186:189], v[206:209], v[98:101]
	v_mfma_f32_16x16x32_bf16 v[86:89], v[178:181], v[214:217], v[86:89]
	v_mfma_f32_16x16x32_bf16 v[82:85], v[186:189], v[214:217], v[82:85]
	v_mfma_f32_16x16x32_bf16 v[70:73], v[178:181], v[222:225], v[70:73]
	v_mfma_f32_16x16x32_bf16 v[66:69], v[186:189], v[222:225], v[66:69]
	s_setprio 0
	s_barrier
	s_add_i32 s70, s82, s2
	v_lshl_add_u64 v[160:161], v[160:161], 0, s[10:11]
	s_mov_b32 m0, s70
	ds_read_b128 v[190:193], v150 offset:49152
	ds_read_b128 v[194:197], v150 offset:50176
	ds_read_b128 v[202:205], v150 offset:51200
	ds_read_b128 v[206:209], v150 offset:52224
	ds_read_b128 v[210:213], v150 offset:53248
	ds_read_b128 v[214:217], v150 offset:54272
	ds_read_b128 v[218:221], v150 offset:55296
	ds_read_b128 v[222:225], v150 offset:56320
	global_load_lds_dwordx4 v[160:161], off
	s_add_i32 m0, s70, 0x2000
	s_add_u32 s54, s54, 0x20080
	v_lshl_add_u64 v[160:161], v[198:199], 0, s[10:11]
	s_addc_u32 s55, s55, 0
	s_add_i32 s70, s83, s2
	global_load_lds_dwordx4 v[160:161], off
	v_lshl_add_u64 v[160:161], s[54:55], 0, v[132:133]
	s_mov_b32 m0, s70
	s_nop 0
	global_load_lds_dwordx4 v[160:161], off
	v_lshl_add_u64 v[160:161], s[54:55], 0, v[136:137]
	s_add_i32 m0, s70, 0x2000
	s_nop 0
	global_load_lds_dwordx4 v[160:161], off
	v_lshl_add_u64 v[160:161], v[226:227], 0, s[10:11]
	s_mov_b32 m0, s57
	s_nop 0
	global_load_lds_dwordx4 v[160:161], off
	v_lshl_add_u64 v[160:161], v[228:229], 0, s[10:11]
	s_mov_b32 m0, s67
	s_nop 0
	global_load_lds_dwordx4 v[160:161], off
	s_waitcnt vmcnt(8)
	s_waitcnt lgkmcnt(0)
	s_barrier
	s_setprio 1
	s_waitcnt lgkmcnt(0)
	v_mfma_f32_16x16x32_bf16 v[62:65], v[152:155], v[190:193], v[62:65]
	v_mfma_f32_16x16x32_bf16 v[58:61], v[166:169], v[190:193], v[58:61]
	v_mfma_f32_16x16x32_bf16 v[46:49], v[152:155], v[202:205], v[46:49]
	v_mfma_f32_16x16x32_bf16 v[42:45], v[166:169], v[202:205], v[42:45]
	v_mfma_f32_16x16x32_bf16 v[30:33], v[152:155], v[210:213], v[30:33]
	v_mfma_f32_16x16x32_bf16 v[26:29], v[166:169], v[210:213], v[26:29]
	v_mfma_f32_16x16x32_bf16 v[14:17], v[152:155], v[218:221], v[14:17]
	v_mfma_f32_16x16x32_bf16 v[10:13], v[166:169], v[218:221], v[10:13]
	v_mfma_f32_16x16x32_bf16 v[62:65], v[156:159], v[194:197], v[62:65]
	v_mfma_f32_16x16x32_bf16 v[58:61], v[170:173], v[194:197], v[58:61]
	v_mfma_f32_16x16x32_bf16 v[46:49], v[156:159], v[206:209], v[46:49]
	v_mfma_f32_16x16x32_bf16 v[42:45], v[170:173], v[206:209], v[42:45]
	v_mfma_f32_16x16x32_bf16 v[30:33], v[156:159], v[214:217], v[30:33]
	v_mfma_f32_16x16x32_bf16 v[26:29], v[170:173], v[214:217], v[26:29]
	v_mfma_f32_16x16x32_bf16 v[14:17], v[156:159], v[222:225], v[14:17]
	v_mfma_f32_16x16x32_bf16 v[10:13], v[170:173], v[222:225], v[10:13]
	s_setprio 0
	s_setprio 1
	v_mfma_f32_16x16x32_bf16 v[54:57], v[174:177], v[190:193], v[54:57]
	v_mfma_f32_16x16x32_bf16 v[50:53], v[182:185], v[190:193], v[50:53]
	v_mfma_f32_16x16x32_bf16 v[38:41], v[174:177], v[202:205], v[38:41]
	v_mfma_f32_16x16x32_bf16 v[34:37], v[182:185], v[202:205], v[34:37]
	v_mfma_f32_16x16x32_bf16 v[22:25], v[174:177], v[210:213], v[22:25]
	v_mfma_f32_16x16x32_bf16 v[18:21], v[182:185], v[210:213], v[18:21]
	v_mfma_f32_16x16x32_bf16 v[6:9], v[174:177], v[218:221], v[6:9]
	v_mfma_f32_16x16x32_bf16 v[2:5], v[182:185], v[218:221], v[2:5]
	v_mfma_f32_16x16x32_bf16 v[54:57], v[178:181], v[194:197], v[54:57]
	v_mfma_f32_16x16x32_bf16 v[50:53], v[186:189], v[194:197], v[50:53]
	v_mfma_f32_16x16x32_bf16 v[38:41], v[178:181], v[206:209], v[38:41]
	v_mfma_f32_16x16x32_bf16 v[34:37], v[186:189], v[206:209], v[34:37]
	v_mfma_f32_16x16x32_bf16 v[22:25], v[178:181], v[214:217], v[22:25]
	v_mfma_f32_16x16x32_bf16 v[18:21], v[186:189], v[214:217], v[18:21]
	v_mfma_f32_16x16x32_bf16 v[6:9], v[178:181], v[222:225], v[6:9]
	v_mfma_f32_16x16x32_bf16 v[2:5], v[186:189], v[222:225], v[2:5]
	s_setprio 0
	s_barrier
	s_add_i32 s81, s81, 2
	s_add_u32 s68, s68, 0x100
	s_addc_u32 s69, s69, 0
	s_add_u32 s79, s79, 0x100
	s_addc_u32 s80, s80, 0
	s_cmp_gt_u32 s81, 5
	s_cbranch_scc0 .LBB0_878
	s_and_b64 vcc, exec, s[14:15]
	s_cbranch_vccz .LBB0_881
	s_barrier

.LBB0_1218:
	s_cmp_gt_i32 s55, 0
	s_cselect_b32 s6, -1, 2
	s_add_i32 s50, s6, s55
	s_add_i32 s6, s93, 2
	s_min_u32 s6, s6, s56
	s_mul_i32 s7, s6, 0x60000
	s_add_u32 s86, s92, s7
	s_addc_u32 s87, s54, 0
	s_lshl_b32 s6, s6, 18
	s_add_u32 s6, s80, s6
	s_mul_i32 s50, s50, 0xb400
	s_addc_u32 s7, s81, 0
	s_add_i32 vcc_lo, s50, 0
	s_and_b64 s[50:51], s[30:31], exec
	s_cselect_b32 s51, s87, s7
	s_cselect_b32 s50, s86, s6
	s_waitcnt vmcnt(6) lgkmcnt(0)
	s_barrier
	s_cmp_eq_u32 s98, 0
	s_cbranch_scc1 .Lskew_done
	s_sleep 8
.Lskew_done:
	v_lshl_add_u64 v[4:5], s[50:51], 0, v[166:167]
	s_add_i32 s50, vcc_lo, s20
	s_mov_b32 s51, m0
	s_mov_b32 m0, s50
	s_nop 0
	global_load_lds_dwordx4 v[4:5], off
	s_mov_b32 m0, s51
	s_and_b64 s[50:51], s[52:53], exec
	s_cselect_b32 s51, s87, s7
	s_cselect_b32 s50, s86, s6
	v_lshl_add_u64 v[4:5], s[50:51], 0, v[146:147]
	s_add_i32 s50, vcc_lo, s26
	s_mov_b32 s51, m0
	s_mov_b32 m0, s50
	s_nop 0
	global_load_lds_dwordx4 v[4:5], off
	s_mov_b32 m0, s51
	s_and_b64 s[50:51], s[72:73], exec
	s_cselect_b32 s51, s87, s7
	s_cselect_b32 s50, s86, s6
	v_lshl_add_u64 v[4:5], s[50:51], 0, v[148:149]
	s_add_i32 s50, vcc_lo, s36
	s_mov_b32 s51, m0
	s_mov_b32 m0, s50
	s_nop 0
	global_load_lds_dwordx4 v[4:5], off
	s_mov_b32 m0, s51
	s_and_b64 s[50:51], s[74:75], exec
	s_cselect_b32 s51, s87, s7
	s_cselect_b32 s50, s86, s6
	v_lshl_add_u64 v[4:5], s[50:51], 0, v[150:151]
	s_add_i32 s50, vcc_lo, s38
	s_mov_b32 s51, m0
	s_mov_b32 m0, s50
	s_nop 0
	global_load_lds_dwordx4 v[4:5], off
	s_mov_b32 m0, s51
	s_and_b64 s[50:51], s[76:77], exec
	s_cselect_b32 s51, s87, s7
	s_cselect_b32 s50, s86, s6
	v_lshl_add_u64 v[4:5], s[50:51], 0, v[168:169]
	s_add_i32 s50, vcc_lo, s88
	s_mov_b32 s51, m0
	s_mov_b32 m0, s50
	s_nop 0
	global_load_lds_dwordx4 v[4:5], off
	s_mov_b32 m0, s51
	s_add_i32 vcc_lo, vcc_lo, s90
	v_lshl_add_u64 v[4:5], s[6:7], 0, v[152:153]
	s_mov_b32 s6, m0
	s_mov_b32 m0, vcc_lo
	s_nop 0
	global_load_lds_dwordx4 v[4:5], off
	s_mov_b32 m0, s6
	s_lshl_b32 s50, s93, 6
	s_cmp_gt_u32 s50, s57
	s_cbranch_scc1 .LBB0_1227
	s_mul_i32 s6, s55, 0xb400
	s_add_i32 s6, s6, 0
	v_add_u32_e32 v3, s6, v204
	v_add3_u32 v4, s6, v206, v207
	s_mov_b32 s51, 0
	s_mov_b64 s[6:7], -1
	s_branch .LBB0_1221

.LBB0_1383:
	v_add_u32_e32 v2, s85, v187
	ds_read_b128 v[134:137], v2
	ds_read_b128 v[138:141], v2 offset:1024
	ds_read_b128 v[142:145], v2 offset:2048
	ds_read_b128 v[146:149], v2 offset:3072
	v_add_u32_e32 v2, s86, v187
	ds_read_b128 v[150:153], v2
	ds_read_b128 v[154:157], v2 offset:1024
	ds_read_b128 v[178:181], v2 offset:2048
	ds_read_b128 v[182:185], v2 offset:3072
	s_add_u32 s51, s76, 0xfff00080
	s_addc_u32 s54, s77, -1
	s_cmp_eq_u32 s50, 28
	s_cselect_b32 s83, s9, s54
	s_cselect_b32 s82, s14, s51
	s_cselect_b32 s79, s15, s37
	s_cselect_b32 s78, s33, s36
	s_waitcnt lgkmcnt(0)
	v_lshl_add_u64 v[4:5], s[76:77], 0, v[170:171]
	s_add_i32 m0, s21, 0xc000
	ds_read_b128 v[192:195], v188
	ds_read_b128 v[196:199], v188 offset:1024
	ds_read_b128 v[210:213], v188 offset:2048
	ds_read_b128 v[214:217], v188 offset:3072
	ds_read_b128 v[218:221], v188 offset:4096
	ds_read_b128 v[222:225], v188 offset:5120
	ds_read_b128 v[226:229], v188 offset:6144
	ds_read_b128 v[230:233], v188 offset:7168
	global_load_lds_dwordx4 v[4:5], off
	v_lshl_add_u64 v[4:5], s[76:77], 0, v[172:173]
	s_add_i32 m0, s21, 0xe000
	s_nop 0
	global_load_lds_dwordx4 v[4:5], off
	s_waitcnt vmcnt(8)
	s_waitcnt lgkmcnt(0)
	s_barrier
	s_setprio 1
	s_waitcnt lgkmcnt(0)
	v_mfma_f32_16x16x32_bf16 v[130:133], v[134:137], v[192:195], v[130:133]
	v_mfma_f32_16x16x32_bf16 v[126:129], v[142:145], v[192:195], v[126:129]
	v_mfma_f32_16x16x32_bf16 v[122:125], v[134:137], v[210:213], v[122:125]
	v_mfma_f32_16x16x32_bf16 v[118:121], v[142:145], v[210:213], v[118:121]
	v_mfma_f32_16x16x32_bf16 v[114:117], v[134:137], v[218:221], v[114:117]
	v_mfma_f32_16x16x32_bf16 v[110:113], v[142:145], v[218:221], v[110:113]
	v_mfma_f32_16x16x32_bf16 v[106:109], v[134:137], v[226:229], v[106:109]
	v_mfma_f32_16x16x32_bf16 v[102:105], v[142:145], v[226:229], v[102:105]
	v_mfma_f32_16x16x32_bf16 v[130:133], v[138:141], v[196:199], v[130:133]
	v_mfma_f32_16x16x32_bf16 v[126:129], v[146:149], v[196:199], v[126:129]
	v_mfma_f32_16x16x32_bf16 v[122:125], v[138:141], v[214:217], v[122:125]
	v_mfma_f32_16x16x32_bf16 v[118:121], v[146:149], v[214:217], v[118:121]
	v_mfma_f32_16x16x32_bf16 v[114:117], v[138:141], v[222:225], v[114:117]
	v_mfma_f32_16x16x32_bf16 v[110:113], v[146:149], v[222:225], v[110:113]
	v_mfma_f32_16x16x32_bf16 v[106:109], v[138:141], v[230:233], v[106:109]
	v_mfma_f32_16x16x32_bf16 v[102:105], v[146:149], v[230:233], v[102:105]
	s_setprio 0
	s_setprio 1
	v_mfma_f32_16x16x32_bf16 v[98:101], v[150:153], v[192:195], v[98:101]
	v_mfma_f32_16x16x32_bf16 v[94:97], v[178:181], v[192:195], v[94:97]
	v_mfma_f32_16x16x32_bf16 v[90:93], v[150:153], v[210:213], v[90:93]
	v_mfma_f32_16x16x32_bf16 v[86:89], v[178:181], v[210:213], v[86:89]
	v_mfma_f32_16x16x32_bf16 v[82:85], v[150:153], v[218:221], v[82:85]
	v_mfma_f32_16x16x32_bf16 v[78:81], v[178:181], v[218:221], v[78:81]
	v_mfma_f32_16x16x32_bf16 v[74:77], v[150:153], v[226:229], v[74:77]
	v_mfma_f32_16x16x32_bf16 v[70:73], v[178:181], v[226:229], v[70:73]
	v_mfma_f32_16x16x32_bf16 v[98:101], v[154:157], v[196:199], v[98:101]
	v_mfma_f32_16x16x32_bf16 v[94:97], v[182:185], v[196:199], v[94:97]
	v_mfma_f32_16x16x32_bf16 v[90:93], v[154:157], v[214:217], v[90:93]
	v_mfma_f32_16x16x32_bf16 v[86:89], v[182:185], v[214:217], v[86:89]
	v_mfma_f32_16x16x32_bf16 v[82:85], v[154:157], v[222:225], v[82:85]
	v_mfma_f32_16x16x32_bf16 v[78:81], v[182:185], v[222:225], v[78:81]
	v_mfma_f32_16x16x32_bf16 v[74:77], v[154:157], v[230:233], v[74:77]
	v_mfma_f32_16x16x32_bf16 v[70:73], v[182:185], v[230:233], v[70:73]
	s_setprio 0
	s_barrier
	s_add_i32 s51, s85, s20
	v_lshl_add_u64 v[234:235], s[78:79], 0, v[160:161]
	s_mov_b32 m0, s51
	ds_read_b128 v[192:195], v188 offset:16384
	ds_read_b128 v[196:199], v188 offset:17408
	ds_read_b128 v[210:213], v188 offset:18432
	ds_read_b128 v[214:217], v188 offset:19456
	ds_read_b128 v[218:221], v188 offset:20480
	ds_read_b128 v[222:225], v188 offset:21504
	ds_read_b128 v[226:229], v188 offset:22528
	ds_read_b128 v[230:233], v188 offset:23552
	global_load_lds_dwordx4 v[234:235], off
	s_add_i32 m0, s51, 0x2000
	s_add_u32 s54, s78, 0x100000
	v_lshl_add_u64 v[236:237], s[78:79], 0, v[168:169]
	s_addc_u32 s55, s79, 0
	s_add_i32 s51, s86, s20
	global_load_lds_dwordx4 v[236:237], off
	v_lshl_add_u64 v[4:5], s[54:55], 0, v[160:161]
	s_mov_b32 m0, s51
	v_lshl_add_u64 v[238:239], s[82:83], 0, v[158:159]
	global_load_lds_dwordx4 v[4:5], off
	v_lshl_add_u64 v[4:5], s[54:55], 0, v[168:169]
	s_add_i32 m0, s51, 0x2000
	v_lshl_add_u64 v[240:241], s[82:83], 0, v[166:167]
	global_load_lds_dwordx4 v[4:5], off
	s_mov_b32 m0, s21
	s_nop 0
	global_load_lds_dwordx4 v[238:239], off
	s_mov_b32 m0, s26
	s_nop 0
	global_load_lds_dwordx4 v[240:241], off
	s_waitcnt vmcnt(8)
	s_waitcnt lgkmcnt(0)
	s_barrier
	s_setprio 1
	s_waitcnt lgkmcnt(0)
	v_mfma_f32_16x16x32_bf16 v[66:69], v[134:137], v[192:195], v[66:69]
	v_mfma_f32_16x16x32_bf16 v[62:65], v[142:145], v[192:195], v[62:65]
	v_mfma_f32_16x16x32_bf16 v[58:61], v[134:137], v[210:213], v[58:61]
	v_mfma_f32_16x16x32_bf16 v[54:57], v[142:145], v[210:213], v[54:57]
	v_mfma_f32_16x16x32_bf16 v[50:53], v[134:137], v[218:221], v[50:53]
	v_mfma_f32_16x16x32_bf16 v[46:49], v[142:145], v[218:221], v[46:49]
	v_mfma_f32_16x16x32_bf16 v[42:45], v[134:137], v[226:229], v[42:45]
	v_mfma_f32_16x16x32_bf16 v[38:41], v[142:145], v[226:229], v[38:41]
	v_mfma_f32_16x16x32_bf16 v[66:69], v[138:141], v[196:199], v[66:69]
	v_mfma_f32_16x16x32_bf16 v[62:65], v[146:149], v[196:199], v[62:65]
	v_mfma_f32_16x16x32_bf16 v[58:61], v[138:141], v[214:217], v[58:61]
	v_mfma_f32_16x16x32_bf16 v[54:57], v[146:149], v[214:217], v[54:57]
	v_mfma_f32_16x16x32_bf16 v[50:53], v[138:141], v[222:225], v[50:53]
	v_mfma_f32_16x16x32_bf16 v[46:49], v[146:149], v[222:225], v[46:49]
	v_mfma_f32_16x16x32_bf16 v[42:45], v[138:141], v[230:233], v[42:45]
	v_mfma_f32_16x16x32_bf16 v[38:41], v[146:149], v[230:233], v[38:41]
	s_setprio 0
	s_setprio 1
	v_mfma_f32_16x16x32_bf16 v[34:37], v[150:153], v[192:195], v[34:37]
	v_mfma_f32_16x16x32_bf16 v[30:33], v[178:181], v[192:195], v[30:33]
	v_mfma_f32_16x16x32_bf16 v[26:29], v[150:153], v[210:213], v[26:29]
	v_mfma_f32_16x16x32_bf16 v[22:25], v[178:181], v[210:213], v[22:25]
	v_mfma_f32_16x16x32_bf16 v[18:21], v[150:153], v[218:221], v[18:21]
	v_mfma_f32_16x16x32_bf16 v[14:17], v[178:181], v[218:221], v[14:17]
	v_mfma_f32_16x16x32_bf16 v[10:13], v[150:153], v[226:229], v[10:13]
	v_mfma_f32_16x16x32_bf16 v[4:7], v[178:181], v[226:229], v[6:9]
	v_mfma_f32_16x16x32_bf16 v[34:37], v[154:157], v[196:199], v[34:37]
	v_mfma_f32_16x16x32_bf16 v[30:33], v[182:185], v[196:199], v[30:33]
	v_mfma_f32_16x16x32_bf16 v[26:29], v[154:157], v[214:217], v[26:29]
	v_mfma_f32_16x16x32_bf16 v[22:25], v[182:185], v[214:217], v[22:25]
	v_mfma_f32_16x16x32_bf16 v[18:21], v[154:157], v[222:225], v[18:21]
	v_mfma_f32_16x16x32_bf16 v[14:17], v[182:185], v[222:225], v[14:17]
	v_mfma_f32_16x16x32_bf16 v[10:13], v[154:157], v[230:233], v[10:13]
	v_mfma_f32_16x16x32_bf16 v[4:7], v[182:185], v[230:233], v[4:7]
	s_setprio 0
	s_barrier
	s_add_i32 s51, 0, 0x18000
	v_add_u32_e32 v2, s51, v187
	s_add_i32 s56, 0, 0x1c000
	ds_read_b128 v[134:137], v2
	ds_read_b128 v[138:141], v2 offset:1024
	ds_read_b128 v[142:145], v2 offset:2048
	ds_read_b128 v[146:149], v2 offset:3072
	v_add_u32_e32 v2, s56, v187
	ds_read_b128 v[150:153], v2
	ds_read_b128 v[154:157], v2 offset:1024
	ds_read_b128 v[178:181], v2 offset:2048
	ds_read_b128 v[182:185], v2 offset:3072
	s_add_u32 s54, s82, 0x100000
	s_addc_u32 s55, s83, 0
	s_mov_b32 m0, s27
	v_lshl_add_u64 v[8:9], s[54:55], 0, v[158:159]
	ds_read_b128 v[192:195], v188 offset:32768
	ds_read_b128 v[196:199], v188 offset:33792
	ds_read_b128 v[210:213], v188 offset:34816
	ds_read_b128 v[214:217], v188 offset:35840
	ds_read_b128 v[218:221], v188 offset:36864
	ds_read_b128 v[222:225], v188 offset:37888
	ds_read_b128 v[226:229], v188 offset:38912
	ds_read_b128 v[230:233], v188 offset:39936
	global_load_lds_dwordx4 v[8:9], off
	v_lshl_add_u64 v[8:9], s[54:55], 0, v[166:167]
	s_mov_b32 m0, s38
	s_nop 0
	global_load_lds_dwordx4 v[8:9], off
	s_waitcnt vmcnt(8)
	s_waitcnt lgkmcnt(0)
	s_barrier
	s_setprio 1
	s_waitcnt lgkmcnt(0)
	v_mfma_f32_16x16x32_bf16 v[130:133], v[134:137], v[192:195], v[130:133]
	v_mfma_f32_16x16x32_bf16 v[126:129], v[142:145], v[192:195], v[126:129]
	v_mfma_f32_16x16x32_bf16 v[122:125], v[134:137], v[210:213], v[122:125]
	v_mfma_f32_16x16x32_bf16 v[118:121], v[142:145], v[210:213], v[118:121]
	v_mfma_f32_16x16x32_bf16 v[114:117], v[134:137], v[218:221], v[114:117]
	v_mfma_f32_16x16x32_bf16 v[110:113], v[142:145], v[218:221], v[110:113]
	v_mfma_f32_16x16x32_bf16 v[106:109], v[134:137], v[226:229], v[106:109]
	v_mfma_f32_16x16x32_bf16 v[102:105], v[142:145], v[226:229], v[102:105]
	v_mfma_f32_16x16x32_bf16 v[130:133], v[138:141], v[196:199], v[130:133]
	v_mfma_f32_16x16x32_bf16 v[126:129], v[146:149], v[196:199], v[126:129]
	v_mfma_f32_16x16x32_bf16 v[122:125], v[138:141], v[214:217], v[122:125]
	v_mfma_f32_16x16x32_bf16 v[118:121], v[146:149], v[214:217], v[118:121]
	v_mfma_f32_16x16x32_bf16 v[114:117], v[138:141], v[222:225], v[114:117]
	v_mfma_f32_16x16x32_bf16 v[110:113], v[146:149], v[222:225], v[110:113]
	v_mfma_f32_16x16x32_bf16 v[106:109], v[138:141], v[230:233], v[106:109]
	v_mfma_f32_16x16x32_bf16 v[102:105], v[146:149], v[230:233], v[102:105]
	s_setprio 0
	s_setprio 1
	v_mfma_f32_16x16x32_bf16 v[98:101], v[150:153], v[192:195], v[98:101]
	v_mfma_f32_16x16x32_bf16 v[94:97], v[178:181], v[192:195], v[94:97]
	v_mfma_f32_16x16x32_bf16 v[90:93], v[150:153], v[210:213], v[90:93]
	v_mfma_f32_16x16x32_bf16 v[86:89], v[178:181], v[210:213], v[86:89]
	v_mfma_f32_16x16x32_bf16 v[82:85], v[150:153], v[218:221], v[82:85]
	v_mfma_f32_16x16x32_bf16 v[78:81], v[178:181], v[218:221], v[78:81]
	v_mfma_f32_16x16x32_bf16 v[74:77], v[150:153], v[226:229], v[74:77]
	v_mfma_f32_16x16x32_bf16 v[70:73], v[178:181], v[226:229], v[70:73]
	v_mfma_f32_16x16x32_bf16 v[98:101], v[154:157], v[196:199], v[98:101]
	v_mfma_f32_16x16x32_bf16 v[94:97], v[182:185], v[196:199], v[94:97]
	v_mfma_f32_16x16x32_bf16 v[90:93], v[154:157], v[214:217], v[90:93]
	v_mfma_f32_16x16x32_bf16 v[86:89], v[182:185], v[214:217], v[86:89]
	v_mfma_f32_16x16x32_bf16 v[82:85], v[154:157], v[222:225], v[82:85]
	v_mfma_f32_16x16x32_bf16 v[78:81], v[182:185], v[222:225], v[78:81]
	v_mfma_f32_16x16x32_bf16 v[74:77], v[154:157], v[230:233], v[74:77]
	v_mfma_f32_16x16x32_bf16 v[70:73], v[182:185], v[230:233], v[70:73]
	s_setprio 0
	s_barrier
	s_add_i32 s51, s51, s20
	v_lshl_add_u64 v[8:9], v[234:235], 0, s[30:31]
	s_mov_b32 m0, s51
	ds_read_b128 v[192:195], v188 offset:49152
	ds_read_b128 v[196:199], v188 offset:50176
	ds_read_b128 v[210:213], v188 offset:51200
	ds_read_b128 v[214:217], v188 offset:52224
	ds_read_b128 v[218:221], v188 offset:53248
	ds_read_b128 v[222:225], v188 offset:54272
	ds_read_b128 v[226:229], v188 offset:55296
	ds_read_b128 v[230:233], v188 offset:56320
	global_load_lds_dwordx4 v[8:9], off
	s_add_i32 m0, s51, 0x2000
	s_add_u32 s54, s78, 0x100080
	v_lshl_add_u64 v[8:9], v[236:237], 0, s[30:31]
	s_addc_u32 s55, s79, 0
	s_add_i32 s51, s56, s20
	global_load_lds_dwordx4 v[8:9], off
	v_lshl_add_u64 v[8:9], s[54:55], 0, v[160:161]
	s_mov_b32 m0, s51
	s_nop 0
	global_load_lds_dwordx4 v[8:9], off
	v_lshl_add_u64 v[8:9], s[54:55], 0, v[168:169]
	s_add_i32 m0, s51, 0x2000
	s_nop 0
	global_load_lds_dwordx4 v[8:9], off
	v_lshl_add_u64 v[8:9], v[238:239], 0, s[30:31]
	s_mov_b32 m0, s75
	s_nop 0
	global_load_lds_dwordx4 v[8:9], off
	v_lshl_add_u64 v[8:9], v[240:241], 0, s[30:31]
	s_mov_b32 m0, s81
	s_nop 0
	global_load_lds_dwordx4 v[8:9], off
	s_waitcnt vmcnt(8)
	s_waitcnt lgkmcnt(0)
	s_barrier
	s_setprio 1
	s_waitcnt lgkmcnt(0)
	v_mfma_f32_16x16x32_bf16 v[66:69], v[134:137], v[192:195], v[66:69]
	v_mfma_f32_16x16x32_bf16 v[62:65], v[142:145], v[192:195], v[62:65]
	v_mfma_f32_16x16x32_bf16 v[58:61], v[134:137], v[210:213], v[58:61]
	v_mfma_f32_16x16x32_bf16 v[54:57], v[142:145], v[210:213], v[54:57]
	v_mfma_f32_16x16x32_bf16 v[50:53], v[134:137], v[218:221], v[50:53]
	v_mfma_f32_16x16x32_bf16 v[46:49], v[142:145], v[218:221], v[46:49]
	v_mfma_f32_16x16x32_bf16 v[42:45], v[134:137], v[226:229], v[42:45]
	v_mfma_f32_16x16x32_bf16 v[38:41], v[142:145], v[226:229], v[38:41]
	v_mfma_f32_16x16x32_bf16 v[66:69], v[138:141], v[196:199], v[66:69]
	v_mfma_f32_16x16x32_bf16 v[62:65], v[146:149], v[196:199], v[62:65]
	v_mfma_f32_16x16x32_bf16 v[58:61], v[138:141], v[214:217], v[58:61]
	v_mfma_f32_16x16x32_bf16 v[54:57], v[146:149], v[214:217], v[54:57]
	v_mfma_f32_16x16x32_bf16 v[50:53], v[138:141], v[222:225], v[50:53]
	v_mfma_f32_16x16x32_bf16 v[46:49], v[146:149], v[222:225], v[46:49]
	v_mfma_f32_16x16x32_bf16 v[42:45], v[138:141], v[230:233], v[42:45]
	v_mfma_f32_16x16x32_bf16 v[38:41], v[146:149], v[230:233], v[38:41]
	s_setprio 0
	s_setprio 1
	v_mfma_f32_16x16x32_bf16 v[34:37], v[150:153], v[192:195], v[34:37]
	v_mfma_f32_16x16x32_bf16 v[30:33], v[178:181], v[192:195], v[30:33]
	v_mfma_f32_16x16x32_bf16 v[26:29], v[150:153], v[210:213], v[26:29]
	v_mfma_f32_16x16x32_bf16 v[22:25], v[178:181], v[210:213], v[22:25]
	v_mfma_f32_16x16x32_bf16 v[18:21], v[150:153], v[218:221], v[18:21]
	v_mfma_f32_16x16x32_bf16 v[14:17], v[178:181], v[218:221], v[14:17]
	v_mfma_f32_16x16x32_bf16 v[8:11], v[150:153], v[226:229], v[10:13]
	v_mfma_f32_16x16x32_bf16 v[4:7], v[178:181], v[226:229], v[4:7]
	v_mfma_f32_16x16x32_bf16 v[34:37], v[154:157], v[196:199], v[34:37]
	v_mfma_f32_16x16x32_bf16 v[30:33], v[182:185], v[196:199], v[30:33]
	v_mfma_f32_16x16x32_bf16 v[26:29], v[154:157], v[214:217], v[26:29]
	v_mfma_f32_16x16x32_bf16 v[22:25], v[182:185], v[214:217], v[22:25]
	v_mfma_f32_16x16x32_bf16 v[18:21], v[154:157], v[222:225], v[18:21]
	v_mfma_f32_16x16x32_bf16 v[14:17], v[182:185], v[222:225], v[14:17]
	v_mfma_f32_16x16x32_bf16 v[10:13], v[154:157], v[230:233], v[8:11]
	v_mfma_f32_16x16x32_bf16 v[6:9], v[182:185], v[230:233], v[4:7]
	s_setprio 0
	s_barrier
	s_add_i32 s50, s50, 2
	s_add_u32 s76, s76, 0x100
	s_addc_u32 s77, s77, 0
	s_add_u32 s36, s36, 0x100
	s_addc_u32 s37, s37, 0
	s_cmp_gt_u32 s50, 29
	s_cbranch_scc0 .LBB0_1383
	s_cmp_eq_u32 s8, 0
	s_cselect_b64 s[76:77], -1, 0
	s_cmp_lg_u32 s8, 0
	s_cselect_b64 s[78:79], -1, 0
	s_or_b64 s[8:9], s[52:53], s[76:77]
	s_andn2_b64 vcc, exec, s[8:9]
	s_cbranch_vccz .LBB0_1386
	s_barrier

.LBB0_1631:
	ds_read_b128 v[150:153], v146
	ds_read_b128 v[154:157], v146 offset:1024
	ds_read_b128 v[158:161], v146 offset:2048
	ds_read_b128 v[166:169], v146 offset:3072
	ds_read_b128 v[170:173], v147
	ds_read_b128 v[174:177], v147 offset:1024
	ds_read_b128 v[178:181], v147 offset:2048
	ds_read_b128 v[182:185], v147 offset:3072
	s_add_u32 s50, s80, 0xfff00080
	s_addc_u32 s51, s81, -1
	s_cmp_eq_u32 s65, 12
	s_cselect_b32 s85, s54, s51
	s_cselect_b32 s84, s55, s50
	s_cselect_b32 s83, s59, s64
	s_cselect_b32 s82, s61, s63
	v_lshl_add_u64 v[198:199], s[80:81], 0, v[138:139]
	s_add_i32 m0, s15, 0xc000
	ds_read_b128 v[186:189], v148
	ds_read_b128 v[190:193], v148 offset:1024
	ds_read_b128 v[194:197], v148 offset:2048
	ds_read_b128 v[210:213], v148 offset:3072
	ds_read_b128 v[214:217], v148 offset:4096
	ds_read_b128 v[218:221], v148 offset:5120
	ds_read_b128 v[222:225], v148 offset:6144
	ds_read_b128 v[226:229], v148 offset:7168
	global_load_lds_dwordx4 v[198:199], off
	v_lshl_add_u64 v[198:199], s[80:81], 0, v[140:141]
	s_add_i32 m0, s15, 0xe000
	s_nop 0
	global_load_lds_dwordx4 v[198:199], off
	s_waitcnt vmcnt(8)
	s_waitcnt lgkmcnt(0)
	s_barrier
	s_setprio 1
	s_waitcnt lgkmcnt(0)
	v_mfma_f32_16x16x32_bf16 v[126:129], v[150:153], v[186:189], v[126:129]
	v_mfma_f32_16x16x32_bf16 v[122:125], v[158:161], v[186:189], v[122:125]
	v_mfma_f32_16x16x32_bf16 v[110:113], v[150:153], v[194:197], v[110:113]
	v_mfma_f32_16x16x32_bf16 v[106:109], v[158:161], v[194:197], v[106:109]
	v_mfma_f32_16x16x32_bf16 v[94:97], v[150:153], v[214:217], v[94:97]
	v_mfma_f32_16x16x32_bf16 v[90:93], v[158:161], v[214:217], v[90:93]
	v_mfma_f32_16x16x32_bf16 v[78:81], v[150:153], v[222:225], v[78:81]
	v_mfma_f32_16x16x32_bf16 v[74:77], v[158:161], v[222:225], v[74:77]
	v_mfma_f32_16x16x32_bf16 v[126:129], v[154:157], v[190:193], v[126:129]
	v_mfma_f32_16x16x32_bf16 v[122:125], v[166:169], v[190:193], v[122:125]
	v_mfma_f32_16x16x32_bf16 v[110:113], v[154:157], v[210:213], v[110:113]
	v_mfma_f32_16x16x32_bf16 v[106:109], v[166:169], v[210:213], v[106:109]
	v_mfma_f32_16x16x32_bf16 v[94:97], v[154:157], v[218:221], v[94:97]
	v_mfma_f32_16x16x32_bf16 v[90:93], v[166:169], v[218:221], v[90:93]
	v_mfma_f32_16x16x32_bf16 v[78:81], v[154:157], v[226:229], v[78:81]
	v_mfma_f32_16x16x32_bf16 v[74:77], v[166:169], v[226:229], v[74:77]
	s_setprio 0
	s_setprio 1
	v_mfma_f32_16x16x32_bf16 v[118:121], v[170:173], v[186:189], v[118:121]
	v_mfma_f32_16x16x32_bf16 v[114:117], v[178:181], v[186:189], v[114:117]
	v_mfma_f32_16x16x32_bf16 v[102:105], v[170:173], v[194:197], v[102:105]
	v_mfma_f32_16x16x32_bf16 v[98:101], v[178:181], v[194:197], v[98:101]
	v_mfma_f32_16x16x32_bf16 v[86:89], v[170:173], v[214:217], v[86:89]
	v_mfma_f32_16x16x32_bf16 v[82:85], v[178:181], v[214:217], v[82:85]
	v_mfma_f32_16x16x32_bf16 v[70:73], v[170:173], v[222:225], v[70:73]
	v_mfma_f32_16x16x32_bf16 v[66:69], v[178:181], v[222:225], v[66:69]
	v_mfma_f32_16x16x32_bf16 v[118:121], v[174:177], v[190:193], v[118:121]
	v_mfma_f32_16x16x32_bf16 v[114:117], v[182:185], v[190:193], v[114:117]
	v_mfma_f32_16x16x32_bf16 v[102:105], v[174:177], v[210:213], v[102:105]
	v_mfma_f32_16x16x32_bf16 v[98:101], v[182:185], v[210:213], v[98:101]
	v_mfma_f32_16x16x32_bf16 v[86:89], v[174:177], v[218:221], v[86:89]
	v_mfma_f32_16x16x32_bf16 v[82:85], v[182:185], v[218:221], v[82:85]
	v_mfma_f32_16x16x32_bf16 v[70:73], v[174:177], v[226:229], v[70:73]
	v_mfma_f32_16x16x32_bf16 v[66:69], v[182:185], v[226:229], v[66:69]
	s_setprio 0
	s_barrier
	s_add_i32 s50, s9, s14
	v_lshl_add_u64 v[198:199], s[82:83], 0, v[134:135]
	s_mov_b32 m0, s50
	ds_read_b128 v[186:189], v148 offset:16384
	ds_read_b128 v[190:193], v148 offset:17408
	ds_read_b128 v[194:197], v148 offset:18432
	ds_read_b128 v[210:213], v148 offset:19456
	ds_read_b128 v[214:217], v148 offset:20480
	ds_read_b128 v[218:221], v148 offset:21504
	ds_read_b128 v[222:225], v148 offset:22528
	ds_read_b128 v[226:229], v148 offset:23552
	global_load_lds_dwordx4 v[198:199], off
	s_add_i32 m0, s50, 0x2000
	s_add_u32 s50, s82, 0x100000
	v_lshl_add_u64 v[230:231], s[82:83], 0, v[130:131]
	s_addc_u32 s51, s83, 0
	s_add_i32 s56, s33, s14
	global_load_lds_dwordx4 v[230:231], off
	v_lshl_add_u64 v[232:233], s[50:51], 0, v[134:135]
	s_mov_b32 m0, s56
	v_lshl_add_u64 v[234:235], s[84:85], 0, v[132:133]
	global_load_lds_dwordx4 v[232:233], off
	v_lshl_add_u64 v[232:233], s[50:51], 0, v[130:131]
	s_add_i32 m0, s56, 0x2000
	s_nop 0
	global_load_lds_dwordx4 v[232:233], off
	v_lshl_add_u64 v[232:233], s[84:85], 0, v[136:137]
	s_mov_b32 m0, s15
	s_nop 0
	global_load_lds_dwordx4 v[232:233], off
	s_mov_b32 m0, s20
	s_nop 0
	global_load_lds_dwordx4 v[234:235], off
	s_waitcnt vmcnt(8)
	s_waitcnt lgkmcnt(0)
	s_barrier
	s_setprio 1
	s_waitcnt lgkmcnt(0)
	v_mfma_f32_16x16x32_bf16 v[62:65], v[150:153], v[186:189], v[62:65]
	v_mfma_f32_16x16x32_bf16 v[58:61], v[158:161], v[186:189], v[58:61]
	v_mfma_f32_16x16x32_bf16 v[46:49], v[150:153], v[194:197], v[46:49]
	v_mfma_f32_16x16x32_bf16 v[42:45], v[158:161], v[194:197], v[42:45]
	v_mfma_f32_16x16x32_bf16 v[30:33], v[150:153], v[214:217], v[30:33]
	v_mfma_f32_16x16x32_bf16 v[26:29], v[158:161], v[214:217], v[26:29]
	v_mfma_f32_16x16x32_bf16 v[14:17], v[150:153], v[222:225], v[14:17]
	v_mfma_f32_16x16x32_bf16 v[10:13], v[158:161], v[222:225], v[10:13]
	v_mfma_f32_16x16x32_bf16 v[62:65], v[154:157], v[190:193], v[62:65]
	v_mfma_f32_16x16x32_bf16 v[58:61], v[166:169], v[190:193], v[58:61]
	v_mfma_f32_16x16x32_bf16 v[46:49], v[154:157], v[210:213], v[46:49]
	v_mfma_f32_16x16x32_bf16 v[42:45], v[166:169], v[210:213], v[42:45]
	v_mfma_f32_16x16x32_bf16 v[30:33], v[154:157], v[218:221], v[30:33]
	v_mfma_f32_16x16x32_bf16 v[26:29], v[166:169], v[218:221], v[26:29]
	v_mfma_f32_16x16x32_bf16 v[14:17], v[154:157], v[226:229], v[14:17]
	v_mfma_f32_16x16x32_bf16 v[10:13], v[166:169], v[226:229], v[10:13]
	s_setprio 0
	s_setprio 1
	v_mfma_f32_16x16x32_bf16 v[54:57], v[170:173], v[186:189], v[54:57]
	v_mfma_f32_16x16x32_bf16 v[50:53], v[178:181], v[186:189], v[50:53]
	v_mfma_f32_16x16x32_bf16 v[38:41], v[170:173], v[194:197], v[38:41]
	v_mfma_f32_16x16x32_bf16 v[34:37], v[178:181], v[194:197], v[34:37]
	v_mfma_f32_16x16x32_bf16 v[22:25], v[170:173], v[214:217], v[22:25]
	v_mfma_f32_16x16x32_bf16 v[18:21], v[178:181], v[214:217], v[18:21]
	v_mfma_f32_16x16x32_bf16 v[6:9], v[170:173], v[222:225], v[6:9]
	v_mfma_f32_16x16x32_bf16 v[2:5], v[178:181], v[222:225], v[2:5]
	v_mfma_f32_16x16x32_bf16 v[54:57], v[174:177], v[190:193], v[54:57]
	v_mfma_f32_16x16x32_bf16 v[50:53], v[182:185], v[190:193], v[50:53]
	v_mfma_f32_16x16x32_bf16 v[38:41], v[174:177], v[210:213], v[38:41]
	v_mfma_f32_16x16x32_bf16 v[34:37], v[182:185], v[210:213], v[34:37]
	v_mfma_f32_16x16x32_bf16 v[22:25], v[174:177], v[218:221], v[22:25]
	v_mfma_f32_16x16x32_bf16 v[18:21], v[182:185], v[218:221], v[18:21]
	v_mfma_f32_16x16x32_bf16 v[6:9], v[174:177], v[226:229], v[6:9]
	v_mfma_f32_16x16x32_bf16 v[2:5], v[182:185], v[226:229], v[2:5]
	s_setprio 0
	s_barrier
	s_add_i32 s56, 0, 0x18000
	s_add_i32 s57, 0, 0x1c000
	v_add_u32_e32 v166, s56, v145
	v_add_u32_e32 v182, s57, v145
	ds_read_b128 v[150:153], v166
	ds_read_b128 v[154:157], v166 offset:1024
	ds_read_b128 v[158:161], v166 offset:2048
	ds_read_b128 v[166:169], v166 offset:3072
	ds_read_b128 v[170:173], v182
	ds_read_b128 v[174:177], v182 offset:1024
	ds_read_b128 v[178:181], v182 offset:2048
	ds_read_b128 v[182:185], v182 offset:3072
	s_add_u32 s50, s84, 0x100000
	s_addc_u32 s51, s85, 0
	s_mov_b32 m0, s21
	v_lshl_add_u64 v[236:237], s[50:51], 0, v[136:137]
	ds_read_b128 v[186:189], v148 offset:32768
	ds_read_b128 v[190:193], v148 offset:33792
	ds_read_b128 v[194:197], v148 offset:34816
	ds_read_b128 v[210:213], v148 offset:35840
	ds_read_b128 v[214:217], v148 offset:36864
	ds_read_b128 v[218:221], v148 offset:37888
	ds_read_b128 v[222:225], v148 offset:38912
	ds_read_b128 v[226:229], v148 offset:39936
	global_load_lds_dwordx4 v[236:237], off
	v_lshl_add_u64 v[236:237], s[50:51], 0, v[132:133]
	s_mov_b32 m0, s26
	s_nop 0
	global_load_lds_dwordx4 v[236:237], off
	s_waitcnt vmcnt(8)
	s_waitcnt lgkmcnt(0)
	s_barrier
	s_setprio 1
	s_waitcnt lgkmcnt(0)
	v_mfma_f32_16x16x32_bf16 v[126:129], v[150:153], v[186:189], v[126:129]
	v_mfma_f32_16x16x32_bf16 v[122:125], v[158:161], v[186:189], v[122:125]
	v_mfma_f32_16x16x32_bf16 v[110:113], v[150:153], v[194:197], v[110:113]
	v_mfma_f32_16x16x32_bf16 v[106:109], v[158:161], v[194:197], v[106:109]
	v_mfma_f32_16x16x32_bf16 v[94:97], v[150:153], v[214:217], v[94:97]
	v_mfma_f32_16x16x32_bf16 v[90:93], v[158:161], v[214:217], v[90:93]
	v_mfma_f32_16x16x32_bf16 v[78:81], v[150:153], v[222:225], v[78:81]
	v_mfma_f32_16x16x32_bf16 v[74:77], v[158:161], v[222:225], v[74:77]
	v_mfma_f32_16x16x32_bf16 v[126:129], v[154:157], v[190:193], v[126:129]
	v_mfma_f32_16x16x32_bf16 v[122:125], v[166:169], v[190:193], v[122:125]
	v_mfma_f32_16x16x32_bf16 v[110:113], v[154:157], v[210:213], v[110:113]
	v_mfma_f32_16x16x32_bf16 v[106:109], v[166:169], v[210:213], v[106:109]
	v_mfma_f32_16x16x32_bf16 v[94:97], v[154:157], v[218:221], v[94:97]
	v_mfma_f32_16x16x32_bf16 v[90:93], v[166:169], v[218:221], v[90:93]
	v_mfma_f32_16x16x32_bf16 v[78:81], v[154:157], v[226:229], v[78:81]
	v_mfma_f32_16x16x32_bf16 v[74:77], v[166:169], v[226:229], v[74:77]
	s_setprio 0
	s_setprio 1
	v_mfma_f32_16x16x32_bf16 v[118:121], v[170:173], v[186:189], v[118:121]
	v_mfma_f32_16x16x32_bf16 v[114:117], v[178:181], v[186:189], v[114:117]
	v_mfma_f32_16x16x32_bf16 v[102:105], v[170:173], v[194:197], v[102:105]
	v_mfma_f32_16x16x32_bf16 v[98:101], v[178:181], v[194:197], v[98:101]
	v_mfma_f32_16x16x32_bf16 v[86:89], v[170:173], v[214:217], v[86:89]
	v_mfma_f32_16x16x32_bf16 v[82:85], v[178:181], v[214:217], v[82:85]
	v_mfma_f32_16x16x32_bf16 v[70:73], v[170:173], v[222:225], v[70:73]
	v_mfma_f32_16x16x32_bf16 v[66:69], v[178:181], v[222:225], v[66:69]
	v_mfma_f32_16x16x32_bf16 v[118:121], v[174:177], v[190:193], v[118:121]
	v_mfma_f32_16x16x32_bf16 v[114:117], v[182:185], v[190:193], v[114:117]
	v_mfma_f32_16x16x32_bf16 v[102:105], v[174:177], v[210:213], v[102:105]
	v_mfma_f32_16x16x32_bf16 v[98:101], v[182:185], v[210:213], v[98:101]
	v_mfma_f32_16x16x32_bf16 v[86:89], v[174:177], v[218:221], v[86:89]
	v_mfma_f32_16x16x32_bf16 v[82:85], v[182:185], v[218:221], v[82:85]
	v_mfma_f32_16x16x32_bf16 v[70:73], v[174:177], v[226:229], v[70:73]
	v_mfma_f32_16x16x32_bf16 v[66:69], v[182:185], v[226:229], v[66:69]
	s_setprio 0
	s_barrier
	s_add_i32 s50, s56, s14
	v_lshl_add_u64 v[198:199], v[198:199], 0, s[6:7]
	s_mov_b32 m0, s50
	ds_read_b128 v[186:189], v148 offset:49152
	ds_read_b128 v[190:193], v148 offset:50176
	ds_read_b128 v[194:197], v148 offset:51200
	ds_read_b128 v[210:213], v148 offset:52224
	ds_read_b128 v[214:217], v148 offset:53248
	ds_read_b128 v[218:221], v148 offset:54272
	ds_read_b128 v[222:225], v148 offset:55296
	ds_read_b128 v[226:229], v148 offset:56320
	global_load_lds_dwordx4 v[198:199], off
	s_add_i32 m0, s50, 0x2000
	s_add_u32 s50, s82, 0x100080
	v_lshl_add_u64 v[198:199], v[230:231], 0, s[6:7]
	s_addc_u32 s51, s83, 0
	s_add_i32 s56, s57, s14
	global_load_lds_dwordx4 v[198:199], off
	v_lshl_add_u64 v[198:199], s[50:51], 0, v[134:135]
	s_mov_b32 m0, s56
	s_nop 0
	global_load_lds_dwordx4 v[198:199], off
	v_lshl_add_u64 v[198:199], s[50:51], 0, v[130:131]
	s_add_i32 m0, s56, 0x2000
	s_nop 0
	global_load_lds_dwordx4 v[198:199], off
	v_lshl_add_u64 v[198:199], v[232:233], 0, s[6:7]
	s_mov_b32 m0, s37
	s_nop 0
	global_load_lds_dwordx4 v[198:199], off
	v_lshl_add_u64 v[198:199], v[234:235], 0, s[6:7]
	s_mov_b32 m0, s38
	s_nop 0
	global_load_lds_dwordx4 v[198:199], off
	s_waitcnt vmcnt(8)
	s_waitcnt lgkmcnt(0)
	s_barrier
	s_setprio 1
	s_waitcnt lgkmcnt(0)
	v_mfma_f32_16x16x32_bf16 v[62:65], v[150:153], v[186:189], v[62:65]
	v_mfma_f32_16x16x32_bf16 v[58:61], v[158:161], v[186:189], v[58:61]
	v_mfma_f32_16x16x32_bf16 v[46:49], v[150:153], v[194:197], v[46:49]
	v_mfma_f32_16x16x32_bf16 v[42:45], v[158:161], v[194:197], v[42:45]
	v_mfma_f32_16x16x32_bf16 v[30:33], v[150:153], v[214:217], v[30:33]
	v_mfma_f32_16x16x32_bf16 v[26:29], v[158:161], v[214:217], v[26:29]
	v_mfma_f32_16x16x32_bf16 v[14:17], v[150:153], v[222:225], v[14:17]
	v_mfma_f32_16x16x32_bf16 v[10:13], v[158:161], v[222:225], v[10:13]
	v_mfma_f32_16x16x32_bf16 v[62:65], v[154:157], v[190:193], v[62:65]
	v_mfma_f32_16x16x32_bf16 v[58:61], v[166:169], v[190:193], v[58:61]
	v_mfma_f32_16x16x32_bf16 v[46:49], v[154:157], v[210:213], v[46:49]
	v_mfma_f32_16x16x32_bf16 v[42:45], v[166:169], v[210:213], v[42:45]
	v_mfma_f32_16x16x32_bf16 v[30:33], v[154:157], v[218:221], v[30:33]
	v_mfma_f32_16x16x32_bf16 v[26:29], v[166:169], v[218:221], v[26:29]
	v_mfma_f32_16x16x32_bf16 v[14:17], v[154:157], v[226:229], v[14:17]
	v_mfma_f32_16x16x32_bf16 v[10:13], v[166:169], v[226:229], v[10:13]
	s_setprio 0
	s_setprio 1
	v_mfma_f32_16x16x32_bf16 v[54:57], v[170:173], v[186:189], v[54:57]
	v_mfma_f32_16x16x32_bf16 v[50:53], v[178:181], v[186:189], v[50:53]
	v_mfma_f32_16x16x32_bf16 v[38:41], v[170:173], v[194:197], v[38:41]
	v_mfma_f32_16x16x32_bf16 v[34:37], v[178:181], v[194:197], v[34:37]
	v_mfma_f32_16x16x32_bf16 v[22:25], v[170:173], v[214:217], v[22:25]
	v_mfma_f32_16x16x32_bf16 v[18:21], v[178:181], v[214:217], v[18:21]
	v_mfma_f32_16x16x32_bf16 v[6:9], v[170:173], v[222:225], v[6:9]
	v_mfma_f32_16x16x32_bf16 v[2:5], v[178:181], v[222:225], v[2:5]
	v_mfma_f32_16x16x32_bf16 v[54:57], v[174:177], v[190:193], v[54:57]
	v_mfma_f32_16x16x32_bf16 v[50:53], v[182:185], v[190:193], v[50:53]
	v_mfma_f32_16x16x32_bf16 v[38:41], v[174:177], v[210:213], v[38:41]
	v_mfma_f32_16x16x32_bf16 v[34:37], v[182:185], v[210:213], v[34:37]
	v_mfma_f32_16x16x32_bf16 v[22:25], v[174:177], v[218:221], v[22:25]
	v_mfma_f32_16x16x32_bf16 v[18:21], v[182:185], v[218:221], v[18:21]
	v_mfma_f32_16x16x32_bf16 v[6:9], v[174:177], v[226:229], v[6:9]
	v_mfma_f32_16x16x32_bf16 v[2:5], v[182:185], v[226:229], v[2:5]
	s_setprio 0
	s_barrier
	s_add_i32 s65, s65, 2
	s_add_u32 s80, s80, 0x100
	s_addc_u32 s81, s81, 0
	s_add_u32 s63, s63, 0x100
	s_addc_u32 s64, s64, 0
	s_cmp_gt_u32 s65, 13
	s_cbranch_scc0 .LBB0_1631
	s_and_b64 vcc, exec, s[24:25]
	s_cbranch_vccz .LBB0_1634
	s_barrier

.LBB0_1934:
	ds_read_b128 v[130:133], v183
	ds_read_b128 v[134:137], v183 offset:1024
	ds_read_b128 v[138:141], v183 offset:2048
	ds_read_b128 v[142:145], v183 offset:3072
	ds_read_b128 v[146:149], v184
	ds_read_b128 v[150:153], v184 offset:1024
	ds_read_b128 v[176:179], v184 offset:2048
	ds_read_b128 v[188:191], v184 offset:3072
	s_add_u32 s50, s66, 0xfffe0080
	s_addc_u32 s51, s67, -1
	s_cmp_eq_u32 s59, 4
	s_cselect_b32 s71, s14, s51
	s_cselect_b32 s70, s15, s50
	s_cselect_b32 s69, s33, s57
	s_cselect_b32 s68, s36, s37
	v_lshl_add_u64 v[228:229], s[66:67], 0, v[168:169]
	s_add_i32 m0, s21, 0xc000
	ds_read_b128 v[192:195], v185
	ds_read_b128 v[196:199], v185 offset:1024
	ds_read_b128 v[204:207], v185 offset:2048
	ds_read_b128 v[208:211], v185 offset:3072
	ds_read_b128 v[212:215], v185 offset:4096
	ds_read_b128 v[216:219], v185 offset:5120
	ds_read_b128 v[220:223], v185 offset:6144
	ds_read_b128 v[224:227], v185 offset:7168
	global_load_lds_dwordx4 v[228:229], off
	v_lshl_add_u64 v[228:229], s[66:67], 0, v[170:171]
	s_add_i32 m0, s21, 0xe000
	s_nop 0
	global_load_lds_dwordx4 v[228:229], off
	s_waitcnt vmcnt(8)
	s_waitcnt lgkmcnt(0)
	s_barrier
	s_setprio 1
	s_waitcnt lgkmcnt(0)
	v_mfma_f32_16x16x32_bf16 v[126:129], v[130:133], v[192:195], v[126:129]
	v_mfma_f32_16x16x32_bf16 v[122:125], v[138:141], v[192:195], v[122:125]
	v_mfma_f32_16x16x32_bf16 v[110:113], v[130:133], v[204:207], v[110:113]
	v_mfma_f32_16x16x32_bf16 v[106:109], v[138:141], v[204:207], v[106:109]
	v_mfma_f32_16x16x32_bf16 v[94:97], v[130:133], v[212:215], v[94:97]
	v_mfma_f32_16x16x32_bf16 v[90:93], v[138:141], v[212:215], v[90:93]
	v_mfma_f32_16x16x32_bf16 v[78:81], v[130:133], v[220:223], v[78:81]
	v_mfma_f32_16x16x32_bf16 v[74:77], v[138:141], v[220:223], v[74:77]
	v_mfma_f32_16x16x32_bf16 v[126:129], v[134:137], v[196:199], v[126:129]
	v_mfma_f32_16x16x32_bf16 v[122:125], v[142:145], v[196:199], v[122:125]
	v_mfma_f32_16x16x32_bf16 v[110:113], v[134:137], v[208:211], v[110:113]
	v_mfma_f32_16x16x32_bf16 v[106:109], v[142:145], v[208:211], v[106:109]
	v_mfma_f32_16x16x32_bf16 v[94:97], v[134:137], v[216:219], v[94:97]
	v_mfma_f32_16x16x32_bf16 v[90:93], v[142:145], v[216:219], v[90:93]
	v_mfma_f32_16x16x32_bf16 v[78:81], v[134:137], v[224:227], v[78:81]
	v_mfma_f32_16x16x32_bf16 v[74:77], v[142:145], v[224:227], v[74:77]
	s_setprio 0
	s_setprio 1
	v_mfma_f32_16x16x32_bf16 v[118:121], v[146:149], v[192:195], v[118:121]
	v_mfma_f32_16x16x32_bf16 v[114:117], v[176:179], v[192:195], v[114:117]
	v_mfma_f32_16x16x32_bf16 v[102:105], v[146:149], v[204:207], v[102:105]
	v_mfma_f32_16x16x32_bf16 v[98:101], v[176:179], v[204:207], v[98:101]
	v_mfma_f32_16x16x32_bf16 v[86:89], v[146:149], v[212:215], v[86:89]
	v_mfma_f32_16x16x32_bf16 v[82:85], v[176:179], v[212:215], v[82:85]
	v_mfma_f32_16x16x32_bf16 v[70:73], v[146:149], v[220:223], v[70:73]
	v_mfma_f32_16x16x32_bf16 v[66:69], v[176:179], v[220:223], v[66:69]
	v_mfma_f32_16x16x32_bf16 v[118:121], v[150:153], v[196:199], v[118:121]
	v_mfma_f32_16x16x32_bf16 v[114:117], v[188:191], v[196:199], v[114:117]
	v_mfma_f32_16x16x32_bf16 v[102:105], v[150:153], v[208:211], v[102:105]
	v_mfma_f32_16x16x32_bf16 v[98:101], v[188:191], v[208:211], v[98:101]
	v_mfma_f32_16x16x32_bf16 v[86:89], v[150:153], v[216:219], v[86:89]
	v_mfma_f32_16x16x32_bf16 v[82:85], v[188:191], v[216:219], v[82:85]
	v_mfma_f32_16x16x32_bf16 v[70:73], v[150:153], v[224:227], v[70:73]
	v_mfma_f32_16x16x32_bf16 v[66:69], v[188:191], v[224:227], v[66:69]
	s_setprio 0
	s_barrier
	s_add_i32 s50, s76, s20
	v_lshl_add_u64 v[228:229], s[68:69], 0, v[156:157]
	s_mov_b32 m0, s50
	ds_read_b128 v[192:195], v185 offset:16384
	ds_read_b128 v[196:199], v185 offset:17408
	ds_read_b128 v[204:207], v185 offset:18432
	ds_read_b128 v[208:211], v185 offset:19456
	ds_read_b128 v[212:215], v185 offset:20480
	ds_read_b128 v[216:219], v185 offset:21504
	ds_read_b128 v[220:223], v185 offset:22528
	ds_read_b128 v[224:227], v185 offset:23552
	global_load_lds_dwordx4 v[228:229], off
	s_add_i32 m0, s50, 0x2000
	s_add_u32 s50, s68, 0x20000
	v_lshl_add_u64 v[230:231], s[68:69], 0, v[160:161]
	s_addc_u32 s51, s69, 0
	s_add_i32 s79, s77, s20
	global_load_lds_dwordx4 v[230:231], off
	v_lshl_add_u64 v[232:233], s[50:51], 0, v[156:157]
	s_mov_b32 m0, s79
	v_lshl_add_u64 v[234:235], s[70:71], 0, v[158:159]
	global_load_lds_dwordx4 v[232:233], off
	v_lshl_add_u64 v[232:233], s[50:51], 0, v[160:161]
	s_add_i32 m0, s79, 0x2000
	s_nop 0
	global_load_lds_dwordx4 v[232:233], off
	v_lshl_add_u64 v[232:233], s[70:71], 0, v[154:155]
	s_mov_b32 m0, s21
	s_nop 0
	global_load_lds_dwordx4 v[232:233], off
	s_mov_b32 m0, s23
	s_nop 0
	global_load_lds_dwordx4 v[234:235], off
	s_waitcnt vmcnt(8)
	s_waitcnt lgkmcnt(0)
	s_barrier
	s_setprio 1
	s_waitcnt lgkmcnt(0)
	v_mfma_f32_16x16x32_bf16 v[62:65], v[130:133], v[192:195], v[62:65]
	v_mfma_f32_16x16x32_bf16 v[58:61], v[138:141], v[192:195], v[58:61]
	v_mfma_f32_16x16x32_bf16 v[46:49], v[130:133], v[204:207], v[46:49]
	v_mfma_f32_16x16x32_bf16 v[42:45], v[138:141], v[204:207], v[42:45]
	v_mfma_f32_16x16x32_bf16 v[30:33], v[130:133], v[212:215], v[30:33]
	v_mfma_f32_16x16x32_bf16 v[26:29], v[138:141], v[212:215], v[26:29]
	v_mfma_f32_16x16x32_bf16 v[14:17], v[130:133], v[220:223], v[14:17]
	v_mfma_f32_16x16x32_bf16 v[10:13], v[138:141], v[220:223], v[10:13]
	v_mfma_f32_16x16x32_bf16 v[62:65], v[134:137], v[196:199], v[62:65]
	v_mfma_f32_16x16x32_bf16 v[58:61], v[142:145], v[196:199], v[58:61]
	v_mfma_f32_16x16x32_bf16 v[46:49], v[134:137], v[208:211], v[46:49]
	v_mfma_f32_16x16x32_bf16 v[42:45], v[142:145], v[208:211], v[42:45]
	v_mfma_f32_16x16x32_bf16 v[30:33], v[134:137], v[216:219], v[30:33]
	v_mfma_f32_16x16x32_bf16 v[26:29], v[142:145], v[216:219], v[26:29]
	v_mfma_f32_16x16x32_bf16 v[14:17], v[134:137], v[224:227], v[14:17]
	v_mfma_f32_16x16x32_bf16 v[10:13], v[142:145], v[224:227], v[10:13]
	s_setprio 0
	s_setprio 1
	v_mfma_f32_16x16x32_bf16 v[54:57], v[146:149], v[192:195], v[54:57]
	v_mfma_f32_16x16x32_bf16 v[50:53], v[176:179], v[192:195], v[50:53]
	v_mfma_f32_16x16x32_bf16 v[38:41], v[146:149], v[204:207], v[38:41]
	v_mfma_f32_16x16x32_bf16 v[34:37], v[176:179], v[204:207], v[34:37]
	v_mfma_f32_16x16x32_bf16 v[22:25], v[146:149], v[212:215], v[22:25]
	v_mfma_f32_16x16x32_bf16 v[18:21], v[176:179], v[212:215], v[18:21]
	v_mfma_f32_16x16x32_bf16 v[6:9], v[146:149], v[220:223], v[6:9]
	v_mfma_f32_16x16x32_bf16 v[2:5], v[176:179], v[220:223], v[2:5]
	v_mfma_f32_16x16x32_bf16 v[54:57], v[150:153], v[196:199], v[54:57]
	v_mfma_f32_16x16x32_bf16 v[50:53], v[188:191], v[196:199], v[50:53]
	v_mfma_f32_16x16x32_bf16 v[38:41], v[150:153], v[208:211], v[38:41]
	v_mfma_f32_16x16x32_bf16 v[34:37], v[188:191], v[208:211], v[34:37]
	v_mfma_f32_16x16x32_bf16 v[22:25], v[150:153], v[216:219], v[22:25]
	v_mfma_f32_16x16x32_bf16 v[18:21], v[188:191], v[216:219], v[18:21]
	v_mfma_f32_16x16x32_bf16 v[6:9], v[150:153], v[224:227], v[6:9]
	v_mfma_f32_16x16x32_bf16 v[2:5], v[188:191], v[224:227], v[2:5]
	s_setprio 0
	s_barrier
	s_add_i32 s79, 0, 0x18000
	s_add_i32 s80, 0, 0x1c000
	v_add_u32_e32 v142, s79, v181
	v_add_u32_e32 v166, s80, v181
	ds_read_b128 v[130:133], v142
	ds_read_b128 v[134:137], v142 offset:1024
	ds_read_b128 v[138:141], v142 offset:2048
	ds_read_b128 v[142:145], v142 offset:3072
	ds_read_b128 v[146:149], v166
	ds_read_b128 v[150:153], v166 offset:1024
	ds_read_b128 v[176:179], v166 offset:2048
	ds_read_b128 v[188:191], v166 offset:3072
	s_add_u32 s50, s70, 0x20000
	s_addc_u32 s51, s71, 0
	s_mov_b32 m0, s26
	v_lshl_add_u64 v[236:237], s[50:51], 0, v[154:155]
	ds_read_b128 v[192:195], v185 offset:32768
	ds_read_b128 v[196:199], v185 offset:33792
	ds_read_b128 v[204:207], v185 offset:34816
	ds_read_b128 v[208:211], v185 offset:35840
	ds_read_b128 v[212:215], v185 offset:36864
	ds_read_b128 v[216:219], v185 offset:37888
	ds_read_b128 v[220:223], v185 offset:38912
	ds_read_b128 v[224:227], v185 offset:39936
	global_load_lds_dwordx4 v[236:237], off
	v_lshl_add_u64 v[236:237], s[50:51], 0, v[158:159]
	s_mov_b32 m0, s27
	s_nop 0
	global_load_lds_dwordx4 v[236:237], off
	s_waitcnt vmcnt(8)
	s_waitcnt lgkmcnt(0)
	s_barrier
	s_setprio 1
	s_waitcnt lgkmcnt(0)
	v_mfma_f32_16x16x32_bf16 v[126:129], v[130:133], v[192:195], v[126:129]
	v_mfma_f32_16x16x32_bf16 v[122:125], v[138:141], v[192:195], v[122:125]
	v_mfma_f32_16x16x32_bf16 v[110:113], v[130:133], v[204:207], v[110:113]
	v_mfma_f32_16x16x32_bf16 v[106:109], v[138:141], v[204:207], v[106:109]
	v_mfma_f32_16x16x32_bf16 v[94:97], v[130:133], v[212:215], v[94:97]
	v_mfma_f32_16x16x32_bf16 v[90:93], v[138:141], v[212:215], v[90:93]
	v_mfma_f32_16x16x32_bf16 v[78:81], v[130:133], v[220:223], v[78:81]
	v_mfma_f32_16x16x32_bf16 v[74:77], v[138:141], v[220:223], v[74:77]
	v_mfma_f32_16x16x32_bf16 v[126:129], v[134:137], v[196:199], v[126:129]
	v_mfma_f32_16x16x32_bf16 v[122:125], v[142:145], v[196:199], v[122:125]
	v_mfma_f32_16x16x32_bf16 v[110:113], v[134:137], v[208:211], v[110:113]
	v_mfma_f32_16x16x32_bf16 v[106:109], v[142:145], v[208:211], v[106:109]
	v_mfma_f32_16x16x32_bf16 v[94:97], v[134:137], v[216:219], v[94:97]
	v_mfma_f32_16x16x32_bf16 v[90:93], v[142:145], v[216:219], v[90:93]
	v_mfma_f32_16x16x32_bf16 v[78:81], v[134:137], v[224:227], v[78:81]
	v_mfma_f32_16x16x32_bf16 v[74:77], v[142:145], v[224:227], v[74:77]
	s_setprio 0
	s_setprio 1
	v_mfma_f32_16x16x32_bf16 v[118:121], v[146:149], v[192:195], v[118:121]
	v_mfma_f32_16x16x32_bf16 v[114:117], v[176:179], v[192:195], v[114:117]
	v_mfma_f32_16x16x32_bf16 v[102:105], v[146:149], v[204:207], v[102:105]
	v_mfma_f32_16x16x32_bf16 v[98:101], v[176:179], v[204:207], v[98:101]
	v_mfma_f32_16x16x32_bf16 v[86:89], v[146:149], v[212:215], v[86:89]
	v_mfma_f32_16x16x32_bf16 v[82:85], v[176:179], v[212:215], v[82:85]
	v_mfma_f32_16x16x32_bf16 v[70:73], v[146:149], v[220:223], v[70:73]
	v_mfma_f32_16x16x32_bf16 v[66:69], v[176:179], v[220:223], v[66:69]
	v_mfma_f32_16x16x32_bf16 v[118:121], v[150:153], v[196:199], v[118:121]
	v_mfma_f32_16x16x32_bf16 v[114:117], v[188:191], v[196:199], v[114:117]
	v_mfma_f32_16x16x32_bf16 v[102:105], v[150:153], v[208:211], v[102:105]
	v_mfma_f32_16x16x32_bf16 v[98:101], v[188:191], v[208:211], v[98:101]
	v_mfma_f32_16x16x32_bf16 v[86:89], v[150:153], v[216:219], v[86:89]
	v_mfma_f32_16x16x32_bf16 v[82:85], v[188:191], v[216:219], v[82:85]
	v_mfma_f32_16x16x32_bf16 v[70:73], v[150:153], v[224:227], v[70:73]
	v_mfma_f32_16x16x32_bf16 v[66:69], v[188:191], v[224:227], v[66:69]
	s_setprio 0
	s_barrier
	s_add_i32 s50, s79, s20
	v_lshl_add_u64 v[228:229], v[228:229], 0, s[52:53]
	s_mov_b32 m0, s50
	ds_read_b128 v[192:195], v185 offset:49152
	ds_read_b128 v[196:199], v185 offset:50176
	ds_read_b128 v[204:207], v185 offset:51200
	ds_read_b128 v[208:211], v185 offset:52224
	ds_read_b128 v[212:215], v185 offset:53248
	ds_read_b128 v[216:219], v185 offset:54272
	ds_read_b128 v[220:223], v185 offset:55296
	ds_read_b128 v[224:227], v185 offset:56320
	global_load_lds_dwordx4 v[228:229], off
	s_add_i32 m0, s50, 0x2000
	s_add_u32 s50, s68, 0x20080
	v_lshl_add_u64 v[228:229], v[230:231], 0, s[52:53]
	s_addc_u32 s51, s69, 0
	s_add_i32 s68, s80, s20
	global_load_lds_dwordx4 v[228:229], off
	v_lshl_add_u64 v[228:229], s[50:51], 0, v[156:157]
	s_mov_b32 m0, s68
	s_nop 0
	global_load_lds_dwordx4 v[228:229], off
	v_lshl_add_u64 v[228:229], s[50:51], 0, v[160:161]
	s_add_i32 m0, s68, 0x2000
	s_nop 0
	global_load_lds_dwordx4 v[228:229], off
	v_lshl_add_u64 v[228:229], v[232:233], 0, s[52:53]
	s_mov_b32 m0, s65
	s_nop 0
	global_load_lds_dwordx4 v[228:229], off
	v_lshl_add_u64 v[228:229], v[234:235], 0, s[52:53]
	s_mov_b32 m0, s72
	s_nop 0
	global_load_lds_dwordx4 v[228:229], off
	s_waitcnt vmcnt(8)
	s_waitcnt lgkmcnt(0)
	s_barrier
	s_setprio 1
	s_waitcnt lgkmcnt(0)
	v_mfma_f32_16x16x32_bf16 v[62:65], v[130:133], v[192:195], v[62:65]
	v_mfma_f32_16x16x32_bf16 v[58:61], v[138:141], v[192:195], v[58:61]
	v_mfma_f32_16x16x32_bf16 v[46:49], v[130:133], v[204:207], v[46:49]
	v_mfma_f32_16x16x32_bf16 v[42:45], v[138:141], v[204:207], v[42:45]
	v_mfma_f32_16x16x32_bf16 v[30:33], v[130:133], v[212:215], v[30:33]
	v_mfma_f32_16x16x32_bf16 v[26:29], v[138:141], v[212:215], v[26:29]
	v_mfma_f32_16x16x32_bf16 v[14:17], v[130:133], v[220:223], v[14:17]
	v_mfma_f32_16x16x32_bf16 v[10:13], v[138:141], v[220:223], v[10:13]
	v_mfma_f32_16x16x32_bf16 v[62:65], v[134:137], v[196:199], v[62:65]
	v_mfma_f32_16x16x32_bf16 v[58:61], v[142:145], v[196:199], v[58:61]
	v_mfma_f32_16x16x32_bf16 v[46:49], v[134:137], v[208:211], v[46:49]
	v_mfma_f32_16x16x32_bf16 v[42:45], v[142:145], v[208:211], v[42:45]
	v_mfma_f32_16x16x32_bf16 v[30:33], v[134:137], v[216:219], v[30:33]
	v_mfma_f32_16x16x32_bf16 v[26:29], v[142:145], v[216:219], v[26:29]
	v_mfma_f32_16x16x32_bf16 v[14:17], v[134:137], v[224:227], v[14:17]
	v_mfma_f32_16x16x32_bf16 v[10:13], v[142:145], v[224:227], v[10:13]
	s_setprio 0
	s_setprio 1
	v_mfma_f32_16x16x32_bf16 v[54:57], v[146:149], v[192:195], v[54:57]
	v_mfma_f32_16x16x32_bf16 v[50:53], v[176:179], v[192:195], v[50:53]
	v_mfma_f32_16x16x32_bf16 v[38:41], v[146:149], v[204:207], v[38:41]
	v_mfma_f32_16x16x32_bf16 v[34:37], v[176:179], v[204:207], v[34:37]
	v_mfma_f32_16x16x32_bf16 v[22:25], v[146:149], v[212:215], v[22:25]
	v_mfma_f32_16x16x32_bf16 v[18:21], v[176:179], v[212:215], v[18:21]
	v_mfma_f32_16x16x32_bf16 v[6:9], v[146:149], v[220:223], v[6:9]
	v_mfma_f32_16x16x32_bf16 v[2:5], v[176:179], v[220:223], v[2:5]
	v_mfma_f32_16x16x32_bf16 v[54:57], v[150:153], v[196:199], v[54:57]
	v_mfma_f32_16x16x32_bf16 v[50:53], v[188:191], v[196:199], v[50:53]
	v_mfma_f32_16x16x32_bf16 v[38:41], v[150:153], v[208:211], v[38:41]
	v_mfma_f32_16x16x32_bf16 v[34:37], v[188:191], v[208:211], v[34:37]
	v_mfma_f32_16x16x32_bf16 v[22:25], v[150:153], v[216:219], v[22:25]
	v_mfma_f32_16x16x32_bf16 v[18:21], v[188:191], v[216:219], v[18:21]
	v_mfma_f32_16x16x32_bf16 v[6:9], v[150:153], v[224:227], v[6:9]
	v_mfma_f32_16x16x32_bf16 v[2:5], v[188:191], v[224:227], v[2:5]
	s_setprio 0
	s_barrier
	s_add_i32 s59, s59, 2
	s_add_u32 s66, s66, 0x100
	s_addc_u32 s67, s67, 0
	s_add_u32 s37, s37, 0x100
	s_addc_u32 s57, s57, 0
	s_cmp_gt_u32 s59, 5
	s_cbranch_scc0 .LBB0_1934
	s_and_b64 vcc, exec, s[54:55]
	s_cbranch_vccz .LBB0_1937
	s_barrier

.LBB0_2171:
	ds_read_b128 v[18:21], v193
	ds_read_b128 v[22:25], v193 offset:1024
	ds_read_b128 v[26:29], v193 offset:2048
	ds_read_b128 v[30:33], v193 offset:3072
	ds_read_b128 v[2:5], v194
	ds_read_b128 v[6:9], v194 offset:1024
	ds_read_b128 v[10:13], v194 offset:2048
	ds_read_b128 v[14:17], v194 offset:3072
	s_add_u32 s58, s56, 0xfff80080
	s_addc_u32 s59, s57, -1
	s_cmp_eq_u32 s72, 28
	s_cselect_b32 s61, s49, s59
	s_cselect_b32 s60, s68, s58
	s_cselect_b32 s59, s31, s71
	s_cselect_b32 s58, s69, s70
	v_lshl_add_u64 v[198:199], s[56:57], 0, v[174:175]
	s_add_i32 m0, s37, 0xc000
	ds_read_b128 v[182:185], v195
	ds_read_b128 v[186:189], v195 offset:1024
	ds_read_b128 v[204:207], v195 offset:2048
	ds_read_b128 v[208:211], v195 offset:3072
	ds_read_b128 v[212:215], v195 offset:4096
	ds_read_b128 v[216:219], v195 offset:5120
	ds_read_b128 v[220:223], v195 offset:6144
	ds_read_b128 v[224:227], v195 offset:7168
	global_load_lds_dwordx4 v[198:199], off
	v_lshl_add_u64 v[198:199], s[56:57], 0, v[176:177]
	s_add_i32 m0, s37, 0xe000
	s_nop 0
	global_load_lds_dwordx4 v[198:199], off
	s_waitcnt vmcnt(8)
	s_waitcnt lgkmcnt(0)
	s_barrier
	s_setprio 1
	s_waitcnt lgkmcnt(0)
	v_mfma_scale_f32_16x16x128_f8f6f4 v[158:161], v[18:25], v[182:189], v[158:161], v196, v196 op_sel_hi:[0,0,0]
	v_mfma_scale_f32_16x16x128_f8f6f4 v[154:157], v[26:33], v[182:189], v[154:157], v196, v196 op_sel_hi:[0,0,0]
	v_mfma_scale_f32_16x16x128_f8f6f4 v[142:145], v[18:25], v[204:211], v[142:145], v196, v196 op_sel_hi:[0,0,0]
	v_mfma_scale_f32_16x16x128_f8f6f4 v[138:141], v[26:33], v[204:211], v[138:141], v196, v196 op_sel_hi:[0,0,0]
	v_mfma_scale_f32_16x16x128_f8f6f4 v[126:129], v[18:25], v[212:219], v[126:129], v196, v196 op_sel_hi:[0,0,0]
	v_mfma_scale_f32_16x16x128_f8f6f4 v[122:125], v[26:33], v[212:219], v[122:125], v196, v196 op_sel_hi:[0,0,0]
	v_mfma_scale_f32_16x16x128_f8f6f4 v[110:113], v[18:25], v[220:227], v[110:113], v196, v196 op_sel_hi:[0,0,0]
	v_mfma_scale_f32_16x16x128_f8f6f4 v[106:109], v[26:33], v[220:227], v[106:109], v196, v196 op_sel_hi:[0,0,0]
	s_setprio 0
	s_setprio 1
	v_mfma_scale_f32_16x16x128_f8f6f4 v[150:153], v[2:9], v[182:189], v[150:153], v196, v196 op_sel_hi:[0,0,0]
	v_mfma_scale_f32_16x16x128_f8f6f4 v[146:149], v[10:17], v[182:189], v[146:149], v196, v196 op_sel_hi:[0,0,0]
	v_mfma_scale_f32_16x16x128_f8f6f4 v[134:137], v[2:9], v[204:211], v[134:137], v196, v196 op_sel_hi:[0,0,0]
	v_mfma_scale_f32_16x16x128_f8f6f4 v[130:133], v[10:17], v[204:211], v[130:133], v196, v196 op_sel_hi:[0,0,0]
	v_mfma_scale_f32_16x16x128_f8f6f4 v[118:121], v[2:9], v[212:219], v[118:121], v196, v196 op_sel_hi:[0,0,0]
	v_mfma_scale_f32_16x16x128_f8f6f4 v[114:117], v[10:17], v[212:219], v[114:117], v196, v196 op_sel_hi:[0,0,0]
	v_mfma_scale_f32_16x16x128_f8f6f4 v[102:105], v[2:9], v[220:227], v[102:105], v196, v196 op_sel_hi:[0,0,0]
	v_mfma_scale_f32_16x16x128_f8f6f4 v[98:101], v[10:17], v[220:227], v[98:101], v196, v196 op_sel_hi:[0,0,0]
	s_setprio 0
	s_barrier
	s_add_i32 s73, s15, s20
	v_lshl_add_u64 v[182:183], s[58:59], 0, v[170:171]
	s_mov_b32 m0, s73
	ds_read_b128 v[204:207], v195 offset:16384
	ds_read_b128 v[208:211], v195 offset:17408
	ds_read_b128 v[212:215], v195 offset:18432
	ds_read_b128 v[216:219], v195 offset:19456
	ds_read_b128 v[220:223], v195 offset:20480
	ds_read_b128 v[224:227], v195 offset:21504
	ds_read_b128 v[228:231], v195 offset:22528
	ds_read_b128 v[232:235], v195 offset:23552
	global_load_lds_dwordx4 v[182:183], off
	s_add_i32 m0, s73, 0x2000
	s_add_u32 s74, s58, 0x80000
	v_lshl_add_u64 v[184:185], s[58:59], 0, v[166:167]
	s_addc_u32 s75, s59, 0
	s_add_i32 s73, s65, s20
	global_load_lds_dwordx4 v[184:185], off
	v_lshl_add_u64 v[186:187], s[74:75], 0, v[170:171]
	s_mov_b32 m0, s73
	v_lshl_add_u64 v[188:189], s[60:61], 0, v[168:169]
	global_load_lds_dwordx4 v[186:187], off
	v_lshl_add_u64 v[186:187], s[74:75], 0, v[166:167]
	s_add_i32 m0, s73, 0x2000
	s_nop 0
	global_load_lds_dwordx4 v[186:187], off
	v_lshl_add_u64 v[186:187], s[60:61], 0, v[172:173]
	s_mov_b32 m0, s37
	s_nop 0
	global_load_lds_dwordx4 v[186:187], off
	s_mov_b32 m0, s38
	s_nop 0
	global_load_lds_dwordx4 v[188:189], off
	s_waitcnt vmcnt(8)
	s_waitcnt lgkmcnt(0)
	s_barrier
	s_setprio 1
	s_waitcnt lgkmcnt(0)
	v_mfma_scale_f32_16x16x128_f8f6f4 v[94:97], v[18:25], v[204:211], v[94:97], v196, v196 op_sel_hi:[0,0,0]
	v_mfma_scale_f32_16x16x128_f8f6f4 v[90:93], v[26:33], v[204:211], v[90:93], v196, v196 op_sel_hi:[0,0,0]
	v_mfma_scale_f32_16x16x128_f8f6f4 v[78:81], v[18:25], v[212:219], v[78:81], v196, v196 op_sel_hi:[0,0,0]
	v_mfma_scale_f32_16x16x128_f8f6f4 v[74:77], v[26:33], v[212:219], v[74:77], v196, v196 op_sel_hi:[0,0,0]
	v_mfma_scale_f32_16x16x128_f8f6f4 v[62:65], v[18:25], v[220:227], v[62:65], v196, v196 op_sel_hi:[0,0,0]
	v_mfma_scale_f32_16x16x128_f8f6f4 v[58:61], v[26:33], v[220:227], v[58:61], v196, v196 op_sel_hi:[0,0,0]
	v_mfma_scale_f32_16x16x128_f8f6f4 v[46:49], v[18:25], v[228:235], v[46:49], v196, v196 op_sel_hi:[0,0,0]
	v_mfma_scale_f32_16x16x128_f8f6f4 v[42:45], v[26:33], v[228:235], v[42:45], v196, v196 op_sel_hi:[0,0,0]
	s_setprio 0
	s_setprio 1
	v_mfma_scale_f32_16x16x128_f8f6f4 v[86:89], v[2:9], v[204:211], v[86:89], v196, v196 op_sel_hi:[0,0,0]
	v_mfma_scale_f32_16x16x128_f8f6f4 v[82:85], v[10:17], v[204:211], v[82:85], v196, v196 op_sel_hi:[0,0,0]
	v_mfma_scale_f32_16x16x128_f8f6f4 v[70:73], v[2:9], v[212:219], v[70:73], v196, v196 op_sel_hi:[0,0,0]
	v_mfma_scale_f32_16x16x128_f8f6f4 v[66:69], v[10:17], v[212:219], v[66:69], v196, v196 op_sel_hi:[0,0,0]
	v_mfma_scale_f32_16x16x128_f8f6f4 v[54:57], v[2:9], v[220:227], v[54:57], v196, v196 op_sel_hi:[0,0,0]
	v_mfma_scale_f32_16x16x128_f8f6f4 v[50:53], v[10:17], v[220:227], v[50:53], v196, v196 op_sel_hi:[0,0,0]
	v_mfma_scale_f32_16x16x128_f8f6f4 v[38:41], v[2:9], v[228:235], v[38:41], v196, v196 op_sel_hi:[0,0,0]
	v_mfma_scale_f32_16x16x128_f8f6f4 v[34:37], v[10:17], v[228:235], v[34:37], v196, v196 op_sel_hi:[0,0,0]
	s_setprio 0
	s_barrier
	s_add_i32 s73, 0, 0x18000
	s_add_i32 s74, 0, 0x1c000
	v_add_u32_e32 v14, s73, v191
	v_add_u32_e32 v30, s74, v191
	ds_read_b128 v[2:5], v14
	ds_read_b128 v[6:9], v14 offset:1024
	ds_read_b128 v[10:13], v14 offset:2048
	ds_read_b128 v[14:17], v14 offset:3072
	ds_read_b128 v[18:21], v30
	ds_read_b128 v[22:25], v30 offset:1024
	ds_read_b128 v[26:29], v30 offset:2048
	ds_read_b128 v[30:33], v30 offset:3072
	s_add_u32 s60, s60, 0x80000
	s_addc_u32 s61, s61, 0
	s_mov_b32 m0, s39
	v_lshl_add_u64 v[198:199], s[60:61], 0, v[172:173]
	ds_read_b128 v[204:207], v195 offset:32768
	ds_read_b128 v[208:211], v195 offset:33792
	ds_read_b128 v[212:215], v195 offset:34816
	ds_read_b128 v[216:219], v195 offset:35840
	ds_read_b128 v[220:223], v195 offset:36864
	ds_read_b128 v[224:227], v195 offset:37888
	ds_read_b128 v[228:231], v195 offset:38912
	ds_read_b128 v[232:235], v195 offset:39936
	global_load_lds_dwordx4 v[198:199], off
	v_lshl_add_u64 v[198:199], s[60:61], 0, v[168:169]
	s_mov_b32 m0, s55
	s_nop 0
	global_load_lds_dwordx4 v[198:199], off
	s_waitcnt vmcnt(8)
	s_waitcnt lgkmcnt(0)
	s_barrier
	s_setprio 1
	s_waitcnt lgkmcnt(0)
	v_mfma_scale_f32_16x16x128_f8f6f4 v[158:161], v[2:9], v[204:211], v[158:161], v196, v196 op_sel_hi:[0,0,0]
	v_mfma_scale_f32_16x16x128_f8f6f4 v[154:157], v[10:17], v[204:211], v[154:157], v196, v196 op_sel_hi:[0,0,0]
	v_mfma_scale_f32_16x16x128_f8f6f4 v[142:145], v[2:9], v[212:219], v[142:145], v196, v196 op_sel_hi:[0,0,0]
	v_mfma_scale_f32_16x16x128_f8f6f4 v[138:141], v[10:17], v[212:219], v[138:141], v196, v196 op_sel_hi:[0,0,0]
	v_mfma_scale_f32_16x16x128_f8f6f4 v[126:129], v[2:9], v[220:227], v[126:129], v196, v196 op_sel_hi:[0,0,0]
	v_mfma_scale_f32_16x16x128_f8f6f4 v[122:125], v[10:17], v[220:227], v[122:125], v196, v196 op_sel_hi:[0,0,0]
	v_mfma_scale_f32_16x16x128_f8f6f4 v[110:113], v[2:9], v[228:235], v[110:113], v196, v196 op_sel_hi:[0,0,0]
	v_mfma_scale_f32_16x16x128_f8f6f4 v[106:109], v[10:17], v[228:235], v[106:109], v196, v196 op_sel_hi:[0,0,0]
	s_setprio 0
	s_setprio 1
	v_mfma_scale_f32_16x16x128_f8f6f4 v[150:153], v[18:25], v[204:211], v[150:153], v196, v196 op_sel_hi:[0,0,0]
	v_mfma_scale_f32_16x16x128_f8f6f4 v[146:149], v[26:33], v[204:211], v[146:149], v196, v196 op_sel_hi:[0,0,0]
	v_mfma_scale_f32_16x16x128_f8f6f4 v[134:137], v[18:25], v[212:219], v[134:137], v196, v196 op_sel_hi:[0,0,0]
	v_mfma_scale_f32_16x16x128_f8f6f4 v[130:133], v[26:33], v[212:219], v[130:133], v196, v196 op_sel_hi:[0,0,0]
	v_mfma_scale_f32_16x16x128_f8f6f4 v[118:121], v[18:25], v[220:227], v[118:121], v196, v196 op_sel_hi:[0,0,0]
	v_mfma_scale_f32_16x16x128_f8f6f4 v[114:117], v[26:33], v[220:227], v[114:117], v196, v196 op_sel_hi:[0,0,0]
	v_mfma_scale_f32_16x16x128_f8f6f4 v[102:105], v[18:25], v[228:235], v[102:105], v196, v196 op_sel_hi:[0,0,0]
	v_mfma_scale_f32_16x16x128_f8f6f4 v[98:101], v[26:33], v[228:235], v[98:101], v196, v196 op_sel_hi:[0,0,0]
	s_setprio 0
	s_barrier
	s_add_i32 s60, s73, s20
	v_lshl_add_u64 v[182:183], v[182:183], 0, s[22:23]
	s_mov_b32 m0, s60
	ds_read_b128 v[204:207], v195 offset:49152
	ds_read_b128 v[208:211], v195 offset:50176
	ds_read_b128 v[212:215], v195 offset:51200
	ds_read_b128 v[216:219], v195 offset:52224
	ds_read_b128 v[220:223], v195 offset:53248
	ds_read_b128 v[224:227], v195 offset:54272
	ds_read_b128 v[228:231], v195 offset:55296
	ds_read_b128 v[232:235], v195 offset:56320
	global_load_lds_dwordx4 v[182:183], off
	s_add_i32 m0, s60, 0x2000
	s_add_u32 s58, s58, 0x80080
	v_lshl_add_u64 v[182:183], v[184:185], 0, s[22:23]
	s_addc_u32 s59, s59, 0
	s_add_i32 s60, s74, s20
	global_load_lds_dwordx4 v[182:183], off
	v_lshl_add_u64 v[182:183], s[58:59], 0, v[170:171]
	s_mov_b32 m0, s60
	s_nop 0
	global_load_lds_dwordx4 v[182:183], off
	v_lshl_add_u64 v[182:183], s[58:59], 0, v[166:167]
	s_add_i32 m0, s60, 0x2000
	s_nop 0
	global_load_lds_dwordx4 v[182:183], off
	v_lshl_add_u64 v[182:183], v[186:187], 0, s[22:23]
	s_mov_b32 m0, s63
	s_nop 0
	global_load_lds_dwordx4 v[182:183], off
	v_lshl_add_u64 v[182:183], v[188:189], 0, s[22:23]
	s_mov_b32 m0, s64
	s_nop 0
	global_load_lds_dwordx4 v[182:183], off
	s_waitcnt vmcnt(8)
	s_waitcnt lgkmcnt(0)
	s_barrier
	s_setprio 1
	s_waitcnt lgkmcnt(0)
	v_mfma_scale_f32_16x16x128_f8f6f4 v[94:97], v[2:9], v[204:211], v[94:97], v196, v196 op_sel_hi:[0,0,0]
	v_mfma_scale_f32_16x16x128_f8f6f4 v[90:93], v[10:17], v[204:211], v[90:93], v196, v196 op_sel_hi:[0,0,0]
	v_mfma_scale_f32_16x16x128_f8f6f4 v[78:81], v[2:9], v[212:219], v[78:81], v196, v196 op_sel_hi:[0,0,0]
	v_mfma_scale_f32_16x16x128_f8f6f4 v[74:77], v[10:17], v[212:219], v[74:77], v196, v196 op_sel_hi:[0,0,0]
	v_mfma_scale_f32_16x16x128_f8f6f4 v[62:65], v[2:9], v[220:227], v[62:65], v196, v196 op_sel_hi:[0,0,0]
	v_mfma_scale_f32_16x16x128_f8f6f4 v[58:61], v[10:17], v[220:227], v[58:61], v196, v196 op_sel_hi:[0,0,0]
	v_mfma_scale_f32_16x16x128_f8f6f4 v[46:49], v[2:9], v[228:235], v[46:49], v196, v196 op_sel_hi:[0,0,0]
	v_mfma_scale_f32_16x16x128_f8f6f4 v[42:45], v[10:17], v[228:235], v[42:45], v196, v196 op_sel_hi:[0,0,0]
	s_setprio 0
	s_setprio 1
	v_mfma_scale_f32_16x16x128_f8f6f4 v[86:89], v[18:25], v[204:211], v[86:89], v196, v196 op_sel_hi:[0,0,0]
	v_mfma_scale_f32_16x16x128_f8f6f4 v[82:85], v[26:33], v[204:211], v[82:85], v196, v196 op_sel_hi:[0,0,0]
	v_mfma_scale_f32_16x16x128_f8f6f4 v[70:73], v[18:25], v[212:219], v[70:73], v196, v196 op_sel_hi:[0,0,0]
	v_mfma_scale_f32_16x16x128_f8f6f4 v[66:69], v[26:33], v[212:219], v[66:69], v196, v196 op_sel_hi:[0,0,0]
	v_mfma_scale_f32_16x16x128_f8f6f4 v[54:57], v[18:25], v[220:227], v[54:57], v196, v196 op_sel_hi:[0,0,0]
	v_mfma_scale_f32_16x16x128_f8f6f4 v[50:53], v[26:33], v[220:227], v[50:53], v196, v196 op_sel_hi:[0,0,0]
	v_mfma_scale_f32_16x16x128_f8f6f4 v[38:41], v[18:25], v[228:235], v[38:41], v196, v196 op_sel_hi:[0,0,0]
	v_mfma_scale_f32_16x16x128_f8f6f4 v[34:37], v[26:33], v[228:235], v[34:37], v196, v196 op_sel_hi:[0,0,0]
	s_setprio 0
	s_barrier
	s_add_i32 s72, s72, 2
	s_add_u32 s56, s56, 0x100
	s_addc_u32 s57, s57, 0
	s_add_u32 s70, s70, 0x100
	s_addc_u32 s71, s71, 0
	s_cmp_gt_u32 s72, 29
	s_cbranch_scc0 .LBB0_2171
	s_and_b64 vcc, exec, s[24:25]
	s_cbranch_vccz .LBB0_2174
	s_barrier

.LBB0_2400:
	ds_read_b128 v[16:19], v187
	ds_read_b128 v[20:23], v187 offset:1024
	ds_read_b128 v[24:27], v187 offset:2048
	ds_read_b128 v[28:31], v187 offset:3072
	ds_read_b128 v[0:3], v188
	ds_read_b128 v[4:7], v188 offset:1024
	ds_read_b128 v[8:11], v188 offset:2048
	ds_read_b128 v[12:15], v188 offset:3072
	s_add_u32 s22, s20, 0xffea8080
	s_addc_u32 s23, s21, -1
	s_cmpk_eq_i32 s43, 0x52
	s_cselect_b32 s25, s5, s23
	s_cselect_b32 s24, s4, s22
	s_cselect_b32 s23, s19, s42
	s_cselect_b32 s22, s18, s41
	v_lshl_add_u64 v[216:217], s[20:21], 0, v[162:163]
	s_add_i32 m0, s26, 0xc000
	ds_read_b128 v[176:179], v189
	ds_read_b128 v[180:183], v189 offset:1024
	ds_read_b128 v[192:195], v189 offset:2048
	ds_read_b128 v[196:199], v189 offset:3072
	ds_read_b128 v[200:203], v189 offset:4096
	ds_read_b128 v[204:207], v189 offset:5120
	ds_read_b128 v[208:211], v189 offset:6144
	ds_read_b128 v[212:215], v189 offset:7168
	global_load_lds_dwordx4 v[216:217], off
	v_lshl_add_u64 v[216:217], s[20:21], 0, v[170:171]
	s_add_i32 m0, s26, 0xe000
	s_nop 0
	global_load_lds_dwordx4 v[216:217], off
	s_waitcnt vmcnt(8)
	s_waitcnt lgkmcnt(0)
	s_barrier
	s_setprio 1
	s_waitcnt lgkmcnt(0)
	v_mfma_scale_f32_16x16x128_f8f6f4 v[156:159], v[16:23], v[176:183], v[156:159], v190, v190 op_sel_hi:[0,0,0]
	v_mfma_scale_f32_16x16x128_f8f6f4 v[152:155], v[24:31], v[176:183], v[152:155], v190, v190 op_sel_hi:[0,0,0]
	v_mfma_scale_f32_16x16x128_f8f6f4 v[148:151], v[16:23], v[192:199], v[148:151], v190, v190 op_sel_hi:[0,0,0]
	v_mfma_scale_f32_16x16x128_f8f6f4 v[144:147], v[24:31], v[192:199], v[144:147], v190, v190 op_sel_hi:[0,0,0]
	v_mfma_scale_f32_16x16x128_f8f6f4 v[132:135], v[16:23], v[200:207], v[132:135], v190, v190 op_sel_hi:[0,0,0]
	v_mfma_scale_f32_16x16x128_f8f6f4 v[120:123], v[24:31], v[200:207], v[120:123], v190, v190 op_sel_hi:[0,0,0]
	v_mfma_scale_f32_16x16x128_f8f6f4 v[112:115], v[16:23], v[208:215], v[112:115], v190, v190 op_sel_hi:[0,0,0]
	v_mfma_scale_f32_16x16x128_f8f6f4 v[104:107], v[24:31], v[208:215], v[104:107], v190, v190 op_sel_hi:[0,0,0]
	s_setprio 0
	s_setprio 1
	v_mfma_scale_f32_16x16x128_f8f6f4 v[140:143], v[0:7], v[176:183], v[140:143], v190, v190 op_sel_hi:[0,0,0]
	v_mfma_scale_f32_16x16x128_f8f6f4 v[136:139], v[8:15], v[176:183], v[136:139], v190, v190 op_sel_hi:[0,0,0]
	v_mfma_scale_f32_16x16x128_f8f6f4 v[128:131], v[0:7], v[192:199], v[128:131], v190, v190 op_sel_hi:[0,0,0]
	v_mfma_scale_f32_16x16x128_f8f6f4 v[124:127], v[8:15], v[192:199], v[124:127], v190, v190 op_sel_hi:[0,0,0]
	v_mfma_scale_f32_16x16x128_f8f6f4 v[116:119], v[0:7], v[200:207], v[116:119], v190, v190 op_sel_hi:[0,0,0]
	v_mfma_scale_f32_16x16x128_f8f6f4 v[108:111], v[8:15], v[200:207], v[108:111], v190, v190 op_sel_hi:[0,0,0]
	v_mfma_scale_f32_16x16x128_f8f6f4 v[100:103], v[0:7], v[208:215], v[100:103], v190, v190 op_sel_hi:[0,0,0]
	v_mfma_scale_f32_16x16x128_f8f6f4 v[96:99], v[8:15], v[208:215], v[96:99], v190, v190 op_sel_hi:[0,0,0]
	s_setprio 0
	s_barrier
	s_add_i32 s48, s35, s15
	v_lshl_add_u64 v[176:177], s[22:23], 0, v[164:165]
	s_mov_b32 m0, s48
	ds_read_b128 v[192:195], v189 offset:16384
	ds_read_b128 v[196:199], v189 offset:17408
	ds_read_b128 v[200:203], v189 offset:18432
	ds_read_b128 v[204:207], v189 offset:19456
	ds_read_b128 v[208:211], v189 offset:20480
	ds_read_b128 v[212:215], v189 offset:21504
	ds_read_b128 v[216:219], v189 offset:22528
	ds_read_b128 v[220:223], v189 offset:23552
	global_load_lds_dwordx4 v[176:177], off
	s_add_i32 m0, s48, 0x2000
	s_add_u32 s48, s22, 0x158000
	v_lshl_add_u64 v[178:179], s[22:23], 0, v[168:169]
	s_addc_u32 s49, s23, 0
	s_add_i32 s50, s36, s15
	global_load_lds_dwordx4 v[178:179], off
	v_lshl_add_u64 v[180:181], s[48:49], 0, v[164:165]
	s_mov_b32 m0, s50
	v_lshl_add_u64 v[182:183], s[24:25], 0, v[166:167]
	global_load_lds_dwordx4 v[180:181], off
	v_lshl_add_u64 v[180:181], s[48:49], 0, v[168:169]
	s_add_i32 m0, s50, 0x2000
	s_nop 0
	global_load_lds_dwordx4 v[180:181], off
	v_lshl_add_u64 v[180:181], s[24:25], 0, v[160:161]
	s_mov_b32 m0, s26
	s_nop 0
	global_load_lds_dwordx4 v[180:181], off
	s_mov_b32 m0, s27
	s_nop 0
	global_load_lds_dwordx4 v[182:183], off
	s_waitcnt vmcnt(8)
	s_waitcnt lgkmcnt(0)
	s_barrier
	s_setprio 1
	s_waitcnt lgkmcnt(0)
	v_mfma_scale_f32_16x16x128_f8f6f4 v[92:95], v[16:23], v[192:199], v[92:95], v190, v190 op_sel_hi:[0,0,0]
	v_mfma_scale_f32_16x16x128_f8f6f4 v[88:91], v[24:31], v[192:199], v[88:91], v190, v190 op_sel_hi:[0,0,0]
	v_mfma_scale_f32_16x16x128_f8f6f4 v[80:83], v[16:23], v[200:207], v[80:83], v190, v190 op_sel_hi:[0,0,0]
	v_mfma_scale_f32_16x16x128_f8f6f4 v[72:75], v[24:31], v[200:207], v[72:75], v190, v190 op_sel_hi:[0,0,0]
	v_mfma_scale_f32_16x16x128_f8f6f4 v[64:67], v[16:23], v[208:215], v[64:67], v190, v190 op_sel_hi:[0,0,0]
	v_mfma_scale_f32_16x16x128_f8f6f4 v[56:59], v[24:31], v[208:215], v[56:59], v190, v190 op_sel_hi:[0,0,0]
	v_mfma_scale_f32_16x16x128_f8f6f4 v[48:51], v[16:23], v[216:223], v[48:51], v190, v190 op_sel_hi:[0,0,0]
	v_mfma_scale_f32_16x16x128_f8f6f4 v[40:43], v[24:31], v[216:223], v[40:43], v190, v190 op_sel_hi:[0,0,0]
	s_setprio 0
	s_setprio 1
	v_mfma_scale_f32_16x16x128_f8f6f4 v[84:87], v[0:7], v[192:199], v[84:87], v190, v190 op_sel_hi:[0,0,0]
	v_mfma_scale_f32_16x16x128_f8f6f4 v[76:79], v[8:15], v[192:199], v[76:79], v190, v190 op_sel_hi:[0,0,0]
	v_mfma_scale_f32_16x16x128_f8f6f4 v[68:71], v[0:7], v[200:207], v[68:71], v190, v190 op_sel_hi:[0,0,0]
	v_mfma_scale_f32_16x16x128_f8f6f4 v[60:63], v[8:15], v[200:207], v[60:63], v190, v190 op_sel_hi:[0,0,0]
	v_mfma_scale_f32_16x16x128_f8f6f4 v[52:55], v[0:7], v[208:215], v[52:55], v190, v190 op_sel_hi:[0,0,0]
	v_mfma_scale_f32_16x16x128_f8f6f4 v[44:47], v[8:15], v[208:215], v[44:47], v190, v190 op_sel_hi:[0,0,0]
	v_mfma_scale_f32_16x16x128_f8f6f4 v[36:39], v[0:7], v[216:223], v[36:39], v190, v190 op_sel_hi:[0,0,0]
	v_mfma_scale_f32_16x16x128_f8f6f4 v[32:35], v[8:15], v[216:223], v[32:35], v190, v190 op_sel_hi:[0,0,0]
	s_setprio 0
	s_barrier
	s_add_i32 s48, 0, 0x18000
	s_add_i32 s49, 0, 0x1c000
	v_add_u32_e32 v12, s48, v184
	v_add_u32_e32 v28, s49, v184
	ds_read_b128 v[0:3], v12
	ds_read_b128 v[4:7], v12 offset:1024
	ds_read_b128 v[8:11], v12 offset:2048
	ds_read_b128 v[12:15], v12 offset:3072
	ds_read_b128 v[16:19], v28
	ds_read_b128 v[20:23], v28 offset:1024
	ds_read_b128 v[24:27], v28 offset:2048
	ds_read_b128 v[28:31], v28 offset:3072
	s_add_u32 s24, s24, 0x158000
	s_addc_u32 s25, s25, 0
	s_mov_b32 m0, s28
	v_lshl_add_u64 v[224:225], s[24:25], 0, v[160:161]
	ds_read_b128 v[192:195], v189 offset:32768
	ds_read_b128 v[196:199], v189 offset:33792
	ds_read_b128 v[200:203], v189 offset:34816
	ds_read_b128 v[204:207], v189 offset:35840
	ds_read_b128 v[208:211], v189 offset:36864
	ds_read_b128 v[212:215], v189 offset:37888
	ds_read_b128 v[216:219], v189 offset:38912
	ds_read_b128 v[220:223], v189 offset:39936
	global_load_lds_dwordx4 v[224:225], off
	v_lshl_add_u64 v[224:225], s[24:25], 0, v[166:167]
	s_mov_b32 m0, s29
	s_nop 0
	global_load_lds_dwordx4 v[224:225], off
	s_waitcnt vmcnt(8)
	s_waitcnt lgkmcnt(0)
	s_barrier
	s_setprio 1
	s_waitcnt lgkmcnt(0)
	v_mfma_scale_f32_16x16x128_f8f6f4 v[156:159], v[0:7], v[192:199], v[156:159], v190, v190 op_sel_hi:[0,0,0]
	v_mfma_scale_f32_16x16x128_f8f6f4 v[152:155], v[8:15], v[192:199], v[152:155], v190, v190 op_sel_hi:[0,0,0]
	v_mfma_scale_f32_16x16x128_f8f6f4 v[148:151], v[0:7], v[200:207], v[148:151], v190, v190 op_sel_hi:[0,0,0]
	v_mfma_scale_f32_16x16x128_f8f6f4 v[144:147], v[8:15], v[200:207], v[144:147], v190, v190 op_sel_hi:[0,0,0]
	v_mfma_scale_f32_16x16x128_f8f6f4 v[132:135], v[0:7], v[208:215], v[132:135], v190, v190 op_sel_hi:[0,0,0]
	v_mfma_scale_f32_16x16x128_f8f6f4 v[120:123], v[8:15], v[208:215], v[120:123], v190, v190 op_sel_hi:[0,0,0]
	v_mfma_scale_f32_16x16x128_f8f6f4 v[112:115], v[0:7], v[216:223], v[112:115], v190, v190 op_sel_hi:[0,0,0]
	v_mfma_scale_f32_16x16x128_f8f6f4 v[104:107], v[8:15], v[216:223], v[104:107], v190, v190 op_sel_hi:[0,0,0]
	s_setprio 0
	s_setprio 1
	v_mfma_scale_f32_16x16x128_f8f6f4 v[140:143], v[16:23], v[192:199], v[140:143], v190, v190 op_sel_hi:[0,0,0]
	v_mfma_scale_f32_16x16x128_f8f6f4 v[136:139], v[24:31], v[192:199], v[136:139], v190, v190 op_sel_hi:[0,0,0]
	v_mfma_scale_f32_16x16x128_f8f6f4 v[128:131], v[16:23], v[200:207], v[128:131], v190, v190 op_sel_hi:[0,0,0]
	v_mfma_scale_f32_16x16x128_f8f6f4 v[124:127], v[24:31], v[200:207], v[124:127], v190, v190 op_sel_hi:[0,0,0]
	v_mfma_scale_f32_16x16x128_f8f6f4 v[116:119], v[16:23], v[208:215], v[116:119], v190, v190 op_sel_hi:[0,0,0]
	v_mfma_scale_f32_16x16x128_f8f6f4 v[108:111], v[24:31], v[208:215], v[108:111], v190, v190 op_sel_hi:[0,0,0]
	v_mfma_scale_f32_16x16x128_f8f6f4 v[100:103], v[16:23], v[216:223], v[100:103], v190, v190 op_sel_hi:[0,0,0]
	v_mfma_scale_f32_16x16x128_f8f6f4 v[96:99], v[24:31], v[216:223], v[96:99], v190, v190 op_sel_hi:[0,0,0]
	s_setprio 0
	s_barrier
	s_add_i32 s24, s48, s15
	v_lshl_add_u64 v[176:177], v[176:177], 0, s[8:9]
	s_mov_b32 m0, s24
	ds_read_b128 v[192:195], v189 offset:49152
	ds_read_b128 v[196:199], v189 offset:50176
	ds_read_b128 v[200:203], v189 offset:51200
	ds_read_b128 v[204:207], v189 offset:52224
	ds_read_b128 v[208:211], v189 offset:53248
	ds_read_b128 v[212:215], v189 offset:54272
	ds_read_b128 v[216:219], v189 offset:55296
	ds_read_b128 v[220:223], v189 offset:56320
	global_load_lds_dwordx4 v[176:177], off
	s_add_i32 m0, s24, 0x2000
	s_add_u32 s22, s22, 0x158080
	v_lshl_add_u64 v[176:177], v[178:179], 0, s[8:9]
	s_addc_u32 s23, s23, 0
	s_add_i32 s24, s49, s15
	global_load_lds_dwordx4 v[176:177], off
	v_lshl_add_u64 v[176:177], s[22:23], 0, v[164:165]
	s_mov_b32 m0, s24
	s_nop 0
	global_load_lds_dwordx4 v[176:177], off
	v_lshl_add_u64 v[176:177], s[22:23], 0, v[168:169]
	s_add_i32 m0, s24, 0x2000
	s_nop 0
	global_load_lds_dwordx4 v[176:177], off
	v_lshl_add_u64 v[176:177], v[180:181], 0, s[8:9]
	s_mov_b32 m0, s31
	s_nop 0
	global_load_lds_dwordx4 v[176:177], off
	v_lshl_add_u64 v[176:177], v[182:183], 0, s[8:9]
	s_mov_b32 m0, s33
	s_nop 0
	global_load_lds_dwordx4 v[176:177], off
	s_waitcnt vmcnt(8)
	s_waitcnt lgkmcnt(0)
	s_barrier
	s_setprio 1
	s_waitcnt lgkmcnt(0)
	v_mfma_scale_f32_16x16x128_f8f6f4 v[92:95], v[0:7], v[192:199], v[92:95], v190, v190 op_sel_hi:[0,0,0]
	v_mfma_scale_f32_16x16x128_f8f6f4 v[88:91], v[8:15], v[192:199], v[88:91], v190, v190 op_sel_hi:[0,0,0]
	v_mfma_scale_f32_16x16x128_f8f6f4 v[80:83], v[0:7], v[200:207], v[80:83], v190, v190 op_sel_hi:[0,0,0]
	v_mfma_scale_f32_16x16x128_f8f6f4 v[72:75], v[8:15], v[200:207], v[72:75], v190, v190 op_sel_hi:[0,0,0]
	v_mfma_scale_f32_16x16x128_f8f6f4 v[64:67], v[0:7], v[208:215], v[64:67], v190, v190 op_sel_hi:[0,0,0]
	v_mfma_scale_f32_16x16x128_f8f6f4 v[56:59], v[8:15], v[208:215], v[56:59], v190, v190 op_sel_hi:[0,0,0]
	v_mfma_scale_f32_16x16x128_f8f6f4 v[48:51], v[0:7], v[216:223], v[48:51], v190, v190 op_sel_hi:[0,0,0]
	v_mfma_scale_f32_16x16x128_f8f6f4 v[40:43], v[8:15], v[216:223], v[40:43], v190, v190 op_sel_hi:[0,0,0]
	s_setprio 0
	s_setprio 1
	v_mfma_scale_f32_16x16x128_f8f6f4 v[84:87], v[16:23], v[192:199], v[84:87], v190, v190 op_sel_hi:[0,0,0]
	v_mfma_scale_f32_16x16x128_f8f6f4 v[76:79], v[24:31], v[192:199], v[76:79], v190, v190 op_sel_hi:[0,0,0]
	v_mfma_scale_f32_16x16x128_f8f6f4 v[68:71], v[16:23], v[200:207], v[68:71], v190, v190 op_sel_hi:[0,0,0]
	v_mfma_scale_f32_16x16x128_f8f6f4 v[60:63], v[24:31], v[200:207], v[60:63], v190, v190 op_sel_hi:[0,0,0]
	v_mfma_scale_f32_16x16x128_f8f6f4 v[52:55], v[16:23], v[208:215], v[52:55], v190, v190 op_sel_hi:[0,0,0]
	v_mfma_scale_f32_16x16x128_f8f6f4 v[44:47], v[24:31], v[208:215], v[44:47], v190, v190 op_sel_hi:[0,0,0]
	v_mfma_scale_f32_16x16x128_f8f6f4 v[36:39], v[16:23], v[216:223], v[36:39], v190, v190 op_sel_hi:[0,0,0]
	v_mfma_scale_f32_16x16x128_f8f6f4 v[32:35], v[24:31], v[216:223], v[32:35], v190, v190 op_sel_hi:[0,0,0]
	s_setprio 0
	s_barrier
	s_add_i32 s43, s43, 2
	s_add_u32 s20, s20, 0x100
	s_addc_u32 s21, s21, 0
	s_add_u32 s41, s41, 0x100
	s_addc_u32 s42, s42, 0
	s_cmpk_gt_u32 s43, 0x53
	s_cbranch_scc0 .LBB0_2400
	s_and_b64 vcc, exec, s[12:13]
	s_cbranch_vccz .LBB0_2403
	s_barrier

	.amdhsa_kernel _Z10fwd_kernel4Args
		.amdhsa_group_segment_fixed_size 0
		.amdhsa_private_segment_fixed_size 0
		.amdhsa_kernarg_size 536
		.amdhsa_user_sgpr_count 2
		.amdhsa_user_sgpr_dispatch_ptr 0
		.amdhsa_user_sgpr_queue_ptr 0
		.amdhsa_user_sgpr_kernarg_segment_ptr 1
		.amdhsa_user_sgpr_dispatch_id 0
		.amdhsa_user_sgpr_kernarg_preload_length 0
		.amdhsa_user_sgpr_kernarg_preload_offset 0
		.amdhsa_user_sgpr_private_segment_size 0
		.amdhsa_uses_dynamic_stack 0
		.amdhsa_enable_private_segment 0
		.amdhsa_system_sgpr_workgroup_id_x 1
		.amdhsa_system_sgpr_workgroup_id_y 0
		.amdhsa_system_sgpr_workgroup_id_z 0
		.amdhsa_system_sgpr_workgroup_info 0
		.amdhsa_system_vgpr_workitem_id 0
		.amdhsa_next_free_vgpr 251
		.amdhsa_next_free_sgpr 102
		.amdhsa_accum_offset 252
		.amdhsa_reserve_vcc 1
		.amdhsa_float_round_mode_32 0
		.amdhsa_float_round_mode_16_64 0
		.amdhsa_float_denorm_mode_32 3
		.amdhsa_float_denorm_mode_16_64 3
		.amdhsa_dx10_clamp 1
		.amdhsa_ieee_mode 1
		.amdhsa_fp16_overflow 0
		.amdhsa_tg_split 0
		.amdhsa_exception_fp_ieee_invalid_op 0
		.amdhsa_exception_fp_denorm_src 0
		.amdhsa_exception_fp_ieee_div_zero 0
		.amdhsa_exception_fp_ieee_overflow 0
		.amdhsa_exception_fp_ieee_underflow 0
		.amdhsa_exception_fp_ieee_inexact 0
		.amdhsa_exception_int_div_zero 0
	.end_amdhsa_kernel

amdhsa.kernels:
  - .agpr_count:     0
    .args:
      - .offset:         0
        .size:           280
        .value_kind:     by_value
      - .offset:         280
        .size:           4
        .value_kind:     hidden_block_count_x
      - .offset:         284
        .size:           4
        .value_kind:     hidden_block_count_y
      - .offset:         288
        .size:           4
        .value_kind:     hidden_block_count_z
      - .offset:         292
        .size:           2
        .value_kind:     hidden_group_size_x
      - .offset:         294
        .size:           2
        .value_kind:     hidden_group_size_y
      - .offset:         296
        .size:           2
        .value_kind:     hidden_group_size_z
      - .offset:         298
        .size:           2
        .value_kind:     hidden_remainder_x
      - .offset:         300
        .size:           2
        .value_kind:     hidden_remainder_y
      - .offset:         302
        .size:           2
        .value_kind:     hidden_remainder_z
      - .offset:         320
        .size:           8
        .value_kind:     hidden_global_offset_x
      - .offset:         328
        .size:           8
        .value_kind:     hidden_global_offset_y
      - .offset:         336
        .size:           8
        .value_kind:     hidden_global_offset_z
      - .offset:         344
        .size:           2
        .value_kind:     hidden_grid_dims
      - .offset:         400
        .size:           4
        .value_kind:     hidden_dynamic_lds_size
    .group_segment_fixed_size: 0
    .kernarg_segment_align: 8
    .kernarg_segment_size: 536
    .language:       OpenCL C
    .language_version:
      - 2
      - 0
    .max_flat_workgroup_size: 512
    .name:           _Z10fwd_kernel4Args
    .private_segment_fixed_size: 0
    .sgpr_count:     108
    .sgpr_spill_count: 58
    .symbol:         _Z10fwd_kernel4Args.kd
    .uniform_work_group_size: 1
    .uses_dynamic_stack: false
    .vgpr_count:     251
    .vgpr_spill_count: 0
    .wavefront_size: 64
